# A/B of the seed's mid-segment s_setprio 0 / s_setprio 1 pairs inside the GEMM MFMA segments: both deleted (36 sites)
# baseline (speedup 1.0000x reference)
; #define PG8_STAGE(bufoff, gbase, voff) do { _Pragma("unroll") for (int _i = 0; _i < 2; ++_i) \
;         __builtin_amdgcn_global_load_lds((const unsigned*)((const char*)(gbase) + (voff)[_i]), (LAS unsigned*)(lds + (bufoff) + ldsw + _i * 8192), 16, 0, 0); } while (0)
; #define PG8_LDA(dst, b, h) do { _Pragma("unroll") for (int m = 0; m < 4; ++m) _Pragma("unroll") for (int k = 0; k < 2; ++k) dst[m][k] = *(const LAS bf16x8*)(lds + PG8_SA(b, h) + aoff + m * 2048 + k * 1024); } while (0)
; #define PG8_LDB(dst, b, h) do { _Pragma("unroll") for (int n = 0; n < 2; ++n) _Pragma("unroll") for (int k = 0; k < 2; ++k) dst[n][k] = *(const LAS bf16x8*)(lds + PG8_SB(b, h) + boff + n * 2048 + k * 1024); } while (0)
; #define PG8_MMA(ai, bj, At, Bt) do { __builtin_amdgcn_s_setprio(1); _Pragma("unroll") for (int m = 0; m < 4; ++m) _Pragma("unroll") for (int n = 0; n < 2; ++n) _Pragma("unroll") for (int k = 0; k < 2; ++k) \
;         acc[ai][bj][m][n] = __builtin_amdgcn_mfma_f32_16x16x32_bf16(Bt[n][k], At[m][k], acc[ai][bj][m][n], 0, 0, 0); __builtin_amdgcn_s_setprio(0); } while (0)
; #define PG8_BAR __builtin_amdgcn_s_barrier()
; template <class Epi, bool SEG>
; __device__ __forceinline__ void gemm_phase(LAS unsigned char* lds, const Gemm g, const int G, const int cidx, const Epi& E) {
;     ...
;         const bool has_next = S.next(ui + 1, nxt);
;         const char* nA = has_next ? (const char*)g.A + (long)nxt.pm * (long)tstepA + aoff0 : cA; const char* nB = has_next ? (const char*)g.Bt + (size_t)nxt.pn * tstepB : cB;
;         for (int t = 0; t < nt; t += 2) {
;             const bool last = (t == nt - 2);
;             const char* a1 = cA + (size_t)(t + 1) * kstep;
;             const char* a2 = last ? nA : cA + (size_t)(t + 2) * kstep; const char* b2 = last ? nB : cB + (size_t)(t + 2) * kstep;
;             const char* a3 = a2 + kstep; const char* b3 = b2 + kstep;
;             PG8_LDB(B0, 0, 0); PG8_LDB(B1, 0, 1); PG8_SCHED; PG8_LDA(At, 0, 0); PG8_STAGE(PG8_SA(1, 1), a1 + hstepA, voffA);
;             PG8_WAIT_V(8); PG8_WAIT_L(0); PG8_BAR; PG8_MMA(0, 0, At, B0); PG8_MMA(0, 1, At, B1); PG8_BAR; PG8_SCHED;
;             PG8_LDA(At, 0, 1); PG8_STAGE(PG8_SB(0, 0), b2, voffB); PG8_STAGE(PG8_SB(0, 1), b2 + hstepB, voffB); PG8_STAGE(PG8_SA(0, 0), a2, voffA);
;             PG8_WAIT_V(8); PG8_WAIT_L(0); PG8_BAR; PG8_MMA(1, 0, At, B0); PG8_MMA(1, 1, At, B1); PG8_BAR; PG8_SCHED;
.LBB0_293:
	s_ashr_i32 s23, s22, 31
	s_lshl_b64 s[42:43], s[22:23], 19
	s_add_u32 s42, s82, s42
	s_addc_u32 s43, s83, s43
	s_and_b64 s[44:45], s[40:41], exec
	s_cselect_b32 s7, s43, s47
	s_cselect_b32 s23, s42, s46
	s_ashr_i32 s21, s20, 31
	s_lshl_b64 s[44:45], s[20:21], 19
	s_add_u32 s44, s12, s44
	s_addc_u32 s45, s13, s45
	s_and_b64 s[50:51], s[40:41], exec
	s_cselect_b32 s21, s45, s49
	s_cselect_b32 s59, s44, s48
	s_add_u32 s46, s46, 0x40080
	s_addc_u32 s47, s47, 0
	s_add_u32 s60, s48, 0x100
	s_addc_u32 s61, s49, 0
	s_mov_b32 s62, -2
	s_add_u32 s48, s46, 0xfffc0080
	s_addc_u32 s49, s47, -1
	s_add_i32 s63, 0, 0x10000
	s_cmp_eq_u32 s62, 12
	s_cselect_b32 s51, s7, s49
	s_cselect_b32 s50, s23, s48
	s_cselect_b32 s49, s21, s61
	s_cselect_b32 s48, s59, s60
	s_add_i32 s66, 0, 0x14000
	v_add_u32_e32 v146, s63, v175
	v_add_u32_e32 v170, s66, v175
	ds_read_b128 v[134:137], v146
	ds_read_b128 v[138:141], v146 offset:1024
	ds_read_b128 v[142:145], v146 offset:2048
	ds_read_b128 v[146:149], v146 offset:3072
	ds_read_b128 v[158:161], v170
	ds_read_b128 v[162:165], v170 offset:1024
	ds_read_b128 v[166:169], v170 offset:2048
	ds_read_b128 v[170:173], v170 offset:3072
	v_lshl_add_u64 v[200:201], s[46:47], 0, v[154:155]
	s_add_i32 m0, s39, 0xc000
	ds_read_b128 v[180:183], v179
	ds_read_b128 v[184:187], v179 offset:1024
	ds_read_b128 v[188:191], v179 offset:2048
	ds_read_b128 v[192:195], v179 offset:3072
	ds_read_b128 v[196:199], v179 offset:4096
	ds_read_b128 v[212:215], v179 offset:5120
	ds_read_b128 v[216:219], v179 offset:6144
	ds_read_b128 v[220:223], v179 offset:7168
	global_load_lds_dwordx4 v[200:201], off
	v_lshl_add_u64 v[200:201], s[46:47], 0, v[156:157]
	s_add_i32 m0, s39, 0xe000
	s_nop 0
	global_load_lds_dwordx4 v[200:201], off
	s_waitcnt vmcnt(8)
	s_waitcnt lgkmcnt(0)
	s_setprio 1
	s_barrier
	v_mfma_f32_16x16x32_bf16 v[130:133], v[134:137], v[180:183], 0
	v_mfma_f32_16x16x32_bf16 v[126:129], v[142:145], v[180:183], 0
	v_mfma_f32_16x16x32_bf16 v[118:121], v[134:137], v[188:191], 0
	v_mfma_f32_16x16x32_bf16 v[110:113], v[142:145], v[188:191], 0
	v_mfma_f32_16x16x32_bf16 v[102:105], v[134:137], v[196:199], 0
	v_mfma_f32_16x16x32_bf16 v[94:97], v[142:145], v[196:199], 0
	v_mfma_f32_16x16x32_bf16 v[86:89], v[134:137], v[216:219], 0
	v_mfma_f32_16x16x32_bf16 v[78:81], v[142:145], v[216:219], 0
	v_mfma_f32_16x16x32_bf16 v[130:133], v[138:141], v[184:187], v[130:133]
	v_mfma_f32_16x16x32_bf16 v[126:129], v[146:149], v[184:187], v[126:129]
	v_mfma_f32_16x16x32_bf16 v[118:121], v[138:141], v[192:195], v[118:121]
	v_mfma_f32_16x16x32_bf16 v[110:113], v[146:149], v[192:195], v[110:113]
	v_mfma_f32_16x16x32_bf16 v[102:105], v[138:141], v[212:215], v[102:105]
	v_mfma_f32_16x16x32_bf16 v[94:97], v[146:149], v[212:215], v[94:97]
	v_mfma_f32_16x16x32_bf16 v[86:89], v[138:141], v[220:223], v[86:89]
	v_mfma_f32_16x16x32_bf16 v[78:81], v[146:149], v[220:223], v[78:81]
	v_mfma_f32_16x16x32_bf16 v[122:125], v[158:161], v[180:183], 0
	v_mfma_f32_16x16x32_bf16 v[114:117], v[166:169], v[180:183], 0
	v_mfma_f32_16x16x32_bf16 v[106:109], v[158:161], v[188:191], 0
	v_mfma_f32_16x16x32_bf16 v[98:101], v[166:169], v[188:191], 0
	v_mfma_f32_16x16x32_bf16 v[90:93], v[158:161], v[196:199], 0
	v_mfma_f32_16x16x32_bf16 v[82:85], v[166:169], v[196:199], 0
	v_mfma_f32_16x16x32_bf16 v[74:77], v[158:161], v[216:219], 0
	v_mfma_f32_16x16x32_bf16 v[70:73], v[166:169], v[216:219], 0
	v_mfma_f32_16x16x32_bf16 v[122:125], v[162:165], v[184:187], v[122:125]
	v_mfma_f32_16x16x32_bf16 v[114:117], v[170:173], v[184:187], v[114:117]
	v_mfma_f32_16x16x32_bf16 v[106:109], v[162:165], v[192:195], v[106:109]
	v_mfma_f32_16x16x32_bf16 v[98:101], v[170:173], v[192:195], v[98:101]
	v_mfma_f32_16x16x32_bf16 v[90:93], v[162:165], v[212:215], v[90:93]
	v_mfma_f32_16x16x32_bf16 v[82:85], v[170:173], v[212:215], v[82:85]
	v_mfma_f32_16x16x32_bf16 v[74:77], v[162:165], v[220:223], v[74:77]
	v_mfma_f32_16x16x32_bf16 v[70:73], v[170:173], v[220:223], v[70:73]
	s_barrier
	s_setprio 0
	s_add_i32 s63, s63, s1
	v_lshl_add_u64 v[200:201], s[48:49], 0, v[0:1]
	s_mov_b32 m0, s63
	ds_read_b128 v[180:183], v179 offset:16384
	ds_read_b128 v[184:187], v179 offset:17408
	ds_read_b128 v[188:191], v179 offset:18432
	ds_read_b128 v[192:195], v179 offset:19456
	ds_read_b128 v[196:199], v179 offset:20480
	ds_read_b128 v[212:215], v179 offset:21504
	ds_read_b128 v[216:219], v179 offset:22528
	ds_read_b128 v[220:223], v179 offset:23552
	global_load_lds_dwordx4 v[200:201], off
	s_add_i32 m0, s63, 0x2000
	s_add_u32 s64, s48, 0x40000
	v_lshl_add_u64 v[224:225], s[48:49], 0, v[14:15]
	s_addc_u32 s65, s49, 0
	s_add_i32 s63, s66, s1
	global_load_lds_dwordx4 v[224:225], off
	v_lshl_add_u64 v[226:227], s[64:65], 0, v[0:1]
	s_mov_b32 m0, s63
	v_lshl_add_u64 v[228:229], s[50:51], 0, v[150:151]
	global_load_lds_dwordx4 v[226:227], off
	v_lshl_add_u64 v[226:227], s[64:65], 0, v[14:15]
	s_add_i32 m0, s63, 0x2000
	s_nop 0
	global_load_lds_dwordx4 v[226:227], off
	v_lshl_add_u64 v[226:227], s[50:51], 0, v[152:153]
	s_mov_b32 m0, s39
	s_nop 0
	global_load_lds_dwordx4 v[226:227], off
	s_mov_b32 m0, s52
	s_nop 0
	global_load_lds_dwordx4 v[228:229], off
	s_waitcnt vmcnt(8)
	s_waitcnt lgkmcnt(0)
	s_setprio 1
	s_barrier
; #define PG8_STAGE(bufoff, gbase, voff) do { _Pragma("unroll") for (int _i = 0; _i < 2; ++_i) \
;         __builtin_amdgcn_global_load_lds((const unsigned*)((const char*)(gbase) + (voff)[_i]), (LAS unsigned*)(lds + (bufoff) + ldsw + _i * 8192), 16, 0, 0); } while (0)
; #define PG8_LDA(dst, b, h) do { _Pragma("unroll") for (int m = 0; m < 4; ++m) _Pragma("unroll") for (int k = 0; k < 2; ++k) dst[m][k] = *(const LAS bf16x8*)(lds + PG8_SA(b, h) + aoff + m * 2048 + k * 1024); } while (0)
; #define PG8_LDB(dst, b, h) do { _Pragma("unroll") for (int n = 0; n < 2; ++n) _Pragma("unroll") for (int k = 0; k < 2; ++k) dst[n][k] = *(const LAS bf16x8*)(lds + PG8_SB(b, h) + boff + n * 2048 + k * 1024); } while (0)
; #define PG8_MMA(ai, bj, At, Bt) do { __builtin_amdgcn_s_setprio(1); _Pragma("unroll") for (int m = 0; m < 4; ++m) _Pragma("unroll") for (int n = 0; n < 2; ++n) _Pragma("unroll") for (int k = 0; k < 2; ++k) \
;         acc[ai][bj][m][n] = __builtin_amdgcn_mfma_f32_16x16x32_bf16(Bt[n][k], At[m][k], acc[ai][bj][m][n], 0, 0, 0); __builtin_amdgcn_s_setprio(0); } while (0)
; #define PG8_WAIT_V(n) asm volatile("s_waitcnt vmcnt(" #n ")" ::: "memory")
; #define PG8_WAIT_L(n) asm volatile("s_waitcnt lgkmcnt(" #n ")" ::: "memory")
; #define PG8_BAR __builtin_amdgcn_s_barrier()
; #define PG8_SCHED __builtin_amdgcn_sched_barrier(0)
; template <class Epi, bool SEG>
; __device__ __forceinline__ void gemm_phase(LAS unsigned char* lds, const Gemm g, const int G, const int cidx, const Epi& E) {
;     ...
;             PG8_WAIT_V(8); PG8_WAIT_L(0); PG8_BAR; PG8_MMA(1, 0, At, B0); PG8_MMA(1, 1, At, B1); PG8_BAR; PG8_SCHED;
;             PG8_LDB(B0, 1, 0); PG8_LDB(B1, 1, 1); PG8_SCHED; PG8_LDA(At, 1, 0); PG8_STAGE(PG8_SA(0, 1), a2 + hstepA, voffA);
;             PG8_WAIT_V(8); PG8_WAIT_L(0); PG8_BAR; PG8_MMA(0, 0, At, B0); PG8_MMA(0, 1, At, B1); PG8_BAR; PG8_SCHED;
;             PG8_LDA(At, 1, 1); PG8_STAGE(PG8_SB(1, 0), b3, voffB); PG8_STAGE(PG8_SB(1, 1), b3 + hstepB, voffB); PG8_STAGE(PG8_SA(1, 0), a3, voffA);
	v_mfma_f32_16x16x32_bf16 v[66:69], v[134:137], v[180:183], 0
	v_mfma_f32_16x16x32_bf16 v[62:65], v[142:145], v[180:183], 0
	v_mfma_f32_16x16x32_bf16 v[54:57], v[134:137], v[188:191], 0
	v_mfma_f32_16x16x32_bf16 v[46:49], v[142:145], v[188:191], 0
	v_mfma_f32_16x16x32_bf16 v[38:41], v[134:137], v[196:199], 0
	v_mfma_f32_16x16x32_bf16 v[30:33], v[142:145], v[196:199], 0
	v_mfma_f32_16x16x32_bf16 v[22:25], v[134:137], v[216:219], 0
	v_mfma_f32_16x16x32_bf16 v[10:13], v[142:145], v[216:219], 0
	v_mfma_f32_16x16x32_bf16 v[66:69], v[138:141], v[184:187], v[66:69]
	v_mfma_f32_16x16x32_bf16 v[62:65], v[146:149], v[184:187], v[62:65]
	v_mfma_f32_16x16x32_bf16 v[54:57], v[138:141], v[192:195], v[54:57]
	v_mfma_f32_16x16x32_bf16 v[46:49], v[146:149], v[192:195], v[46:49]
	v_mfma_f32_16x16x32_bf16 v[38:41], v[138:141], v[212:215], v[38:41]
	v_mfma_f32_16x16x32_bf16 v[30:33], v[146:149], v[212:215], v[30:33]
	v_mfma_f32_16x16x32_bf16 v[22:25], v[138:141], v[220:223], v[22:25]
	v_mfma_f32_16x16x32_bf16 v[10:13], v[146:149], v[220:223], v[10:13]
	v_mfma_f32_16x16x32_bf16 v[58:61], v[158:161], v[180:183], 0
	v_mfma_f32_16x16x32_bf16 v[50:53], v[166:169], v[180:183], 0
	v_mfma_f32_16x16x32_bf16 v[42:45], v[158:161], v[188:191], 0
	v_mfma_f32_16x16x32_bf16 v[34:37], v[166:169], v[188:191], 0
	v_mfma_f32_16x16x32_bf16 v[26:29], v[158:161], v[196:199], 0
	v_mfma_f32_16x16x32_bf16 v[18:21], v[166:169], v[196:199], 0
	v_mfma_f32_16x16x32_bf16 v[6:9], v[158:161], v[216:219], 0
	v_mfma_f32_16x16x32_bf16 v[2:5], v[166:169], v[216:219], 0
	v_mfma_f32_16x16x32_bf16 v[58:61], v[162:165], v[184:187], v[58:61]
	v_mfma_f32_16x16x32_bf16 v[50:53], v[170:173], v[184:187], v[50:53]
	v_mfma_f32_16x16x32_bf16 v[42:45], v[162:165], v[192:195], v[42:45]
	v_mfma_f32_16x16x32_bf16 v[34:37], v[170:173], v[192:195], v[34:37]
	v_mfma_f32_16x16x32_bf16 v[26:29], v[162:165], v[212:215], v[26:29]
	v_mfma_f32_16x16x32_bf16 v[18:21], v[170:173], v[212:215], v[18:21]
	v_mfma_f32_16x16x32_bf16 v[6:9], v[162:165], v[220:223], v[6:9]
	v_mfma_f32_16x16x32_bf16 v[2:5], v[170:173], v[220:223], v[2:5]
	s_barrier
	s_setprio 0
	s_add_i32 s63, 0, 0x18000
	s_add_i32 s64, 0, 0x1c000
	v_add_u32_e32 v146, s63, v175
	v_add_u32_e32 v170, s64, v175
	ds_read_b128 v[134:137], v146
	ds_read_b128 v[138:141], v146 offset:1024
	ds_read_b128 v[142:145], v146 offset:2048
	ds_read_b128 v[146:149], v146 offset:3072
	ds_read_b128 v[158:161], v170
	ds_read_b128 v[162:165], v170 offset:1024
	ds_read_b128 v[166:169], v170 offset:2048
	ds_read_b128 v[170:173], v170 offset:3072
	s_add_u32 s50, s50, 0x40000
	s_addc_u32 s51, s51, 0
	s_mov_b32 m0, s53
	v_lshl_add_u64 v[244:245], s[50:51], 0, v[152:153]
	ds_read_b128 v[180:183], v179 offset:32768
	ds_read_b128 v[184:187], v179 offset:33792
	ds_read_b128 v[188:191], v179 offset:34816
	ds_read_b128 v[192:195], v179 offset:35840
	ds_read_b128 v[196:199], v179 offset:36864
	ds_read_b128 v[212:215], v179 offset:37888
	ds_read_b128 v[216:219], v179 offset:38912
	ds_read_b128 v[220:223], v179 offset:39936
	global_load_lds_dwordx4 v[244:245], off
	v_lshl_add_u64 v[244:245], s[50:51], 0, v[150:151]
	s_mov_b32 m0, s54
	s_nop 0
	global_load_lds_dwordx4 v[244:245], off
	s_waitcnt vmcnt(8)
	s_waitcnt lgkmcnt(0)
	s_setprio 1
	s_barrier
	v_mfma_f32_16x16x32_bf16 v[130:133], v[134:137], v[180:183], v[130:133]
	v_mfma_f32_16x16x32_bf16 v[126:129], v[142:145], v[180:183], v[126:129]
	v_mfma_f32_16x16x32_bf16 v[118:121], v[134:137], v[188:191], v[118:121]
	v_mfma_f32_16x16x32_bf16 v[110:113], v[142:145], v[188:191], v[110:113]
	v_mfma_f32_16x16x32_bf16 v[102:105], v[134:137], v[196:199], v[102:105]
	v_mfma_f32_16x16x32_bf16 v[94:97], v[142:145], v[196:199], v[94:97]
	v_mfma_f32_16x16x32_bf16 v[86:89], v[134:137], v[216:219], v[86:89]
	v_mfma_f32_16x16x32_bf16 v[78:81], v[142:145], v[216:219], v[78:81]
	v_mfma_f32_16x16x32_bf16 v[130:133], v[138:141], v[184:187], v[130:133]
	v_mfma_f32_16x16x32_bf16 v[126:129], v[146:149], v[184:187], v[126:129]
	v_mfma_f32_16x16x32_bf16 v[118:121], v[138:141], v[192:195], v[118:121]
	v_mfma_f32_16x16x32_bf16 v[110:113], v[146:149], v[192:195], v[110:113]
	v_mfma_f32_16x16x32_bf16 v[102:105], v[138:141], v[212:215], v[102:105]
	v_mfma_f32_16x16x32_bf16 v[94:97], v[146:149], v[212:215], v[94:97]
	v_mfma_f32_16x16x32_bf16 v[86:89], v[138:141], v[220:223], v[86:89]
	v_mfma_f32_16x16x32_bf16 v[78:81], v[146:149], v[220:223], v[78:81]
	v_mfma_f32_16x16x32_bf16 v[122:125], v[158:161], v[180:183], v[122:125]
	v_mfma_f32_16x16x32_bf16 v[114:117], v[166:169], v[180:183], v[114:117]
	v_mfma_f32_16x16x32_bf16 v[106:109], v[158:161], v[188:191], v[106:109]
	v_mfma_f32_16x16x32_bf16 v[98:101], v[166:169], v[188:191], v[98:101]
	v_mfma_f32_16x16x32_bf16 v[90:93], v[158:161], v[196:199], v[90:93]
	v_mfma_f32_16x16x32_bf16 v[82:85], v[166:169], v[196:199], v[82:85]
	v_mfma_f32_16x16x32_bf16 v[74:77], v[158:161], v[216:219], v[74:77]
	v_mfma_f32_16x16x32_bf16 v[70:73], v[166:169], v[216:219], v[70:73]
	v_mfma_f32_16x16x32_bf16 v[122:125], v[162:165], v[184:187], v[122:125]
	v_mfma_f32_16x16x32_bf16 v[114:117], v[170:173], v[184:187], v[114:117]
	v_mfma_f32_16x16x32_bf16 v[106:109], v[162:165], v[192:195], v[106:109]
	v_mfma_f32_16x16x32_bf16 v[98:101], v[170:173], v[192:195], v[98:101]
	v_mfma_f32_16x16x32_bf16 v[90:93], v[162:165], v[212:215], v[90:93]
	v_mfma_f32_16x16x32_bf16 v[82:85], v[170:173], v[212:215], v[82:85]
	v_mfma_f32_16x16x32_bf16 v[74:77], v[162:165], v[220:223], v[74:77]
	v_mfma_f32_16x16x32_bf16 v[70:73], v[170:173], v[220:223], v[70:73]
	s_barrier
; #define PG8_STAGE(bufoff, gbase, voff) do { _Pragma("unroll") for (int _i = 0; _i < 2; ++_i) \
;         __builtin_amdgcn_global_load_lds((const unsigned*)((const char*)(gbase) + (voff)[_i]), (LAS unsigned*)(lds + (bufoff) + ldsw + _i * 8192), 16, 0, 0); } while (0)
; #define PG8_LDA(dst, b, h) do { _Pragma("unroll") for (int m = 0; m < 4; ++m) _Pragma("unroll") for (int k = 0; k < 2; ++k) dst[m][k] = *(const LAS bf16x8*)(lds + PG8_SA(b, h) + aoff + m * 2048 + k * 1024); } while (0)
; #define PG8_LDB(dst, b, h) do { _Pragma("unroll") for (int n = 0; n < 2; ++n) _Pragma("unroll") for (int k = 0; k < 2; ++k) dst[n][k] = *(const LAS bf16x8*)(lds + PG8_SB(b, h) + boff + n * 2048 + k * 1024); } while (0)
; #define PG8_MMA(ai, bj, At, Bt) do { __builtin_amdgcn_s_setprio(1); _Pragma("unroll") for (int m = 0; m < 4; ++m) _Pragma("unroll") for (int n = 0; n < 2; ++n) _Pragma("unroll") for (int k = 0; k < 2; ++k) \
;         acc[ai][bj][m][n] = __builtin_amdgcn_mfma_f32_16x16x32_bf16(Bt[n][k], At[m][k], acc[ai][bj][m][n], 0, 0, 0); __builtin_amdgcn_s_setprio(0); } while (0)
; #define PG8_WAIT_V(n) asm volatile("s_waitcnt vmcnt(" #n ")" ::: "memory")
; #define PG8_WAIT_L(n) asm volatile("s_waitcnt lgkmcnt(" #n ")" ::: "memory")
; #define PG8_BAR __builtin_amdgcn_s_barrier()
; #define PG8_SCHED __builtin_amdgcn_sched_barrier(0)
; template <class Epi, bool SEG>
; __device__ __forceinline__ void gemm_phase(LAS unsigned char* lds, const Gemm g, const int G, const int cidx, const Epi& E) {
;     ...
;         for (int t = 0; t < nt; t += 2) {
;             const bool last = (t == nt - 2);
;             const char* a1 = cA + (size_t)(t + 1) * kstep;
;             const char* a2 = last ? nA : cA + (size_t)(t + 2) * kstep; const char* b2 = last ? nB : cB + (size_t)(t + 2) * kstep;
;             const char* a3 = a2 + kstep; const char* b3 = b2 + kstep;
;             PG8_LDB(B0, 0, 0); PG8_LDB(B1, 0, 1); PG8_SCHED; PG8_LDA(At, 0, 0); PG8_STAGE(PG8_SA(1, 1), a1 + hstepA, voffA);
;             PG8_WAIT_V(8); PG8_WAIT_L(0); PG8_BAR; PG8_MMA(0, 0, At, B0); PG8_MMA(0, 1, At, B1); PG8_BAR; PG8_SCHED;
;     ...
;             PG8_LDA(At, 1, 1); PG8_STAGE(PG8_SB(1, 0), b3, voffB); PG8_STAGE(PG8_SB(1, 1), b3 + hstepB, voffB); PG8_STAGE(PG8_SA(1, 0), a3, voffA);
;             PG8_WAIT_V(8); PG8_WAIT_L(0); PG8_BAR; PG8_MMA(1, 0, At, B0); PG8_MMA(1, 1, At, B1); PG8_BAR; PG8_SCHED;
	s_setprio 0
	s_add_i32 s50, s63, s1
	v_lshl_add_u64 v[200:201], v[200:201], 0, s[28:29]
	s_mov_b32 m0, s50
	ds_read_b128 v[180:183], v179 offset:49152
	ds_read_b128 v[184:187], v179 offset:50176
	ds_read_b128 v[188:191], v179 offset:51200
	ds_read_b128 v[192:195], v179 offset:52224
	ds_read_b128 v[196:199], v179 offset:53248
	ds_read_b128 v[212:215], v179 offset:54272
	ds_read_b128 v[216:219], v179 offset:55296
	ds_read_b128 v[220:223], v179 offset:56320
	global_load_lds_dwordx4 v[200:201], off
	s_add_i32 m0, s50, 0x2000
	s_add_u32 s48, s48, 0x40080
	v_lshl_add_u64 v[200:201], v[224:225], 0, s[28:29]
	s_addc_u32 s49, s49, 0
	s_add_i32 s50, s64, s1
	global_load_lds_dwordx4 v[200:201], off
	v_lshl_add_u64 v[200:201], s[48:49], 0, v[0:1]
	s_mov_b32 m0, s50
	s_nop 0
	global_load_lds_dwordx4 v[200:201], off
	v_lshl_add_u64 v[200:201], s[48:49], 0, v[14:15]
	s_add_i32 m0, s50, 0x2000
	s_nop 0
	global_load_lds_dwordx4 v[200:201], off
	v_lshl_add_u64 v[200:201], v[226:227], 0, s[28:29]
	s_mov_b32 m0, s55
	s_nop 0
	global_load_lds_dwordx4 v[200:201], off
	v_lshl_add_u64 v[200:201], v[228:229], 0, s[28:29]
	s_mov_b32 m0, s56
	s_nop 0
	global_load_lds_dwordx4 v[200:201], off
	s_waitcnt vmcnt(8)
	s_waitcnt lgkmcnt(0)
	s_setprio 1
	s_barrier
	v_mfma_f32_16x16x32_bf16 v[66:69], v[134:137], v[180:183], v[66:69]
	v_mfma_f32_16x16x32_bf16 v[62:65], v[142:145], v[180:183], v[62:65]
	v_mfma_f32_16x16x32_bf16 v[54:57], v[134:137], v[188:191], v[54:57]
	v_mfma_f32_16x16x32_bf16 v[46:49], v[142:145], v[188:191], v[46:49]
	v_mfma_f32_16x16x32_bf16 v[38:41], v[134:137], v[196:199], v[38:41]
	v_mfma_f32_16x16x32_bf16 v[30:33], v[142:145], v[196:199], v[30:33]
	v_mfma_f32_16x16x32_bf16 v[22:25], v[134:137], v[216:219], v[22:25]
	v_mfma_f32_16x16x32_bf16 v[10:13], v[142:145], v[216:219], v[10:13]
	v_mfma_f32_16x16x32_bf16 v[66:69], v[138:141], v[184:187], v[66:69]
	v_mfma_f32_16x16x32_bf16 v[62:65], v[146:149], v[184:187], v[62:65]
	v_mfma_f32_16x16x32_bf16 v[54:57], v[138:141], v[192:195], v[54:57]
	v_mfma_f32_16x16x32_bf16 v[46:49], v[146:149], v[192:195], v[46:49]
	v_mfma_f32_16x16x32_bf16 v[38:41], v[138:141], v[212:215], v[38:41]
	v_mfma_f32_16x16x32_bf16 v[30:33], v[146:149], v[212:215], v[30:33]
	v_mfma_f32_16x16x32_bf16 v[22:25], v[138:141], v[220:223], v[22:25]
	v_mfma_f32_16x16x32_bf16 v[10:13], v[146:149], v[220:223], v[10:13]
	v_mfma_f32_16x16x32_bf16 v[58:61], v[158:161], v[180:183], v[58:61]
	v_mfma_f32_16x16x32_bf16 v[50:53], v[166:169], v[180:183], v[50:53]
	v_mfma_f32_16x16x32_bf16 v[42:45], v[158:161], v[188:191], v[42:45]
	v_mfma_f32_16x16x32_bf16 v[34:37], v[166:169], v[188:191], v[34:37]
	v_mfma_f32_16x16x32_bf16 v[26:29], v[158:161], v[196:199], v[26:29]
	v_mfma_f32_16x16x32_bf16 v[18:21], v[166:169], v[196:199], v[18:21]
	v_mfma_f32_16x16x32_bf16 v[6:9], v[158:161], v[216:219], v[6:9]
	v_mfma_f32_16x16x32_bf16 v[2:5], v[166:169], v[216:219], v[2:5]
	v_mfma_f32_16x16x32_bf16 v[58:61], v[162:165], v[184:187], v[58:61]
	v_mfma_f32_16x16x32_bf16 v[50:53], v[170:173], v[184:187], v[50:53]
	v_mfma_f32_16x16x32_bf16 v[42:45], v[162:165], v[192:195], v[42:45]
	v_mfma_f32_16x16x32_bf16 v[34:37], v[170:173], v[192:195], v[34:37]
	v_mfma_f32_16x16x32_bf16 v[26:29], v[162:165], v[212:215], v[26:29]
	v_mfma_f32_16x16x32_bf16 v[18:21], v[170:173], v[212:215], v[18:21]
	v_mfma_f32_16x16x32_bf16 v[6:9], v[162:165], v[220:223], v[6:9]
	v_mfma_f32_16x16x32_bf16 v[2:5], v[170:173], v[220:223], v[2:5]
	s_barrier
	s_setprio 0
	s_add_i32 s62, s62, 2
	s_add_u32 s46, s46, 0x100
	s_addc_u32 s47, s47, 0
	s_add_u32 s60, s60, 0x100
	s_addc_u32 s61, s61, 0
.LBB0_294:
	s_add_u32 s48, s46, 0xfffc0080
	s_addc_u32 s49, s47, -1
	s_add_i32 s63, 0, 0x10000
	s_cmp_eq_u32 s62, 12
	s_cselect_b32 s51, s7, s49
	s_cselect_b32 s50, s23, s48
	s_cselect_b32 s49, s21, s61
	s_cselect_b32 s48, s59, s60
	s_add_i32 s66, 0, 0x14000
	v_add_u32_e32 v146, s63, v175
	v_add_u32_e32 v170, s66, v175
	ds_read_b128 v[134:137], v146
	ds_read_b128 v[138:141], v146 offset:1024
	ds_read_b128 v[142:145], v146 offset:2048
	ds_read_b128 v[146:149], v146 offset:3072
	ds_read_b128 v[158:161], v170
	ds_read_b128 v[162:165], v170 offset:1024
	ds_read_b128 v[166:169], v170 offset:2048
	ds_read_b128 v[170:173], v170 offset:3072
	v_lshl_add_u64 v[200:201], s[46:47], 0, v[154:155]
	s_add_i32 m0, s39, 0xc000
	ds_read_b128 v[180:183], v179
	ds_read_b128 v[184:187], v179 offset:1024
	ds_read_b128 v[188:191], v179 offset:2048
	ds_read_b128 v[192:195], v179 offset:3072
	ds_read_b128 v[196:199], v179 offset:4096
	ds_read_b128 v[212:215], v179 offset:5120
	ds_read_b128 v[216:219], v179 offset:6144
	ds_read_b128 v[220:223], v179 offset:7168
	global_load_lds_dwordx4 v[200:201], off
	v_lshl_add_u64 v[200:201], s[46:47], 0, v[156:157]
	s_add_i32 m0, s39, 0xe000
	s_nop 0
	global_load_lds_dwordx4 v[200:201], off
	s_waitcnt vmcnt(8)
	s_waitcnt lgkmcnt(0)
	s_setprio 1
	s_barrier
; #define PG8_STAGE(bufoff, gbase, voff) do { _Pragma("unroll") for (int _i = 0; _i < 2; ++_i) \
;         __builtin_amdgcn_global_load_lds((const unsigned*)((const char*)(gbase) + (voff)[_i]), (LAS unsigned*)(lds + (bufoff) + ldsw + _i * 8192), 16, 0, 0); } while (0)
; #define PG8_LDA(dst, b, h) do { _Pragma("unroll") for (int m = 0; m < 4; ++m) _Pragma("unroll") for (int k = 0; k < 2; ++k) dst[m][k] = *(const LAS bf16x8*)(lds + PG8_SA(b, h) + aoff + m * 2048 + k * 1024); } while (0)
; #define PG8_LDB(dst, b, h) do { _Pragma("unroll") for (int n = 0; n < 2; ++n) _Pragma("unroll") for (int k = 0; k < 2; ++k) dst[n][k] = *(const LAS bf16x8*)(lds + PG8_SB(b, h) + boff + n * 2048 + k * 1024); } while (0)
; #define PG8_MMA(ai, bj, At, Bt) do { __builtin_amdgcn_s_setprio(1); _Pragma("unroll") for (int m = 0; m < 4; ++m) _Pragma("unroll") for (int n = 0; n < 2; ++n) _Pragma("unroll") for (int k = 0; k < 2; ++k) \
;         acc[ai][bj][m][n] = __builtin_amdgcn_mfma_f32_16x16x32_bf16(Bt[n][k], At[m][k], acc[ai][bj][m][n], 0, 0, 0); __builtin_amdgcn_s_setprio(0); } while (0)
; #define PG8_WAIT_V(n) asm volatile("s_waitcnt vmcnt(" #n ")" ::: "memory")
; #define PG8_WAIT_L(n) asm volatile("s_waitcnt lgkmcnt(" #n ")" ::: "memory")
; #define PG8_BAR __builtin_amdgcn_s_barrier()
; #define PG8_SCHED __builtin_amdgcn_sched_barrier(0)
; template <class Epi, bool SEG>
; __device__ __forceinline__ void gemm_phase(LAS unsigned char* lds, const Gemm g, const int G, const int cidx, const Epi& E) {
;     ...
;             PG8_WAIT_V(8); PG8_WAIT_L(0); PG8_BAR; PG8_MMA(0, 0, At, B0); PG8_MMA(0, 1, At, B1); PG8_BAR; PG8_SCHED;
;             PG8_LDA(At, 0, 1); PG8_STAGE(PG8_SB(0, 0), b2, voffB); PG8_STAGE(PG8_SB(0, 1), b2 + hstepB, voffB); PG8_STAGE(PG8_SA(0, 0), a2, voffA);
;             PG8_WAIT_V(8); PG8_WAIT_L(0); PG8_BAR; PG8_MMA(1, 0, At, B0); PG8_MMA(1, 1, At, B1); PG8_BAR; PG8_SCHED;
;             PG8_LDB(B0, 1, 0); PG8_LDB(B1, 1, 1); PG8_SCHED; PG8_LDA(At, 1, 0); PG8_STAGE(PG8_SA(0, 1), a2 + hstepA, voffA);
;             PG8_WAIT_V(8); PG8_WAIT_L(0); PG8_BAR; PG8_MMA(0, 0, At, B0); PG8_MMA(0, 1, At, B1); PG8_BAR; PG8_SCHED;
	v_mfma_f32_16x16x32_bf16 v[130:133], v[134:137], v[180:183], v[130:133]
	v_mfma_f32_16x16x32_bf16 v[126:129], v[142:145], v[180:183], v[126:129]
	v_mfma_f32_16x16x32_bf16 v[118:121], v[134:137], v[188:191], v[118:121]
	v_mfma_f32_16x16x32_bf16 v[110:113], v[142:145], v[188:191], v[110:113]
	v_mfma_f32_16x16x32_bf16 v[102:105], v[134:137], v[196:199], v[102:105]
	v_mfma_f32_16x16x32_bf16 v[94:97], v[142:145], v[196:199], v[94:97]
	v_mfma_f32_16x16x32_bf16 v[86:89], v[134:137], v[216:219], v[86:89]
	v_mfma_f32_16x16x32_bf16 v[78:81], v[142:145], v[216:219], v[78:81]
	v_mfma_f32_16x16x32_bf16 v[130:133], v[138:141], v[184:187], v[130:133]
	v_mfma_f32_16x16x32_bf16 v[126:129], v[146:149], v[184:187], v[126:129]
	v_mfma_f32_16x16x32_bf16 v[118:121], v[138:141], v[192:195], v[118:121]
	v_mfma_f32_16x16x32_bf16 v[110:113], v[146:149], v[192:195], v[110:113]
	v_mfma_f32_16x16x32_bf16 v[102:105], v[138:141], v[212:215], v[102:105]
	v_mfma_f32_16x16x32_bf16 v[94:97], v[146:149], v[212:215], v[94:97]
	v_mfma_f32_16x16x32_bf16 v[86:89], v[138:141], v[220:223], v[86:89]
	v_mfma_f32_16x16x32_bf16 v[78:81], v[146:149], v[220:223], v[78:81]
	v_mfma_f32_16x16x32_bf16 v[122:125], v[158:161], v[180:183], v[122:125]
	v_mfma_f32_16x16x32_bf16 v[114:117], v[166:169], v[180:183], v[114:117]
	v_mfma_f32_16x16x32_bf16 v[106:109], v[158:161], v[188:191], v[106:109]
	v_mfma_f32_16x16x32_bf16 v[98:101], v[166:169], v[188:191], v[98:101]
	v_mfma_f32_16x16x32_bf16 v[90:93], v[158:161], v[196:199], v[90:93]
	v_mfma_f32_16x16x32_bf16 v[82:85], v[166:169], v[196:199], v[82:85]
	v_mfma_f32_16x16x32_bf16 v[74:77], v[158:161], v[216:219], v[74:77]
	v_mfma_f32_16x16x32_bf16 v[70:73], v[166:169], v[216:219], v[70:73]
	v_mfma_f32_16x16x32_bf16 v[122:125], v[162:165], v[184:187], v[122:125]
	v_mfma_f32_16x16x32_bf16 v[114:117], v[170:173], v[184:187], v[114:117]
	v_mfma_f32_16x16x32_bf16 v[106:109], v[162:165], v[192:195], v[106:109]
	v_mfma_f32_16x16x32_bf16 v[98:101], v[170:173], v[192:195], v[98:101]
	v_mfma_f32_16x16x32_bf16 v[90:93], v[162:165], v[212:215], v[90:93]
	v_mfma_f32_16x16x32_bf16 v[82:85], v[170:173], v[212:215], v[82:85]
	v_mfma_f32_16x16x32_bf16 v[74:77], v[162:165], v[220:223], v[74:77]
	v_mfma_f32_16x16x32_bf16 v[70:73], v[170:173], v[220:223], v[70:73]
	s_barrier
	s_setprio 0
	s_add_i32 s63, s63, s1
	v_lshl_add_u64 v[200:201], s[48:49], 0, v[0:1]
	s_mov_b32 m0, s63
	ds_read_b128 v[180:183], v179 offset:16384
	ds_read_b128 v[184:187], v179 offset:17408
	ds_read_b128 v[188:191], v179 offset:18432
	ds_read_b128 v[192:195], v179 offset:19456
	ds_read_b128 v[196:199], v179 offset:20480
	ds_read_b128 v[212:215], v179 offset:21504
	ds_read_b128 v[216:219], v179 offset:22528
	ds_read_b128 v[220:223], v179 offset:23552
	global_load_lds_dwordx4 v[200:201], off
	s_add_i32 m0, s63, 0x2000
	s_add_u32 s64, s48, 0x40000
	v_lshl_add_u64 v[224:225], s[48:49], 0, v[14:15]
	s_addc_u32 s65, s49, 0
	s_add_i32 s63, s66, s1
	global_load_lds_dwordx4 v[224:225], off
	v_lshl_add_u64 v[226:227], s[64:65], 0, v[0:1]
	s_mov_b32 m0, s63
	v_lshl_add_u64 v[228:229], s[50:51], 0, v[150:151]
	global_load_lds_dwordx4 v[226:227], off
	v_lshl_add_u64 v[226:227], s[64:65], 0, v[14:15]
	s_add_i32 m0, s63, 0x2000
	s_nop 0
	global_load_lds_dwordx4 v[226:227], off
	v_lshl_add_u64 v[226:227], s[50:51], 0, v[152:153]
	s_mov_b32 m0, s39
	s_nop 0
	global_load_lds_dwordx4 v[226:227], off
	s_mov_b32 m0, s52
	s_nop 0
	global_load_lds_dwordx4 v[228:229], off
	s_waitcnt vmcnt(8)
	s_waitcnt lgkmcnt(0)
	s_setprio 1
	s_barrier
	v_mfma_f32_16x16x32_bf16 v[66:69], v[134:137], v[180:183], v[66:69]
	v_mfma_f32_16x16x32_bf16 v[62:65], v[142:145], v[180:183], v[62:65]
	v_mfma_f32_16x16x32_bf16 v[54:57], v[134:137], v[188:191], v[54:57]
	v_mfma_f32_16x16x32_bf16 v[46:49], v[142:145], v[188:191], v[46:49]
	v_mfma_f32_16x16x32_bf16 v[38:41], v[134:137], v[196:199], v[38:41]
	v_mfma_f32_16x16x32_bf16 v[30:33], v[142:145], v[196:199], v[30:33]
	v_mfma_f32_16x16x32_bf16 v[22:25], v[134:137], v[216:219], v[22:25]
	v_mfma_f32_16x16x32_bf16 v[10:13], v[142:145], v[216:219], v[10:13]
	v_mfma_f32_16x16x32_bf16 v[66:69], v[138:141], v[184:187], v[66:69]
	v_mfma_f32_16x16x32_bf16 v[62:65], v[146:149], v[184:187], v[62:65]
	v_mfma_f32_16x16x32_bf16 v[54:57], v[138:141], v[192:195], v[54:57]
	v_mfma_f32_16x16x32_bf16 v[46:49], v[146:149], v[192:195], v[46:49]
	v_mfma_f32_16x16x32_bf16 v[38:41], v[138:141], v[212:215], v[38:41]
	v_mfma_f32_16x16x32_bf16 v[30:33], v[146:149], v[212:215], v[30:33]
	v_mfma_f32_16x16x32_bf16 v[22:25], v[138:141], v[220:223], v[22:25]
	v_mfma_f32_16x16x32_bf16 v[10:13], v[146:149], v[220:223], v[10:13]
	v_mfma_f32_16x16x32_bf16 v[58:61], v[158:161], v[180:183], v[58:61]
	v_mfma_f32_16x16x32_bf16 v[50:53], v[166:169], v[180:183], v[50:53]
	v_mfma_f32_16x16x32_bf16 v[42:45], v[158:161], v[188:191], v[42:45]
	v_mfma_f32_16x16x32_bf16 v[34:37], v[166:169], v[188:191], v[34:37]
	v_mfma_f32_16x16x32_bf16 v[26:29], v[158:161], v[196:199], v[26:29]
	v_mfma_f32_16x16x32_bf16 v[18:21], v[166:169], v[196:199], v[18:21]
	v_mfma_f32_16x16x32_bf16 v[6:9], v[158:161], v[216:219], v[6:9]
	v_mfma_f32_16x16x32_bf16 v[2:5], v[166:169], v[216:219], v[2:5]
	v_mfma_f32_16x16x32_bf16 v[58:61], v[162:165], v[184:187], v[58:61]
	v_mfma_f32_16x16x32_bf16 v[50:53], v[170:173], v[184:187], v[50:53]
	v_mfma_f32_16x16x32_bf16 v[42:45], v[162:165], v[192:195], v[42:45]
	v_mfma_f32_16x16x32_bf16 v[34:37], v[170:173], v[192:195], v[34:37]
	v_mfma_f32_16x16x32_bf16 v[26:29], v[162:165], v[212:215], v[26:29]
	v_mfma_f32_16x16x32_bf16 v[18:21], v[170:173], v[212:215], v[18:21]
	v_mfma_f32_16x16x32_bf16 v[6:9], v[162:165], v[220:223], v[6:9]
	v_mfma_f32_16x16x32_bf16 v[2:5], v[170:173], v[220:223], v[2:5]
	s_barrier
; #define PG8_STAGE(bufoff, gbase, voff) do { _Pragma("unroll") for (int _i = 0; _i < 2; ++_i) \
;         __builtin_amdgcn_global_load_lds((const unsigned*)((const char*)(gbase) + (voff)[_i]), (LAS unsigned*)(lds + (bufoff) + ldsw + _i * 8192), 16, 0, 0); } while (0)
; #define PG8_LDA(dst, b, h) do { _Pragma("unroll") for (int m = 0; m < 4; ++m) _Pragma("unroll") for (int k = 0; k < 2; ++k) dst[m][k] = *(const LAS bf16x8*)(lds + PG8_SA(b, h) + aoff + m * 2048 + k * 1024); } while (0)
; #define PG8_LDB(dst, b, h) do { _Pragma("unroll") for (int n = 0; n < 2; ++n) _Pragma("unroll") for (int k = 0; k < 2; ++k) dst[n][k] = *(const LAS bf16x8*)(lds + PG8_SB(b, h) + boff + n * 2048 + k * 1024); } while (0)
; #define PG8_MMA(ai, bj, At, Bt) do { __builtin_amdgcn_s_setprio(1); _Pragma("unroll") for (int m = 0; m < 4; ++m) _Pragma("unroll") for (int n = 0; n < 2; ++n) _Pragma("unroll") for (int k = 0; k < 2; ++k) \
;         acc[ai][bj][m][n] = __builtin_amdgcn_mfma_f32_16x16x32_bf16(Bt[n][k], At[m][k], acc[ai][bj][m][n], 0, 0, 0); __builtin_amdgcn_s_setprio(0); } while (0)
; #define PG8_WAIT_V(n) asm volatile("s_waitcnt vmcnt(" #n ")" ::: "memory")
; #define PG8_WAIT_L(n) asm volatile("s_waitcnt lgkmcnt(" #n ")" ::: "memory")
; #define PG8_BAR __builtin_amdgcn_s_barrier()
; #define PG8_SCHED __builtin_amdgcn_sched_barrier(0)
; template <class Epi, bool SEG>
; __device__ __forceinline__ void gemm_phase(LAS unsigned char* lds, const Gemm g, const int G, const int cidx, const Epi& E) {
;     ...
;             PG8_LDB(B0, 1, 0); PG8_LDB(B1, 1, 1); PG8_SCHED; PG8_LDA(At, 1, 0); PG8_STAGE(PG8_SA(0, 1), a2 + hstepA, voffA);
;             PG8_WAIT_V(8); PG8_WAIT_L(0); PG8_BAR; PG8_MMA(0, 0, At, B0); PG8_MMA(0, 1, At, B1); PG8_BAR; PG8_SCHED;
;             PG8_LDA(At, 1, 1); PG8_STAGE(PG8_SB(1, 0), b3, voffB); PG8_STAGE(PG8_SB(1, 1), b3 + hstepB, voffB); PG8_STAGE(PG8_SA(1, 0), a3, voffA);
;             PG8_WAIT_V(8); PG8_WAIT_L(0); PG8_BAR; PG8_MMA(1, 0, At, B0); PG8_MMA(1, 1, At, B1); PG8_BAR; PG8_SCHED;
	s_setprio 0
	s_add_i32 s63, 0, 0x18000
	s_add_i32 s64, 0, 0x1c000
	v_add_u32_e32 v146, s63, v175
	v_add_u32_e32 v170, s64, v175
	ds_read_b128 v[134:137], v146
	ds_read_b128 v[138:141], v146 offset:1024
	ds_read_b128 v[142:145], v146 offset:2048
	ds_read_b128 v[146:149], v146 offset:3072
	ds_read_b128 v[158:161], v170
	ds_read_b128 v[162:165], v170 offset:1024
	ds_read_b128 v[166:169], v170 offset:2048
	ds_read_b128 v[170:173], v170 offset:3072
	s_add_u32 s50, s50, 0x40000
	s_addc_u32 s51, s51, 0
	s_mov_b32 m0, s53
	v_lshl_add_u64 v[244:245], s[50:51], 0, v[152:153]
	ds_read_b128 v[180:183], v179 offset:32768
	ds_read_b128 v[184:187], v179 offset:33792
	ds_read_b128 v[188:191], v179 offset:34816
	ds_read_b128 v[192:195], v179 offset:35840
	ds_read_b128 v[196:199], v179 offset:36864
	ds_read_b128 v[212:215], v179 offset:37888
	ds_read_b128 v[216:219], v179 offset:38912
	ds_read_b128 v[220:223], v179 offset:39936
	global_load_lds_dwordx4 v[244:245], off
	v_lshl_add_u64 v[244:245], s[50:51], 0, v[150:151]
	s_mov_b32 m0, s54
	s_nop 0
	global_load_lds_dwordx4 v[244:245], off
	s_waitcnt vmcnt(8)
	s_waitcnt lgkmcnt(0)
	s_setprio 1
	s_barrier
	v_mfma_f32_16x16x32_bf16 v[130:133], v[134:137], v[180:183], v[130:133]
	v_mfma_f32_16x16x32_bf16 v[126:129], v[142:145], v[180:183], v[126:129]
	v_mfma_f32_16x16x32_bf16 v[118:121], v[134:137], v[188:191], v[118:121]
	v_mfma_f32_16x16x32_bf16 v[110:113], v[142:145], v[188:191], v[110:113]
	v_mfma_f32_16x16x32_bf16 v[102:105], v[134:137], v[196:199], v[102:105]
	v_mfma_f32_16x16x32_bf16 v[94:97], v[142:145], v[196:199], v[94:97]
	v_mfma_f32_16x16x32_bf16 v[86:89], v[134:137], v[216:219], v[86:89]
	v_mfma_f32_16x16x32_bf16 v[78:81], v[142:145], v[216:219], v[78:81]
	v_mfma_f32_16x16x32_bf16 v[130:133], v[138:141], v[184:187], v[130:133]
	v_mfma_f32_16x16x32_bf16 v[126:129], v[146:149], v[184:187], v[126:129]
	v_mfma_f32_16x16x32_bf16 v[118:121], v[138:141], v[192:195], v[118:121]
	v_mfma_f32_16x16x32_bf16 v[110:113], v[146:149], v[192:195], v[110:113]
	v_mfma_f32_16x16x32_bf16 v[102:105], v[138:141], v[212:215], v[102:105]
	v_mfma_f32_16x16x32_bf16 v[94:97], v[146:149], v[212:215], v[94:97]
	v_mfma_f32_16x16x32_bf16 v[86:89], v[138:141], v[220:223], v[86:89]
	v_mfma_f32_16x16x32_bf16 v[78:81], v[146:149], v[220:223], v[78:81]
	v_mfma_f32_16x16x32_bf16 v[122:125], v[158:161], v[180:183], v[122:125]
	v_mfma_f32_16x16x32_bf16 v[114:117], v[166:169], v[180:183], v[114:117]
	v_mfma_f32_16x16x32_bf16 v[106:109], v[158:161], v[188:191], v[106:109]
	v_mfma_f32_16x16x32_bf16 v[98:101], v[166:169], v[188:191], v[98:101]
	v_mfma_f32_16x16x32_bf16 v[90:93], v[158:161], v[196:199], v[90:93]
	v_mfma_f32_16x16x32_bf16 v[82:85], v[166:169], v[196:199], v[82:85]
	v_mfma_f32_16x16x32_bf16 v[74:77], v[158:161], v[216:219], v[74:77]
	v_mfma_f32_16x16x32_bf16 v[70:73], v[166:169], v[216:219], v[70:73]
	v_mfma_f32_16x16x32_bf16 v[122:125], v[162:165], v[184:187], v[122:125]
	v_mfma_f32_16x16x32_bf16 v[114:117], v[170:173], v[184:187], v[114:117]
	v_mfma_f32_16x16x32_bf16 v[106:109], v[162:165], v[192:195], v[106:109]
	v_mfma_f32_16x16x32_bf16 v[98:101], v[170:173], v[192:195], v[98:101]
	v_mfma_f32_16x16x32_bf16 v[90:93], v[162:165], v[212:215], v[90:93]
	v_mfma_f32_16x16x32_bf16 v[82:85], v[170:173], v[212:215], v[82:85]
	v_mfma_f32_16x16x32_bf16 v[74:77], v[162:165], v[220:223], v[74:77]
	v_mfma_f32_16x16x32_bf16 v[70:73], v[170:173], v[220:223], v[70:73]
	s_barrier
	s_setprio 0
	s_add_i32 s50, s63, s1
	v_lshl_add_u64 v[200:201], v[200:201], 0, s[28:29]
	s_mov_b32 m0, s50
	ds_read_b128 v[180:183], v179 offset:49152
	ds_read_b128 v[184:187], v179 offset:50176
	ds_read_b128 v[188:191], v179 offset:51200
	ds_read_b128 v[192:195], v179 offset:52224
	ds_read_b128 v[196:199], v179 offset:53248
	ds_read_b128 v[212:215], v179 offset:54272
	ds_read_b128 v[216:219], v179 offset:55296
	ds_read_b128 v[220:223], v179 offset:56320
	global_load_lds_dwordx4 v[200:201], off
	s_add_i32 m0, s50, 0x2000
	s_add_u32 s48, s48, 0x40080
	v_lshl_add_u64 v[200:201], v[224:225], 0, s[28:29]
	s_addc_u32 s49, s49, 0
	s_add_i32 s50, s64, s1
	global_load_lds_dwordx4 v[200:201], off
	v_lshl_add_u64 v[200:201], s[48:49], 0, v[0:1]
	s_mov_b32 m0, s50
	s_nop 0
	global_load_lds_dwordx4 v[200:201], off
	v_lshl_add_u64 v[200:201], s[48:49], 0, v[14:15]
	s_add_i32 m0, s50, 0x2000
	s_nop 0
	global_load_lds_dwordx4 v[200:201], off
	v_lshl_add_u64 v[200:201], v[226:227], 0, s[28:29]
	s_mov_b32 m0, s55
	s_nop 0
	global_load_lds_dwordx4 v[200:201], off
	v_lshl_add_u64 v[200:201], v[228:229], 0, s[28:29]
	s_mov_b32 m0, s56
	s_nop 0
	global_load_lds_dwordx4 v[200:201], off
	s_waitcnt vmcnt(8)
	s_waitcnt lgkmcnt(0)
	s_setprio 1
	s_barrier
; #define PG8_STAGE(bufoff, gbase, voff) do { _Pragma("unroll") for (int _i = 0; _i < 2; ++_i) \
;         __builtin_amdgcn_global_load_lds((const unsigned*)((const char*)(gbase) + (voff)[_i]), (LAS unsigned*)(lds + (bufoff) + ldsw + _i * 8192), 16, 0, 0); } while (0)
; #define PG8_LDA(dst, b, h) do { _Pragma("unroll") for (int m = 0; m < 4; ++m) _Pragma("unroll") for (int k = 0; k < 2; ++k) dst[m][k] = *(const LAS bf16x8*)(lds + PG8_SA(b, h) + aoff + m * 2048 + k * 1024); } while (0)
; #define PG8_MMA(ai, bj, At, Bt) do { __builtin_amdgcn_s_setprio(1); _Pragma("unroll") for (int m = 0; m < 4; ++m) _Pragma("unroll") for (int n = 0; n < 2; ++n) _Pragma("unroll") for (int k = 0; k < 2; ++k) \
;         acc[ai][bj][m][n] = __builtin_amdgcn_mfma_f32_16x16x32_bf16(Bt[n][k], At[m][k], acc[ai][bj][m][n], 0, 0, 0); __builtin_amdgcn_s_setprio(0); } while (0)
; #define PG8_WAIT_V(n) asm volatile("s_waitcnt vmcnt(" #n ")" ::: "memory")
; #define PG8_WAIT_L(n) asm volatile("s_waitcnt lgkmcnt(" #n ")" ::: "memory")
; #define PG8_BAR __builtin_amdgcn_s_barrier()
; #define PG8_SCHED __builtin_amdgcn_sched_barrier(0)
;     __device__ __forceinline__ void operator()(f32x4 (&acc)[2][2][4][2], const Unit& u, int wr, int wc, int fr, int fq) const {
;     ...
;         if (SCALE) { f32x4 q[8];
; #pragma unroll
;             for (int i = 0; i < 8; ++i) q[i] = *(const f32x4*)(ss + (size_t)(row0 + (i >> 2) * HALF + (i & 3) * 16) * 4);
; template <class Epi, bool SEG>
; __device__ __forceinline__ void gemm_phase(LAS unsigned char* lds, const Gemm g, const int G, const int cidx, const Epi& E) {
;     ...
;             PG8_LDA(At, 1, 1); PG8_STAGE(PG8_SB(1, 0), b3, voffB); PG8_STAGE(PG8_SB(1, 1), b3 + hstepB, voffB); PG8_STAGE(PG8_SA(1, 0), a3, voffA);
;             PG8_WAIT_V(8); PG8_WAIT_L(0); PG8_BAR; PG8_MMA(1, 0, At, B0); PG8_MMA(1, 1, At, B1); PG8_BAR; PG8_SCHED;
;         }
;         if (wr == 0) PG8_BAR;
	v_mfma_f32_16x16x32_bf16 v[66:69], v[134:137], v[180:183], v[66:69]
	v_mfma_f32_16x16x32_bf16 v[62:65], v[142:145], v[180:183], v[62:65]
	v_mfma_f32_16x16x32_bf16 v[54:57], v[134:137], v[188:191], v[54:57]
	v_mfma_f32_16x16x32_bf16 v[46:49], v[142:145], v[188:191], v[46:49]
	v_mfma_f32_16x16x32_bf16 v[38:41], v[134:137], v[196:199], v[38:41]
	v_mfma_f32_16x16x32_bf16 v[30:33], v[142:145], v[196:199], v[30:33]
	v_mfma_f32_16x16x32_bf16 v[22:25], v[134:137], v[216:219], v[22:25]
	v_mfma_f32_16x16x32_bf16 v[10:13], v[142:145], v[216:219], v[10:13]
	v_mfma_f32_16x16x32_bf16 v[66:69], v[138:141], v[184:187], v[66:69]
	v_mfma_f32_16x16x32_bf16 v[62:65], v[146:149], v[184:187], v[62:65]
	v_mfma_f32_16x16x32_bf16 v[54:57], v[138:141], v[192:195], v[54:57]
	v_mfma_f32_16x16x32_bf16 v[46:49], v[146:149], v[192:195], v[46:49]
	v_mfma_f32_16x16x32_bf16 v[38:41], v[138:141], v[212:215], v[38:41]
	v_mfma_f32_16x16x32_bf16 v[30:33], v[146:149], v[212:215], v[30:33]
	v_mfma_f32_16x16x32_bf16 v[22:25], v[138:141], v[220:223], v[22:25]
	v_mfma_f32_16x16x32_bf16 v[10:13], v[146:149], v[220:223], v[10:13]
	v_mfma_f32_16x16x32_bf16 v[58:61], v[158:161], v[180:183], v[58:61]
	v_mfma_f32_16x16x32_bf16 v[50:53], v[166:169], v[180:183], v[50:53]
	v_mfma_f32_16x16x32_bf16 v[42:45], v[158:161], v[188:191], v[42:45]
	v_mfma_f32_16x16x32_bf16 v[34:37], v[166:169], v[188:191], v[34:37]
	v_mfma_f32_16x16x32_bf16 v[26:29], v[158:161], v[196:199], v[26:29]
	v_mfma_f32_16x16x32_bf16 v[18:21], v[166:169], v[196:199], v[18:21]
	v_mfma_f32_16x16x32_bf16 v[6:9], v[158:161], v[216:219], v[6:9]
	v_mfma_f32_16x16x32_bf16 v[2:5], v[166:169], v[216:219], v[2:5]
	v_mfma_f32_16x16x32_bf16 v[58:61], v[162:165], v[184:187], v[58:61]
	v_mfma_f32_16x16x32_bf16 v[50:53], v[170:173], v[184:187], v[50:53]
	v_mfma_f32_16x16x32_bf16 v[42:45], v[162:165], v[192:195], v[42:45]
	v_mfma_f32_16x16x32_bf16 v[34:37], v[170:173], v[192:195], v[34:37]
	v_mfma_f32_16x16x32_bf16 v[26:29], v[162:165], v[212:215], v[26:29]
	v_mfma_f32_16x16x32_bf16 v[18:21], v[170:173], v[212:215], v[18:21]
	v_mfma_f32_16x16x32_bf16 v[6:9], v[162:165], v[220:223], v[6:9]
	v_mfma_f32_16x16x32_bf16 v[2:5], v[170:173], v[220:223], v[2:5]
	s_barrier
	s_setprio 0
	s_add_i32 s62, s62, 2
	s_add_u32 s46, s46, 0x100
	s_addc_u32 s47, s47, 0
	s_add_u32 s60, s60, 0x100
	s_addc_u32 s61, s61, 0
	s_cmp_gt_u32 s62, 13
	s_cbranch_scc0 .LBB0_294
	v_lshl_add_u32 v172, s6, 8, v17
	v_readlane_b32 s6, v252, 28
	v_ashrrev_i32_e32 v173, 31, v172
	v_readlane_b32 s7, v252, 29
	v_or_b32_e32 v170, 16, v172
	v_ashrrev_i32_e32 v171, 31, v170
	v_lshl_add_u64 v[134:135], v[172:173], 4, s[6:7]
	global_load_dwordx4 v[180:183], v[134:135], off
	v_lshl_add_u64 v[134:135], v[170:171], 4, s[6:7]
	global_load_dwordx4 v[184:187], v[134:135], off
	v_or_b32_e32 v168, 32, v172
	v_ashrrev_i32_e32 v169, 31, v168
	v_or_b32_e32 v166, 48, v172
	v_lshl_add_u64 v[134:135], v[168:169], 4, s[6:7]
	v_ashrrev_i32_e32 v167, 31, v166
	global_load_dwordx4 v[188:191], v[134:135], off
	v_lshl_add_u64 v[134:135], v[166:167], 4, s[6:7]
	global_load_dwordx4 v[192:195], v[134:135], off
	v_add_u32_e32 v164, 0x80, v172
	v_ashrrev_i32_e32 v165, 31, v164
	v_add_u32_e32 v162, 0x90, v172
	v_lshl_add_u64 v[134:135], v[164:165], 4, s[6:7]
	v_ashrrev_i32_e32 v163, 31, v162
	global_load_dwordx4 v[146:149], v[134:135], off
	v_lshl_add_u64 v[134:135], v[162:163], 4, s[6:7]
	global_load_dwordx4 v[142:145], v[134:135], off
	v_add_u32_e32 v160, 0xa0, v172
	v_ashrrev_i32_e32 v161, 31, v160
	v_add_u32_e32 v158, 0xb0, v172
	v_lshl_add_u64 v[134:135], v[160:161], 4, s[6:7]
	v_ashrrev_i32_e32 v159, 31, v158
	global_load_dwordx4 v[138:141], v[134:135], off
	v_lshl_add_u64 v[134:135], v[158:159], 4, s[6:7]
	global_load_dwordx4 v[134:137], v[134:135], off
	s_and_b64 vcc, exec, s[18:19]
	s_cbranch_vccz .LBB0_297
	s_barrier

; #define PG8_STAGE(bufoff, gbase, voff) do { _Pragma("unroll") for (int _i = 0; _i < 2; ++_i) \
;         __builtin_amdgcn_global_load_lds((const unsigned*)((const char*)(gbase) + (voff)[_i]), (LAS unsigned*)(lds + (bufoff) + ldsw + _i * 8192), 16, 0, 0); } while (0)
; #define PG8_LDA(dst, b, h) do { _Pragma("unroll") for (int m = 0; m < 4; ++m) _Pragma("unroll") for (int k = 0; k < 2; ++k) dst[m][k] = *(const LAS bf16x8*)(lds + PG8_SA(b, h) + aoff + m * 2048 + k * 1024); } while (0)
; #define PG8_LDB(dst, b, h) do { _Pragma("unroll") for (int n = 0; n < 2; ++n) _Pragma("unroll") for (int k = 0; k < 2; ++k) dst[n][k] = *(const LAS bf16x8*)(lds + PG8_SB(b, h) + boff + n * 2048 + k * 1024); } while (0)
; #define PG8_MMA(ai, bj, At, Bt) do { __builtin_amdgcn_s_setprio(1); _Pragma("unroll") for (int m = 0; m < 4; ++m) _Pragma("unroll") for (int n = 0; n < 2; ++n) _Pragma("unroll") for (int k = 0; k < 2; ++k) \
;         acc[ai][bj][m][n] = __builtin_amdgcn_mfma_f32_16x16x32_bf16(Bt[n][k], At[m][k], acc[ai][bj][m][n], 0, 0, 0); __builtin_amdgcn_s_setprio(0); } while (0)
; #define PG8_BAR __builtin_amdgcn_s_barrier()
; template <class Epi, bool SEG>
; __device__ __forceinline__ void gemm_phase(LAS unsigned char* lds, const Gemm g, const int G, const int cidx, const Epi& E) {
;     ...
;         const bool has_next = S.next(ui + 1, nxt);
;         const char* nA = has_next ? (const char*)g.A + (long)nxt.pm * (long)tstepA + aoff0 : cA; const char* nB = has_next ? (const char*)g.Bt + (size_t)nxt.pn * tstepB : cB;
;         for (int t = 0; t < nt; t += 2) {
;             const bool last = (t == nt - 2);
;             const char* a1 = cA + (size_t)(t + 1) * kstep;
;             const char* a2 = last ? nA : cA + (size_t)(t + 2) * kstep; const char* b2 = last ? nB : cB + (size_t)(t + 2) * kstep;
;             const char* a3 = a2 + kstep; const char* b3 = b2 + kstep;
;             PG8_LDB(B0, 0, 0); PG8_LDB(B1, 0, 1); PG8_SCHED; PG8_LDA(At, 0, 0); PG8_STAGE(PG8_SA(1, 1), a1 + hstepA, voffA);
;             PG8_WAIT_V(8); PG8_WAIT_L(0); PG8_BAR; PG8_MMA(0, 0, At, B0); PG8_MMA(0, 1, At, B1); PG8_BAR; PG8_SCHED;
;             PG8_LDA(At, 0, 1); PG8_STAGE(PG8_SB(0, 0), b2, voffB); PG8_STAGE(PG8_SB(0, 1), b2 + hstepB, voffB); PG8_STAGE(PG8_SA(0, 0), a2, voffA);
;             PG8_WAIT_V(8); PG8_WAIT_L(0); PG8_BAR; PG8_MMA(1, 0, At, B0); PG8_MMA(1, 1, At, B1); PG8_BAR; PG8_SCHED;
.LBB0_705:
	s_ashr_i32 s19, s18, 31
	s_lshl_b64 s[20:21], s[18:19], 19
	s_add_u32 s20, s6, s20
	s_addc_u32 s21, s7, s21
	s_and_b64 s[22:23], s[46:47], exec
	s_cselect_b32 s19, s21, s41
	s_cselect_b32 s54, s20, s40
	s_ashr_i32 s17, s16, 31
	s_lshl_b64 s[22:23], s[16:17], 19
	s_add_u32 s22, s8, s22
	s_addc_u32 s23, s1, s23
	s_and_b64 s[50:51], s[46:47], exec
	s_cselect_b32 s17, s23, s49
	s_cselect_b32 s55, s22, s48
	s_add_u32 s40, s40, 0x40080
	s_addc_u32 s41, s41, 0
	s_add_u32 s56, s48, 0x100
	s_addc_u32 s57, s49, 0
	s_mov_b32 s58, -2
	s_waitcnt lgkmcnt(0)
	s_waitcnt vmcnt(0)
	s_add_u32 s48, s40, 0xfffc0080
	s_addc_u32 s49, s41, -1
	s_add_i32 s59, 0, 0x10000
	s_cmp_eq_u32 s58, 12
	s_cselect_b32 s51, s19, s49
	s_cselect_b32 s50, s54, s48
	s_cselect_b32 s49, s17, s57
	s_cselect_b32 s48, s55, s56
	s_add_i32 s62, 0, 0x14000
	v_add_u32_e32 v146, s59, v228
	v_add_u32_e32 v162, s62, v228
	ds_read_b128 v[130:133], v146
	ds_read_b128 v[138:141], v146 offset:1024
	ds_read_b128 v[142:145], v146 offset:2048
	ds_read_b128 v[146:149], v146 offset:3072
	ds_read_b128 v[150:153], v162
	ds_read_b128 v[154:157], v162 offset:1024
	ds_read_b128 v[158:161], v162 offset:2048
	ds_read_b128 v[162:165], v162 offset:3072
	v_lshl_add_u64 v[216:217], s[40:41], 0, v[198:199]
	s_add_i32 m0, s30, 0xc000
	ds_read_b128 v[166:169], v244
	ds_read_b128 v[170:173], v244 offset:1024
	ds_read_b128 v[174:177], v244 offset:2048
	ds_read_b128 v[178:181], v244 offset:3072
	ds_read_b128 v[182:185], v244 offset:4096
	ds_read_b128 v[186:189], v244 offset:5120
	ds_read_b128 v[190:193], v244 offset:6144
	ds_read_b128 v[212:215], v244 offset:7168
	global_load_lds_dwordx4 v[216:217], off
	v_lshl_add_u64 v[216:217], s[40:41], 0, v[200:201]
	s_add_i32 m0, s30, 0xe000
	s_nop 0
	global_load_lds_dwordx4 v[216:217], off
	s_waitcnt vmcnt(8)
	s_waitcnt lgkmcnt(0)
	s_setprio 1
	s_barrier
	v_mfma_f32_16x16x32_bf16 v[134:137], v[130:133], v[166:169], 0
	v_mfma_f32_16x16x32_bf16 v[126:129], v[142:145], v[166:169], 0
	v_mfma_f32_16x16x32_bf16 v[114:117], v[130:133], v[174:177], 0
	v_mfma_f32_16x16x32_bf16 v[110:113], v[142:145], v[174:177], 0
	v_mfma_f32_16x16x32_bf16 v[98:101], v[130:133], v[182:185], 0
	v_mfma_f32_16x16x32_bf16 v[94:97], v[142:145], v[182:185], 0
	v_mfma_f32_16x16x32_bf16 v[82:85], v[130:133], v[190:193], 0
	v_mfma_f32_16x16x32_bf16 v[78:81], v[142:145], v[190:193], 0
	v_mfma_f32_16x16x32_bf16 v[134:137], v[138:141], v[170:173], v[134:137]
	v_mfma_f32_16x16x32_bf16 v[126:129], v[146:149], v[170:173], v[126:129]
	v_mfma_f32_16x16x32_bf16 v[114:117], v[138:141], v[178:181], v[114:117]
	v_mfma_f32_16x16x32_bf16 v[110:113], v[146:149], v[178:181], v[110:113]
	v_mfma_f32_16x16x32_bf16 v[98:101], v[138:141], v[186:189], v[98:101]
	v_mfma_f32_16x16x32_bf16 v[94:97], v[146:149], v[186:189], v[94:97]
	v_mfma_f32_16x16x32_bf16 v[82:85], v[138:141], v[212:215], v[82:85]
	v_mfma_f32_16x16x32_bf16 v[78:81], v[146:149], v[212:215], v[78:81]
	v_mfma_f32_16x16x32_bf16 v[122:125], v[150:153], v[166:169], 0
	v_mfma_f32_16x16x32_bf16 v[118:121], v[158:161], v[166:169], 0
	v_mfma_f32_16x16x32_bf16 v[106:109], v[150:153], v[174:177], 0
	v_mfma_f32_16x16x32_bf16 v[102:105], v[158:161], v[174:177], 0
	v_mfma_f32_16x16x32_bf16 v[90:93], v[150:153], v[182:185], 0
	v_mfma_f32_16x16x32_bf16 v[86:89], v[158:161], v[182:185], 0
	v_mfma_f32_16x16x32_bf16 v[74:77], v[150:153], v[190:193], 0
	v_mfma_f32_16x16x32_bf16 v[70:73], v[158:161], v[190:193], 0
	v_mfma_f32_16x16x32_bf16 v[122:125], v[154:157], v[170:173], v[122:125]
	v_mfma_f32_16x16x32_bf16 v[118:121], v[162:165], v[170:173], v[118:121]
	v_mfma_f32_16x16x32_bf16 v[106:109], v[154:157], v[178:181], v[106:109]
	v_mfma_f32_16x16x32_bf16 v[102:105], v[162:165], v[178:181], v[102:105]
	v_mfma_f32_16x16x32_bf16 v[90:93], v[154:157], v[186:189], v[90:93]
	v_mfma_f32_16x16x32_bf16 v[86:89], v[162:165], v[186:189], v[86:89]
	v_mfma_f32_16x16x32_bf16 v[74:77], v[154:157], v[212:215], v[74:77]
	v_mfma_f32_16x16x32_bf16 v[70:73], v[162:165], v[212:215], v[70:73]
	s_barrier
	s_setprio 0
	s_add_i32 s59, s59, s9
	v_lshl_add_u64 v[216:217], s[48:49], 0, v[0:1]
	s_mov_b32 m0, s59
	ds_read_b128 v[166:169], v244 offset:16384
	ds_read_b128 v[170:173], v244 offset:17408
	ds_read_b128 v[174:177], v244 offset:18432
	ds_read_b128 v[178:181], v244 offset:19456
	ds_read_b128 v[182:185], v244 offset:20480
	ds_read_b128 v[186:189], v244 offset:21504
	ds_read_b128 v[190:193], v244 offset:22528
	ds_read_b128 v[212:215], v244 offset:23552
	global_load_lds_dwordx4 v[216:217], off
	s_add_i32 m0, s59, 0x2000
	s_add_u32 s60, s48, 0x40000
	v_lshl_add_u64 v[218:219], s[48:49], 0, v[14:15]
	s_addc_u32 s61, s49, 0
	s_add_i32 s59, s62, s9
	global_load_lds_dwordx4 v[218:219], off
	v_lshl_add_u64 v[220:221], s[60:61], 0, v[0:1]
	s_mov_b32 m0, s59
	v_lshl_add_u64 v[222:223], s[50:51], 0, v[194:195]
	global_load_lds_dwordx4 v[220:221], off
	v_lshl_add_u64 v[220:221], s[60:61], 0, v[14:15]
	s_add_i32 m0, s59, 0x2000
	s_nop 0
	global_load_lds_dwordx4 v[220:221], off
	v_lshl_add_u64 v[220:221], s[50:51], 0, v[196:197]
	s_mov_b32 m0, s30
	s_nop 0
	global_load_lds_dwordx4 v[220:221], off
	s_mov_b32 m0, s31
	s_nop 0
	global_load_lds_dwordx4 v[222:223], off
	s_waitcnt vmcnt(8)
	s_waitcnt lgkmcnt(0)
	s_setprio 1
	s_barrier
; #define PG8_STAGE(bufoff, gbase, voff) do { _Pragma("unroll") for (int _i = 0; _i < 2; ++_i) \
;         __builtin_amdgcn_global_load_lds((const unsigned*)((const char*)(gbase) + (voff)[_i]), (LAS unsigned*)(lds + (bufoff) + ldsw + _i * 8192), 16, 0, 0); } while (0)
; #define PG8_LDA(dst, b, h) do { _Pragma("unroll") for (int m = 0; m < 4; ++m) _Pragma("unroll") for (int k = 0; k < 2; ++k) dst[m][k] = *(const LAS bf16x8*)(lds + PG8_SA(b, h) + aoff + m * 2048 + k * 1024); } while (0)
; #define PG8_LDB(dst, b, h) do { _Pragma("unroll") for (int n = 0; n < 2; ++n) _Pragma("unroll") for (int k = 0; k < 2; ++k) dst[n][k] = *(const LAS bf16x8*)(lds + PG8_SB(b, h) + boff + n * 2048 + k * 1024); } while (0)
; #define PG8_MMA(ai, bj, At, Bt) do { __builtin_amdgcn_s_setprio(1); _Pragma("unroll") for (int m = 0; m < 4; ++m) _Pragma("unroll") for (int n = 0; n < 2; ++n) _Pragma("unroll") for (int k = 0; k < 2; ++k) \
;         acc[ai][bj][m][n] = __builtin_amdgcn_mfma_f32_16x16x32_bf16(Bt[n][k], At[m][k], acc[ai][bj][m][n], 0, 0, 0); __builtin_amdgcn_s_setprio(0); } while (0)
; #define PG8_WAIT_V(n) asm volatile("s_waitcnt vmcnt(" #n ")" ::: "memory")
; #define PG8_WAIT_L(n) asm volatile("s_waitcnt lgkmcnt(" #n ")" ::: "memory")
; #define PG8_BAR __builtin_amdgcn_s_barrier()
; #define PG8_SCHED __builtin_amdgcn_sched_barrier(0)
; template <class Epi, bool SEG>
; __device__ __forceinline__ void gemm_phase(LAS unsigned char* lds, const Gemm g, const int G, const int cidx, const Epi& E) {
;     ...
;             PG8_WAIT_V(8); PG8_WAIT_L(0); PG8_BAR; PG8_MMA(1, 0, At, B0); PG8_MMA(1, 1, At, B1); PG8_BAR; PG8_SCHED;
;             PG8_LDB(B0, 1, 0); PG8_LDB(B1, 1, 1); PG8_SCHED; PG8_LDA(At, 1, 0); PG8_STAGE(PG8_SA(0, 1), a2 + hstepA, voffA);
;             PG8_WAIT_V(8); PG8_WAIT_L(0); PG8_BAR; PG8_MMA(0, 0, At, B0); PG8_MMA(0, 1, At, B1); PG8_BAR; PG8_SCHED;
;             PG8_LDA(At, 1, 1); PG8_STAGE(PG8_SB(1, 0), b3, voffB); PG8_STAGE(PG8_SB(1, 1), b3 + hstepB, voffB); PG8_STAGE(PG8_SA(1, 0), a3, voffA);
	v_mfma_f32_16x16x32_bf16 v[66:69], v[130:133], v[166:169], 0
	v_mfma_f32_16x16x32_bf16 v[62:65], v[142:145], v[166:169], 0
	v_mfma_f32_16x16x32_bf16 v[50:53], v[130:133], v[174:177], 0
	v_mfma_f32_16x16x32_bf16 v[46:49], v[142:145], v[174:177], 0
	v_mfma_f32_16x16x32_bf16 v[34:37], v[130:133], v[182:185], 0
	v_mfma_f32_16x16x32_bf16 v[30:33], v[142:145], v[182:185], 0
	v_mfma_f32_16x16x32_bf16 v[18:21], v[130:133], v[190:193], 0
	v_mfma_f32_16x16x32_bf16 v[10:13], v[142:145], v[190:193], 0
	v_mfma_f32_16x16x32_bf16 v[66:69], v[138:141], v[170:173], v[66:69]
	v_mfma_f32_16x16x32_bf16 v[62:65], v[146:149], v[170:173], v[62:65]
	v_mfma_f32_16x16x32_bf16 v[50:53], v[138:141], v[178:181], v[50:53]
	v_mfma_f32_16x16x32_bf16 v[46:49], v[146:149], v[178:181], v[46:49]
	v_mfma_f32_16x16x32_bf16 v[34:37], v[138:141], v[186:189], v[34:37]
	v_mfma_f32_16x16x32_bf16 v[30:33], v[146:149], v[186:189], v[30:33]
	v_mfma_f32_16x16x32_bf16 v[18:21], v[138:141], v[212:215], v[18:21]
	v_mfma_f32_16x16x32_bf16 v[10:13], v[146:149], v[212:215], v[10:13]
	v_mfma_f32_16x16x32_bf16 v[58:61], v[150:153], v[166:169], 0
	v_mfma_f32_16x16x32_bf16 v[54:57], v[158:161], v[166:169], 0
	v_mfma_f32_16x16x32_bf16 v[42:45], v[150:153], v[174:177], 0
	v_mfma_f32_16x16x32_bf16 v[38:41], v[158:161], v[174:177], 0
	v_mfma_f32_16x16x32_bf16 v[26:29], v[150:153], v[182:185], 0
	v_mfma_f32_16x16x32_bf16 v[22:25], v[158:161], v[182:185], 0
	v_mfma_f32_16x16x32_bf16 v[6:9], v[150:153], v[190:193], 0
	v_mfma_f32_16x16x32_bf16 v[2:5], v[158:161], v[190:193], 0
	v_mfma_f32_16x16x32_bf16 v[58:61], v[154:157], v[170:173], v[58:61]
	v_mfma_f32_16x16x32_bf16 v[54:57], v[162:165], v[170:173], v[54:57]
	v_mfma_f32_16x16x32_bf16 v[42:45], v[154:157], v[178:181], v[42:45]
	v_mfma_f32_16x16x32_bf16 v[38:41], v[162:165], v[178:181], v[38:41]
	v_mfma_f32_16x16x32_bf16 v[26:29], v[154:157], v[186:189], v[26:29]
	v_mfma_f32_16x16x32_bf16 v[22:25], v[162:165], v[186:189], v[22:25]
	v_mfma_f32_16x16x32_bf16 v[6:9], v[154:157], v[212:215], v[6:9]
	v_mfma_f32_16x16x32_bf16 v[2:5], v[162:165], v[212:215], v[2:5]
	s_barrier
	s_setprio 0
	s_add_i32 s59, 0, 0x18000
	s_add_i32 s60, 0, 0x1c000
	v_add_u32_e32 v146, s59, v228
	v_add_u32_e32 v162, s60, v228
	ds_read_b128 v[130:133], v146
	ds_read_b128 v[138:141], v146 offset:1024
	ds_read_b128 v[142:145], v146 offset:2048
	ds_read_b128 v[146:149], v146 offset:3072
	ds_read_b128 v[150:153], v162
	ds_read_b128 v[154:157], v162 offset:1024
	ds_read_b128 v[158:161], v162 offset:2048
	ds_read_b128 v[162:165], v162 offset:3072
	s_add_u32 s50, s50, 0x40000
	s_addc_u32 s51, s51, 0
	s_mov_b32 m0, s36
	v_lshl_add_u64 v[224:225], s[50:51], 0, v[196:197]
	ds_read_b128 v[166:169], v244 offset:32768
	ds_read_b128 v[170:173], v244 offset:33792
	ds_read_b128 v[174:177], v244 offset:34816
	ds_read_b128 v[178:181], v244 offset:35840
	ds_read_b128 v[182:185], v244 offset:36864
	ds_read_b128 v[186:189], v244 offset:37888
	ds_read_b128 v[190:193], v244 offset:38912
	ds_read_b128 v[212:215], v244 offset:39936
	global_load_lds_dwordx4 v[224:225], off
	v_lshl_add_u64 v[224:225], s[50:51], 0, v[194:195]
	s_mov_b32 m0, s38
	s_nop 0
	global_load_lds_dwordx4 v[224:225], off
	s_waitcnt vmcnt(8)
	s_waitcnt lgkmcnt(0)
	s_setprio 1
	s_barrier
	v_mfma_f32_16x16x32_bf16 v[134:137], v[130:133], v[166:169], v[134:137]
	v_mfma_f32_16x16x32_bf16 v[126:129], v[142:145], v[166:169], v[126:129]
	v_mfma_f32_16x16x32_bf16 v[114:117], v[130:133], v[174:177], v[114:117]
	v_mfma_f32_16x16x32_bf16 v[110:113], v[142:145], v[174:177], v[110:113]
	v_mfma_f32_16x16x32_bf16 v[98:101], v[130:133], v[182:185], v[98:101]
	v_mfma_f32_16x16x32_bf16 v[94:97], v[142:145], v[182:185], v[94:97]
	v_mfma_f32_16x16x32_bf16 v[82:85], v[130:133], v[190:193], v[82:85]
	v_mfma_f32_16x16x32_bf16 v[78:81], v[142:145], v[190:193], v[78:81]
	v_mfma_f32_16x16x32_bf16 v[134:137], v[138:141], v[170:173], v[134:137]
	v_mfma_f32_16x16x32_bf16 v[126:129], v[146:149], v[170:173], v[126:129]
	v_mfma_f32_16x16x32_bf16 v[114:117], v[138:141], v[178:181], v[114:117]
	v_mfma_f32_16x16x32_bf16 v[110:113], v[146:149], v[178:181], v[110:113]
	v_mfma_f32_16x16x32_bf16 v[98:101], v[138:141], v[186:189], v[98:101]
	v_mfma_f32_16x16x32_bf16 v[94:97], v[146:149], v[186:189], v[94:97]
	v_mfma_f32_16x16x32_bf16 v[82:85], v[138:141], v[212:215], v[82:85]
	v_mfma_f32_16x16x32_bf16 v[78:81], v[146:149], v[212:215], v[78:81]
	v_mfma_f32_16x16x32_bf16 v[122:125], v[150:153], v[166:169], v[122:125]
	v_mfma_f32_16x16x32_bf16 v[118:121], v[158:161], v[166:169], v[118:121]
	v_mfma_f32_16x16x32_bf16 v[106:109], v[150:153], v[174:177], v[106:109]
	v_mfma_f32_16x16x32_bf16 v[102:105], v[158:161], v[174:177], v[102:105]
	v_mfma_f32_16x16x32_bf16 v[90:93], v[150:153], v[182:185], v[90:93]
	v_mfma_f32_16x16x32_bf16 v[86:89], v[158:161], v[182:185], v[86:89]
	v_mfma_f32_16x16x32_bf16 v[74:77], v[150:153], v[190:193], v[74:77]
	v_mfma_f32_16x16x32_bf16 v[70:73], v[158:161], v[190:193], v[70:73]
	v_mfma_f32_16x16x32_bf16 v[122:125], v[154:157], v[170:173], v[122:125]
	v_mfma_f32_16x16x32_bf16 v[118:121], v[162:165], v[170:173], v[118:121]
	v_mfma_f32_16x16x32_bf16 v[106:109], v[154:157], v[178:181], v[106:109]
	v_mfma_f32_16x16x32_bf16 v[102:105], v[162:165], v[178:181], v[102:105]
	v_mfma_f32_16x16x32_bf16 v[90:93], v[154:157], v[186:189], v[90:93]
	v_mfma_f32_16x16x32_bf16 v[86:89], v[162:165], v[186:189], v[86:89]
	v_mfma_f32_16x16x32_bf16 v[74:77], v[154:157], v[212:215], v[74:77]
	v_mfma_f32_16x16x32_bf16 v[70:73], v[162:165], v[212:215], v[70:73]
	s_barrier
; #define PG8_STAGE(bufoff, gbase, voff) do { _Pragma("unroll") for (int _i = 0; _i < 2; ++_i) \
;         __builtin_amdgcn_global_load_lds((const unsigned*)((const char*)(gbase) + (voff)[_i]), (LAS unsigned*)(lds + (bufoff) + ldsw + _i * 8192), 16, 0, 0); } while (0)
; #define PG8_LDA(dst, b, h) do { _Pragma("unroll") for (int m = 0; m < 4; ++m) _Pragma("unroll") for (int k = 0; k < 2; ++k) dst[m][k] = *(const LAS bf16x8*)(lds + PG8_SA(b, h) + aoff + m * 2048 + k * 1024); } while (0)
; #define PG8_LDB(dst, b, h) do { _Pragma("unroll") for (int n = 0; n < 2; ++n) _Pragma("unroll") for (int k = 0; k < 2; ++k) dst[n][k] = *(const LAS bf16x8*)(lds + PG8_SB(b, h) + boff + n * 2048 + k * 1024); } while (0)
; #define PG8_MMA(ai, bj, At, Bt) do { __builtin_amdgcn_s_setprio(1); _Pragma("unroll") for (int m = 0; m < 4; ++m) _Pragma("unroll") for (int n = 0; n < 2; ++n) _Pragma("unroll") for (int k = 0; k < 2; ++k) \
;         acc[ai][bj][m][n] = __builtin_amdgcn_mfma_f32_16x16x32_bf16(Bt[n][k], At[m][k], acc[ai][bj][m][n], 0, 0, 0); __builtin_amdgcn_s_setprio(0); } while (0)
; #define PG8_WAIT_V(n) asm volatile("s_waitcnt vmcnt(" #n ")" ::: "memory")
; #define PG8_WAIT_L(n) asm volatile("s_waitcnt lgkmcnt(" #n ")" ::: "memory")
; #define PG8_BAR __builtin_amdgcn_s_barrier()
; #define PG8_SCHED __builtin_amdgcn_sched_barrier(0)
; template <class Epi, bool SEG>
; __device__ __forceinline__ void gemm_phase(LAS unsigned char* lds, const Gemm g, const int G, const int cidx, const Epi& E) {
;     ...
;         for (int t = 0; t < nt; t += 2) {
;             const bool last = (t == nt - 2);
;             const char* a1 = cA + (size_t)(t + 1) * kstep;
;             const char* a2 = last ? nA : cA + (size_t)(t + 2) * kstep; const char* b2 = last ? nB : cB + (size_t)(t + 2) * kstep;
;             const char* a3 = a2 + kstep; const char* b3 = b2 + kstep;
;             PG8_LDB(B0, 0, 0); PG8_LDB(B1, 0, 1); PG8_SCHED; PG8_LDA(At, 0, 0); PG8_STAGE(PG8_SA(1, 1), a1 + hstepA, voffA);
;             PG8_WAIT_V(8); PG8_WAIT_L(0); PG8_BAR; PG8_MMA(0, 0, At, B0); PG8_MMA(0, 1, At, B1); PG8_BAR; PG8_SCHED;
;     ...
;             PG8_LDA(At, 1, 1); PG8_STAGE(PG8_SB(1, 0), b3, voffB); PG8_STAGE(PG8_SB(1, 1), b3 + hstepB, voffB); PG8_STAGE(PG8_SA(1, 0), a3, voffA);
;             PG8_WAIT_V(8); PG8_WAIT_L(0); PG8_BAR; PG8_MMA(1, 0, At, B0); PG8_MMA(1, 1, At, B1); PG8_BAR; PG8_SCHED;
	s_setprio 0
	s_add_i32 s50, s59, s9
	v_lshl_add_u64 v[216:217], v[216:217], 0, s[28:29]
	s_mov_b32 m0, s50
	ds_read_b128 v[166:169], v244 offset:49152
	ds_read_b128 v[170:173], v244 offset:50176
	ds_read_b128 v[174:177], v244 offset:51200
	ds_read_b128 v[178:181], v244 offset:52224
	ds_read_b128 v[182:185], v244 offset:53248
	ds_read_b128 v[186:189], v244 offset:54272
	ds_read_b128 v[190:193], v244 offset:55296
	ds_read_b128 v[212:215], v244 offset:56320
	global_load_lds_dwordx4 v[216:217], off
	s_add_i32 m0, s50, 0x2000
	s_add_u32 s48, s48, 0x40080
	v_lshl_add_u64 v[216:217], v[218:219], 0, s[28:29]
	s_addc_u32 s49, s49, 0
	s_add_i32 s50, s60, s9
	global_load_lds_dwordx4 v[216:217], off
	v_lshl_add_u64 v[216:217], s[48:49], 0, v[0:1]
	s_mov_b32 m0, s50
	s_nop 0
	global_load_lds_dwordx4 v[216:217], off
	v_lshl_add_u64 v[216:217], s[48:49], 0, v[14:15]
	s_add_i32 m0, s50, 0x2000
	s_nop 0
	global_load_lds_dwordx4 v[216:217], off
	v_lshl_add_u64 v[216:217], v[220:221], 0, s[28:29]
	s_mov_b32 m0, s39
	s_nop 0
	global_load_lds_dwordx4 v[216:217], off
	v_lshl_add_u64 v[216:217], v[222:223], 0, s[28:29]
	s_mov_b32 m0, s52
	s_nop 0
	global_load_lds_dwordx4 v[216:217], off
	s_waitcnt vmcnt(8)
	s_waitcnt lgkmcnt(0)
	s_setprio 1
	s_barrier
	v_mfma_f32_16x16x32_bf16 v[66:69], v[130:133], v[166:169], v[66:69]
	v_mfma_f32_16x16x32_bf16 v[62:65], v[142:145], v[166:169], v[62:65]
	v_mfma_f32_16x16x32_bf16 v[50:53], v[130:133], v[174:177], v[50:53]
	v_mfma_f32_16x16x32_bf16 v[46:49], v[142:145], v[174:177], v[46:49]
	v_mfma_f32_16x16x32_bf16 v[34:37], v[130:133], v[182:185], v[34:37]
	v_mfma_f32_16x16x32_bf16 v[30:33], v[142:145], v[182:185], v[30:33]
	v_mfma_f32_16x16x32_bf16 v[18:21], v[130:133], v[190:193], v[18:21]
	v_mfma_f32_16x16x32_bf16 v[10:13], v[142:145], v[190:193], v[10:13]
	v_mfma_f32_16x16x32_bf16 v[66:69], v[138:141], v[170:173], v[66:69]
	v_mfma_f32_16x16x32_bf16 v[62:65], v[146:149], v[170:173], v[62:65]
	v_mfma_f32_16x16x32_bf16 v[50:53], v[138:141], v[178:181], v[50:53]
	v_mfma_f32_16x16x32_bf16 v[46:49], v[146:149], v[178:181], v[46:49]
	v_mfma_f32_16x16x32_bf16 v[34:37], v[138:141], v[186:189], v[34:37]
	v_mfma_f32_16x16x32_bf16 v[30:33], v[146:149], v[186:189], v[30:33]
	v_mfma_f32_16x16x32_bf16 v[18:21], v[138:141], v[212:215], v[18:21]
	v_mfma_f32_16x16x32_bf16 v[10:13], v[146:149], v[212:215], v[10:13]
	v_mfma_f32_16x16x32_bf16 v[58:61], v[150:153], v[166:169], v[58:61]
	v_mfma_f32_16x16x32_bf16 v[54:57], v[158:161], v[166:169], v[54:57]
	v_mfma_f32_16x16x32_bf16 v[42:45], v[150:153], v[174:177], v[42:45]
	v_mfma_f32_16x16x32_bf16 v[38:41], v[158:161], v[174:177], v[38:41]
	v_mfma_f32_16x16x32_bf16 v[26:29], v[150:153], v[182:185], v[26:29]
	v_mfma_f32_16x16x32_bf16 v[22:25], v[158:161], v[182:185], v[22:25]
	v_mfma_f32_16x16x32_bf16 v[6:9], v[150:153], v[190:193], v[6:9]
	v_mfma_f32_16x16x32_bf16 v[2:5], v[158:161], v[190:193], v[2:5]
	v_mfma_f32_16x16x32_bf16 v[58:61], v[154:157], v[170:173], v[58:61]
	v_mfma_f32_16x16x32_bf16 v[54:57], v[162:165], v[170:173], v[54:57]
	v_mfma_f32_16x16x32_bf16 v[42:45], v[154:157], v[178:181], v[42:45]
	v_mfma_f32_16x16x32_bf16 v[38:41], v[162:165], v[178:181], v[38:41]
	v_mfma_f32_16x16x32_bf16 v[26:29], v[154:157], v[186:189], v[26:29]
	v_mfma_f32_16x16x32_bf16 v[22:25], v[162:165], v[186:189], v[22:25]
	v_mfma_f32_16x16x32_bf16 v[6:9], v[154:157], v[212:215], v[6:9]
	v_mfma_f32_16x16x32_bf16 v[2:5], v[162:165], v[212:215], v[2:5]
	s_barrier
	s_setprio 0
	s_add_i32 s58, s58, 2
	s_add_u32 s40, s40, 0x100
	s_addc_u32 s41, s41, 0
	s_add_u32 s56, s56, 0x100
	s_addc_u32 s57, s57, 0
.LBB0_706:
	s_add_u32 s48, s40, 0xfffc0080
	s_addc_u32 s49, s41, -1
	s_add_i32 s59, 0, 0x10000
	s_cmp_eq_u32 s58, 12
	s_cselect_b32 s51, s19, s49
	s_cselect_b32 s50, s54, s48
	s_cselect_b32 s49, s17, s57
	s_cselect_b32 s48, s55, s56
	s_add_i32 s62, 0, 0x14000
	v_add_u32_e32 v146, s59, v228
	v_add_u32_e32 v162, s62, v228
	ds_read_b128 v[130:133], v146
	ds_read_b128 v[138:141], v146 offset:1024
	ds_read_b128 v[142:145], v146 offset:2048
	ds_read_b128 v[146:149], v146 offset:3072
	ds_read_b128 v[150:153], v162
	ds_read_b128 v[154:157], v162 offset:1024
	ds_read_b128 v[158:161], v162 offset:2048
	ds_read_b128 v[162:165], v162 offset:3072
	v_lshl_add_u64 v[216:217], s[40:41], 0, v[198:199]
	s_add_i32 m0, s30, 0xc000
	ds_read_b128 v[166:169], v244
	ds_read_b128 v[170:173], v244 offset:1024
	ds_read_b128 v[174:177], v244 offset:2048
	ds_read_b128 v[178:181], v244 offset:3072
	ds_read_b128 v[182:185], v244 offset:4096
	ds_read_b128 v[186:189], v244 offset:5120
	ds_read_b128 v[190:193], v244 offset:6144
	ds_read_b128 v[212:215], v244 offset:7168
	global_load_lds_dwordx4 v[216:217], off
	v_lshl_add_u64 v[216:217], s[40:41], 0, v[200:201]
	s_add_i32 m0, s30, 0xe000
	s_nop 0
	global_load_lds_dwordx4 v[216:217], off
	s_waitcnt vmcnt(8)
	s_waitcnt lgkmcnt(0)
	s_setprio 1
	s_barrier
; #define PG8_STAGE(bufoff, gbase, voff) do { _Pragma("unroll") for (int _i = 0; _i < 2; ++_i) \
;         __builtin_amdgcn_global_load_lds((const unsigned*)((const char*)(gbase) + (voff)[_i]), (LAS unsigned*)(lds + (bufoff) + ldsw + _i * 8192), 16, 0, 0); } while (0)
; #define PG8_LDA(dst, b, h) do { _Pragma("unroll") for (int m = 0; m < 4; ++m) _Pragma("unroll") for (int k = 0; k < 2; ++k) dst[m][k] = *(const LAS bf16x8*)(lds + PG8_SA(b, h) + aoff + m * 2048 + k * 1024); } while (0)
; #define PG8_LDB(dst, b, h) do { _Pragma("unroll") for (int n = 0; n < 2; ++n) _Pragma("unroll") for (int k = 0; k < 2; ++k) dst[n][k] = *(const LAS bf16x8*)(lds + PG8_SB(b, h) + boff + n * 2048 + k * 1024); } while (0)
; #define PG8_MMA(ai, bj, At, Bt) do { __builtin_amdgcn_s_setprio(1); _Pragma("unroll") for (int m = 0; m < 4; ++m) _Pragma("unroll") for (int n = 0; n < 2; ++n) _Pragma("unroll") for (int k = 0; k < 2; ++k) \
;         acc[ai][bj][m][n] = __builtin_amdgcn_mfma_f32_16x16x32_bf16(Bt[n][k], At[m][k], acc[ai][bj][m][n], 0, 0, 0); __builtin_amdgcn_s_setprio(0); } while (0)
; #define PG8_WAIT_V(n) asm volatile("s_waitcnt vmcnt(" #n ")" ::: "memory")
; #define PG8_WAIT_L(n) asm volatile("s_waitcnt lgkmcnt(" #n ")" ::: "memory")
; #define PG8_BAR __builtin_amdgcn_s_barrier()
; #define PG8_SCHED __builtin_amdgcn_sched_barrier(0)
; template <class Epi, bool SEG>
; __device__ __forceinline__ void gemm_phase(LAS unsigned char* lds, const Gemm g, const int G, const int cidx, const Epi& E) {
;     ...
;             PG8_WAIT_V(8); PG8_WAIT_L(0); PG8_BAR; PG8_MMA(0, 0, At, B0); PG8_MMA(0, 1, At, B1); PG8_BAR; PG8_SCHED;
;             PG8_LDA(At, 0, 1); PG8_STAGE(PG8_SB(0, 0), b2, voffB); PG8_STAGE(PG8_SB(0, 1), b2 + hstepB, voffB); PG8_STAGE(PG8_SA(0, 0), a2, voffA);
;             PG8_WAIT_V(8); PG8_WAIT_L(0); PG8_BAR; PG8_MMA(1, 0, At, B0); PG8_MMA(1, 1, At, B1); PG8_BAR; PG8_SCHED;
;             PG8_LDB(B0, 1, 0); PG8_LDB(B1, 1, 1); PG8_SCHED; PG8_LDA(At, 1, 0); PG8_STAGE(PG8_SA(0, 1), a2 + hstepA, voffA);
;             PG8_WAIT_V(8); PG8_WAIT_L(0); PG8_BAR; PG8_MMA(0, 0, At, B0); PG8_MMA(0, 1, At, B1); PG8_BAR; PG8_SCHED;
	v_mfma_f32_16x16x32_bf16 v[134:137], v[130:133], v[166:169], v[134:137]
	v_mfma_f32_16x16x32_bf16 v[126:129], v[142:145], v[166:169], v[126:129]
	v_mfma_f32_16x16x32_bf16 v[114:117], v[130:133], v[174:177], v[114:117]
	v_mfma_f32_16x16x32_bf16 v[110:113], v[142:145], v[174:177], v[110:113]
	v_mfma_f32_16x16x32_bf16 v[98:101], v[130:133], v[182:185], v[98:101]
	v_mfma_f32_16x16x32_bf16 v[94:97], v[142:145], v[182:185], v[94:97]
	v_mfma_f32_16x16x32_bf16 v[82:85], v[130:133], v[190:193], v[82:85]
	v_mfma_f32_16x16x32_bf16 v[78:81], v[142:145], v[190:193], v[78:81]
	v_mfma_f32_16x16x32_bf16 v[134:137], v[138:141], v[170:173], v[134:137]
	v_mfma_f32_16x16x32_bf16 v[126:129], v[146:149], v[170:173], v[126:129]
	v_mfma_f32_16x16x32_bf16 v[114:117], v[138:141], v[178:181], v[114:117]
	v_mfma_f32_16x16x32_bf16 v[110:113], v[146:149], v[178:181], v[110:113]
	v_mfma_f32_16x16x32_bf16 v[98:101], v[138:141], v[186:189], v[98:101]
	v_mfma_f32_16x16x32_bf16 v[94:97], v[146:149], v[186:189], v[94:97]
	v_mfma_f32_16x16x32_bf16 v[82:85], v[138:141], v[212:215], v[82:85]
	v_mfma_f32_16x16x32_bf16 v[78:81], v[146:149], v[212:215], v[78:81]
	v_mfma_f32_16x16x32_bf16 v[122:125], v[150:153], v[166:169], v[122:125]
	v_mfma_f32_16x16x32_bf16 v[118:121], v[158:161], v[166:169], v[118:121]
	v_mfma_f32_16x16x32_bf16 v[106:109], v[150:153], v[174:177], v[106:109]
	v_mfma_f32_16x16x32_bf16 v[102:105], v[158:161], v[174:177], v[102:105]
	v_mfma_f32_16x16x32_bf16 v[90:93], v[150:153], v[182:185], v[90:93]
	v_mfma_f32_16x16x32_bf16 v[86:89], v[158:161], v[182:185], v[86:89]
	v_mfma_f32_16x16x32_bf16 v[74:77], v[150:153], v[190:193], v[74:77]
	v_mfma_f32_16x16x32_bf16 v[70:73], v[158:161], v[190:193], v[70:73]
	v_mfma_f32_16x16x32_bf16 v[122:125], v[154:157], v[170:173], v[122:125]
	v_mfma_f32_16x16x32_bf16 v[118:121], v[162:165], v[170:173], v[118:121]
	v_mfma_f32_16x16x32_bf16 v[106:109], v[154:157], v[178:181], v[106:109]
	v_mfma_f32_16x16x32_bf16 v[102:105], v[162:165], v[178:181], v[102:105]
	v_mfma_f32_16x16x32_bf16 v[90:93], v[154:157], v[186:189], v[90:93]
	v_mfma_f32_16x16x32_bf16 v[86:89], v[162:165], v[186:189], v[86:89]
	v_mfma_f32_16x16x32_bf16 v[74:77], v[154:157], v[212:215], v[74:77]
	v_mfma_f32_16x16x32_bf16 v[70:73], v[162:165], v[212:215], v[70:73]
	s_barrier
	s_setprio 0
	s_add_i32 s59, s59, s9
	v_lshl_add_u64 v[216:217], s[48:49], 0, v[0:1]
	s_mov_b32 m0, s59
	ds_read_b128 v[166:169], v244 offset:16384
	ds_read_b128 v[170:173], v244 offset:17408
	ds_read_b128 v[174:177], v244 offset:18432
	ds_read_b128 v[178:181], v244 offset:19456
	ds_read_b128 v[182:185], v244 offset:20480
	ds_read_b128 v[186:189], v244 offset:21504
	ds_read_b128 v[190:193], v244 offset:22528
	ds_read_b128 v[212:215], v244 offset:23552
	global_load_lds_dwordx4 v[216:217], off
	s_add_i32 m0, s59, 0x2000
	s_add_u32 s60, s48, 0x40000
	v_lshl_add_u64 v[218:219], s[48:49], 0, v[14:15]
	s_addc_u32 s61, s49, 0
	s_add_i32 s59, s62, s9
	global_load_lds_dwordx4 v[218:219], off
	v_lshl_add_u64 v[220:221], s[60:61], 0, v[0:1]
	s_mov_b32 m0, s59
	v_lshl_add_u64 v[222:223], s[50:51], 0, v[194:195]
	global_load_lds_dwordx4 v[220:221], off
	v_lshl_add_u64 v[220:221], s[60:61], 0, v[14:15]
	s_add_i32 m0, s59, 0x2000
	s_nop 0
	global_load_lds_dwordx4 v[220:221], off
	v_lshl_add_u64 v[220:221], s[50:51], 0, v[196:197]
	s_mov_b32 m0, s30
	s_nop 0
	global_load_lds_dwordx4 v[220:221], off
	s_mov_b32 m0, s31
	s_nop 0
	global_load_lds_dwordx4 v[222:223], off
	s_waitcnt vmcnt(8)
	s_waitcnt lgkmcnt(0)
	s_setprio 1
	s_barrier
	v_mfma_f32_16x16x32_bf16 v[66:69], v[130:133], v[166:169], v[66:69]
	v_mfma_f32_16x16x32_bf16 v[62:65], v[142:145], v[166:169], v[62:65]
	v_mfma_f32_16x16x32_bf16 v[50:53], v[130:133], v[174:177], v[50:53]
	v_mfma_f32_16x16x32_bf16 v[46:49], v[142:145], v[174:177], v[46:49]
	v_mfma_f32_16x16x32_bf16 v[34:37], v[130:133], v[182:185], v[34:37]
	v_mfma_f32_16x16x32_bf16 v[30:33], v[142:145], v[182:185], v[30:33]
	v_mfma_f32_16x16x32_bf16 v[18:21], v[130:133], v[190:193], v[18:21]
	v_mfma_f32_16x16x32_bf16 v[10:13], v[142:145], v[190:193], v[10:13]
	v_mfma_f32_16x16x32_bf16 v[66:69], v[138:141], v[170:173], v[66:69]
	v_mfma_f32_16x16x32_bf16 v[62:65], v[146:149], v[170:173], v[62:65]
	v_mfma_f32_16x16x32_bf16 v[50:53], v[138:141], v[178:181], v[50:53]
	v_mfma_f32_16x16x32_bf16 v[46:49], v[146:149], v[178:181], v[46:49]
	v_mfma_f32_16x16x32_bf16 v[34:37], v[138:141], v[186:189], v[34:37]
	v_mfma_f32_16x16x32_bf16 v[30:33], v[146:149], v[186:189], v[30:33]
	v_mfma_f32_16x16x32_bf16 v[18:21], v[138:141], v[212:215], v[18:21]
	v_mfma_f32_16x16x32_bf16 v[10:13], v[146:149], v[212:215], v[10:13]
	v_mfma_f32_16x16x32_bf16 v[58:61], v[150:153], v[166:169], v[58:61]
	v_mfma_f32_16x16x32_bf16 v[54:57], v[158:161], v[166:169], v[54:57]
	v_mfma_f32_16x16x32_bf16 v[42:45], v[150:153], v[174:177], v[42:45]
	v_mfma_f32_16x16x32_bf16 v[38:41], v[158:161], v[174:177], v[38:41]
	v_mfma_f32_16x16x32_bf16 v[26:29], v[150:153], v[182:185], v[26:29]
	v_mfma_f32_16x16x32_bf16 v[22:25], v[158:161], v[182:185], v[22:25]
	v_mfma_f32_16x16x32_bf16 v[6:9], v[150:153], v[190:193], v[6:9]
	v_mfma_f32_16x16x32_bf16 v[2:5], v[158:161], v[190:193], v[2:5]
	v_mfma_f32_16x16x32_bf16 v[58:61], v[154:157], v[170:173], v[58:61]
	v_mfma_f32_16x16x32_bf16 v[54:57], v[162:165], v[170:173], v[54:57]
	v_mfma_f32_16x16x32_bf16 v[42:45], v[154:157], v[178:181], v[42:45]
	v_mfma_f32_16x16x32_bf16 v[38:41], v[162:165], v[178:181], v[38:41]
	v_mfma_f32_16x16x32_bf16 v[26:29], v[154:157], v[186:189], v[26:29]
	v_mfma_f32_16x16x32_bf16 v[22:25], v[162:165], v[186:189], v[22:25]
	v_mfma_f32_16x16x32_bf16 v[6:9], v[154:157], v[212:215], v[6:9]
	v_mfma_f32_16x16x32_bf16 v[2:5], v[162:165], v[212:215], v[2:5]
	s_barrier
; #define PG8_STAGE(bufoff, gbase, voff) do { _Pragma("unroll") for (int _i = 0; _i < 2; ++_i) \
;         __builtin_amdgcn_global_load_lds((const unsigned*)((const char*)(gbase) + (voff)[_i]), (LAS unsigned*)(lds + (bufoff) + ldsw + _i * 8192), 16, 0, 0); } while (0)
; #define PG8_LDA(dst, b, h) do { _Pragma("unroll") for (int m = 0; m < 4; ++m) _Pragma("unroll") for (int k = 0; k < 2; ++k) dst[m][k] = *(const LAS bf16x8*)(lds + PG8_SA(b, h) + aoff + m * 2048 + k * 1024); } while (0)
; #define PG8_LDB(dst, b, h) do { _Pragma("unroll") for (int n = 0; n < 2; ++n) _Pragma("unroll") for (int k = 0; k < 2; ++k) dst[n][k] = *(const LAS bf16x8*)(lds + PG8_SB(b, h) + boff + n * 2048 + k * 1024); } while (0)
; #define PG8_MMA(ai, bj, At, Bt) do { __builtin_amdgcn_s_setprio(1); _Pragma("unroll") for (int m = 0; m < 4; ++m) _Pragma("unroll") for (int n = 0; n < 2; ++n) _Pragma("unroll") for (int k = 0; k < 2; ++k) \
;         acc[ai][bj][m][n] = __builtin_amdgcn_mfma_f32_16x16x32_bf16(Bt[n][k], At[m][k], acc[ai][bj][m][n], 0, 0, 0); __builtin_amdgcn_s_setprio(0); } while (0)
; #define PG8_WAIT_V(n) asm volatile("s_waitcnt vmcnt(" #n ")" ::: "memory")
; #define PG8_WAIT_L(n) asm volatile("s_waitcnt lgkmcnt(" #n ")" ::: "memory")
; #define PG8_BAR __builtin_amdgcn_s_barrier()
; #define PG8_SCHED __builtin_amdgcn_sched_barrier(0)
; template <class Epi, bool SEG>
; __device__ __forceinline__ void gemm_phase(LAS unsigned char* lds, const Gemm g, const int G, const int cidx, const Epi& E) {
;     ...
;             PG8_LDB(B0, 1, 0); PG8_LDB(B1, 1, 1); PG8_SCHED; PG8_LDA(At, 1, 0); PG8_STAGE(PG8_SA(0, 1), a2 + hstepA, voffA);
;             PG8_WAIT_V(8); PG8_WAIT_L(0); PG8_BAR; PG8_MMA(0, 0, At, B0); PG8_MMA(0, 1, At, B1); PG8_BAR; PG8_SCHED;
	s_setprio 0
	s_add_i32 s59, 0, 0x18000
	s_add_i32 s60, 0, 0x1c000
	v_add_u32_e32 v146, s59, v228
	v_add_u32_e32 v162, s60, v228
	ds_read_b128 v[130:133], v146
	ds_read_b128 v[138:141], v146 offset:1024
	ds_read_b128 v[142:145], v146 offset:2048
	ds_read_b128 v[146:149], v146 offset:3072
	ds_read_b128 v[150:153], v162
	ds_read_b128 v[154:157], v162 offset:1024
	ds_read_b128 v[158:161], v162 offset:2048
	ds_read_b128 v[162:165], v162 offset:3072
	s_add_u32 s50, s50, 0x40000
	s_addc_u32 s51, s51, 0
	s_mov_b32 m0, s36
	v_lshl_add_u64 v[224:225], s[50:51], 0, v[196:197]
	ds_read_b128 v[166:169], v244 offset:32768
	ds_read_b128 v[170:173], v244 offset:33792
	ds_read_b128 v[174:177], v244 offset:34816
	ds_read_b128 v[178:181], v244 offset:35840
	ds_read_b128 v[182:185], v244 offset:36864
	ds_read_b128 v[186:189], v244 offset:37888
	ds_read_b128 v[190:193], v244 offset:38912
	ds_read_b128 v[212:215], v244 offset:39936
	global_load_lds_dwordx4 v[224:225], off
	v_lshl_add_u64 v[224:225], s[50:51], 0, v[194:195]
	s_mov_b32 m0, s38
	s_nop 0
	global_load_lds_dwordx4 v[224:225], off
	s_waitcnt vmcnt(8)
	s_waitcnt lgkmcnt(0)
	s_setprio 1
	s_barrier
	v_mfma_f32_16x16x32_bf16 v[134:137], v[130:133], v[166:169], v[134:137]
	v_mfma_f32_16x16x32_bf16 v[126:129], v[142:145], v[166:169], v[126:129]
	v_mfma_f32_16x16x32_bf16 v[114:117], v[130:133], v[174:177], v[114:117]
	v_mfma_f32_16x16x32_bf16 v[110:113], v[142:145], v[174:177], v[110:113]
	v_mfma_f32_16x16x32_bf16 v[98:101], v[130:133], v[182:185], v[98:101]
	v_mfma_f32_16x16x32_bf16 v[94:97], v[142:145], v[182:185], v[94:97]
	v_mfma_f32_16x16x32_bf16 v[82:85], v[130:133], v[190:193], v[82:85]
	v_mfma_f32_16x16x32_bf16 v[78:81], v[142:145], v[190:193], v[78:81]
	v_mfma_f32_16x16x32_bf16 v[134:137], v[138:141], v[170:173], v[134:137]
	v_mfma_f32_16x16x32_bf16 v[126:129], v[146:149], v[170:173], v[126:129]
	v_mfma_f32_16x16x32_bf16 v[114:117], v[138:141], v[178:181], v[114:117]
	v_mfma_f32_16x16x32_bf16 v[110:113], v[146:149], v[178:181], v[110:113]
	v_mfma_f32_16x16x32_bf16 v[98:101], v[138:141], v[186:189], v[98:101]
	v_mfma_f32_16x16x32_bf16 v[94:97], v[146:149], v[186:189], v[94:97]
	v_mfma_f32_16x16x32_bf16 v[82:85], v[138:141], v[212:215], v[82:85]
	v_mfma_f32_16x16x32_bf16 v[78:81], v[146:149], v[212:215], v[78:81]
	v_mfma_f32_16x16x32_bf16 v[122:125], v[150:153], v[166:169], v[122:125]
	v_mfma_f32_16x16x32_bf16 v[118:121], v[158:161], v[166:169], v[118:121]
	v_mfma_f32_16x16x32_bf16 v[106:109], v[150:153], v[174:177], v[106:109]
	v_mfma_f32_16x16x32_bf16 v[102:105], v[158:161], v[174:177], v[102:105]
	v_mfma_f32_16x16x32_bf16 v[90:93], v[150:153], v[182:185], v[90:93]
	v_mfma_f32_16x16x32_bf16 v[86:89], v[158:161], v[182:185], v[86:89]
	v_mfma_f32_16x16x32_bf16 v[74:77], v[150:153], v[190:193], v[74:77]
	v_mfma_f32_16x16x32_bf16 v[70:73], v[158:161], v[190:193], v[70:73]
	v_mfma_f32_16x16x32_bf16 v[122:125], v[154:157], v[170:173], v[122:125]
	v_mfma_f32_16x16x32_bf16 v[118:121], v[162:165], v[170:173], v[118:121]
	v_mfma_f32_16x16x32_bf16 v[106:109], v[154:157], v[178:181], v[106:109]
	v_mfma_f32_16x16x32_bf16 v[102:105], v[162:165], v[178:181], v[102:105]
	v_mfma_f32_16x16x32_bf16 v[90:93], v[154:157], v[186:189], v[90:93]
	v_mfma_f32_16x16x32_bf16 v[86:89], v[162:165], v[186:189], v[86:89]
	v_mfma_f32_16x16x32_bf16 v[74:77], v[154:157], v[212:215], v[74:77]
	v_mfma_f32_16x16x32_bf16 v[70:73], v[162:165], v[212:215], v[70:73]
	s_barrier
; #define PG8_STAGE(bufoff, gbase, voff) do { _Pragma("unroll") for (int _i = 0; _i < 2; ++_i) \
;         __builtin_amdgcn_global_load_lds((const unsigned*)((const char*)(gbase) + (voff)[_i]), (LAS unsigned*)(lds + (bufoff) + ldsw + _i * 8192), 16, 0, 0); } while (0)
; #define PG8_LDA(dst, b, h) do { _Pragma("unroll") for (int m = 0; m < 4; ++m) _Pragma("unroll") for (int k = 0; k < 2; ++k) dst[m][k] = *(const LAS bf16x8*)(lds + PG8_SA(b, h) + aoff + m * 2048 + k * 1024); } while (0)
; #define PG8_MMA(ai, bj, At, Bt) do { __builtin_amdgcn_s_setprio(1); _Pragma("unroll") for (int m = 0; m < 4; ++m) _Pragma("unroll") for (int n = 0; n < 2; ++n) _Pragma("unroll") for (int k = 0; k < 2; ++k) \
;         acc[ai][bj][m][n] = __builtin_amdgcn_mfma_f32_16x16x32_bf16(Bt[n][k], At[m][k], acc[ai][bj][m][n], 0, 0, 0); __builtin_amdgcn_s_setprio(0); } while (0)
; #define PG8_WAIT_V(n) asm volatile("s_waitcnt vmcnt(" #n ")" ::: "memory")
; #define PG8_WAIT_L(n) asm volatile("s_waitcnt lgkmcnt(" #n ")" ::: "memory")
; #define PG8_BAR __builtin_amdgcn_s_barrier()
; #define PG8_SCHED __builtin_amdgcn_sched_barrier(0)
;     __device__ __forceinline__ void operator()(f32x4 (&acc)[2][2][4][2], const Unit& u, int wr, int wc, int fr, int fq) const {
;         const int col0 = u.pn * BM + wc * 32 + 8 * fq;
;         bf16_t* rp0 = x + (size_t)(u.pm * BM + wr * 64 + fr) * DM + col0;
;         u32x4 bx[2][4][2];
; #pragma unroll
;         for (int ai = 0; ai < 2; ++ai)
; #pragma unroll
;             for (int m = 0; m < 4; ++m)
; #pragma unroll
;                 for (int bj = 0; bj < 2; ++bj) bx[ai][m][bj] = *(const u32x4*)(rp0 + (size_t)(ai * HALF + m * 16) * DM + bj * HALF);
; template <class Epi, bool SEG>
; __device__ __forceinline__ void gemm_phase(LAS unsigned char* lds, const Gemm g, const int G, const int cidx, const Epi& E) {
;     ...
;             PG8_LDA(At, 1, 1); PG8_STAGE(PG8_SB(1, 0), b3, voffB); PG8_STAGE(PG8_SB(1, 1), b3 + hstepB, voffB); PG8_STAGE(PG8_SA(1, 0), a3, voffA);
;             PG8_WAIT_V(8); PG8_WAIT_L(0); PG8_BAR; PG8_MMA(1, 0, At, B0); PG8_MMA(1, 1, At, B1); PG8_BAR; PG8_SCHED;
;         }
;         if (wr == 0) PG8_BAR;
	s_setprio 0
	s_add_i32 s50, s59, s9
	v_lshl_add_u64 v[216:217], v[216:217], 0, s[28:29]
	s_mov_b32 m0, s50
	ds_read_b128 v[166:169], v244 offset:49152
	ds_read_b128 v[170:173], v244 offset:50176
	ds_read_b128 v[174:177], v244 offset:51200
	ds_read_b128 v[178:181], v244 offset:52224
	ds_read_b128 v[182:185], v244 offset:53248
	ds_read_b128 v[186:189], v244 offset:54272
	ds_read_b128 v[190:193], v244 offset:55296
	ds_read_b128 v[212:215], v244 offset:56320
	global_load_lds_dwordx4 v[216:217], off
	s_add_i32 m0, s50, 0x2000
	s_add_u32 s48, s48, 0x40080
	v_lshl_add_u64 v[216:217], v[218:219], 0, s[28:29]
	s_addc_u32 s49, s49, 0
	s_add_i32 s50, s60, s9
	global_load_lds_dwordx4 v[216:217], off
	v_lshl_add_u64 v[216:217], s[48:49], 0, v[0:1]
	s_mov_b32 m0, s50
	s_nop 0
	global_load_lds_dwordx4 v[216:217], off
	v_lshl_add_u64 v[216:217], s[48:49], 0, v[14:15]
	s_add_i32 m0, s50, 0x2000
	s_nop 0
	global_load_lds_dwordx4 v[216:217], off
	v_lshl_add_u64 v[216:217], v[220:221], 0, s[28:29]
	s_mov_b32 m0, s39
	s_nop 0
	global_load_lds_dwordx4 v[216:217], off
	v_lshl_add_u64 v[216:217], v[222:223], 0, s[28:29]
	s_mov_b32 m0, s52
	s_nop 0
	global_load_lds_dwordx4 v[216:217], off
	s_waitcnt vmcnt(8)
	s_waitcnt lgkmcnt(0)
	s_setprio 1
	s_barrier
	v_mfma_f32_16x16x32_bf16 v[66:69], v[130:133], v[166:169], v[66:69]
	v_mfma_f32_16x16x32_bf16 v[62:65], v[142:145], v[166:169], v[62:65]
	v_mfma_f32_16x16x32_bf16 v[50:53], v[130:133], v[174:177], v[50:53]
	v_mfma_f32_16x16x32_bf16 v[46:49], v[142:145], v[174:177], v[46:49]
	v_mfma_f32_16x16x32_bf16 v[34:37], v[130:133], v[182:185], v[34:37]
	v_mfma_f32_16x16x32_bf16 v[30:33], v[142:145], v[182:185], v[30:33]
	v_mfma_f32_16x16x32_bf16 v[18:21], v[130:133], v[190:193], v[18:21]
	v_mfma_f32_16x16x32_bf16 v[10:13], v[142:145], v[190:193], v[10:13]
	v_mfma_f32_16x16x32_bf16 v[66:69], v[138:141], v[170:173], v[66:69]
	v_mfma_f32_16x16x32_bf16 v[62:65], v[146:149], v[170:173], v[62:65]
	v_mfma_f32_16x16x32_bf16 v[50:53], v[138:141], v[178:181], v[50:53]
	v_mfma_f32_16x16x32_bf16 v[46:49], v[146:149], v[178:181], v[46:49]
	v_mfma_f32_16x16x32_bf16 v[34:37], v[138:141], v[186:189], v[34:37]
	v_mfma_f32_16x16x32_bf16 v[30:33], v[146:149], v[186:189], v[30:33]
	v_mfma_f32_16x16x32_bf16 v[18:21], v[138:141], v[212:215], v[18:21]
	v_mfma_f32_16x16x32_bf16 v[10:13], v[146:149], v[212:215], v[10:13]
	v_mfma_f32_16x16x32_bf16 v[58:61], v[150:153], v[166:169], v[58:61]
	v_mfma_f32_16x16x32_bf16 v[54:57], v[158:161], v[166:169], v[54:57]
	v_mfma_f32_16x16x32_bf16 v[42:45], v[150:153], v[174:177], v[42:45]
	v_mfma_f32_16x16x32_bf16 v[38:41], v[158:161], v[174:177], v[38:41]
	v_mfma_f32_16x16x32_bf16 v[26:29], v[150:153], v[182:185], v[26:29]
	v_mfma_f32_16x16x32_bf16 v[22:25], v[158:161], v[182:185], v[22:25]
	v_mfma_f32_16x16x32_bf16 v[6:9], v[150:153], v[190:193], v[6:9]
	v_mfma_f32_16x16x32_bf16 v[2:5], v[158:161], v[190:193], v[2:5]
	v_mfma_f32_16x16x32_bf16 v[58:61], v[154:157], v[170:173], v[58:61]
	v_mfma_f32_16x16x32_bf16 v[54:57], v[162:165], v[170:173], v[54:57]
	v_mfma_f32_16x16x32_bf16 v[42:45], v[154:157], v[178:181], v[42:45]
	v_mfma_f32_16x16x32_bf16 v[38:41], v[162:165], v[178:181], v[38:41]
	v_mfma_f32_16x16x32_bf16 v[26:29], v[154:157], v[186:189], v[26:29]
	v_mfma_f32_16x16x32_bf16 v[22:25], v[162:165], v[186:189], v[22:25]
	v_mfma_f32_16x16x32_bf16 v[6:9], v[154:157], v[212:215], v[6:9]
	v_mfma_f32_16x16x32_bf16 v[2:5], v[162:165], v[212:215], v[2:5]
	s_barrier
	s_setprio 0
	s_add_i32 s58, s58, 2
	s_add_u32 s40, s40, 0x100
	s_addc_u32 s41, s41, 0
	s_add_u32 s56, s56, 0x100
	s_addc_u32 s57, s57, 0
	s_cmp_gt_u32 s58, 13
	s_cbranch_scc0 .LBB0_706
	s_lshl_b32 s15, s15, 8
	v_add_u32_e32 v132, s15, v17
	v_ashrrev_i32_e32 v133, 31, v132
	v_lshl_or_b32 v130, s14, 8, v229
	v_lshlrev_b64 v[132:133], 11, v[132:133]
	v_lshl_add_u64 v[132:133], s[82:83], 0, v[132:133]
	v_ashrrev_i32_e32 v131, 31, v130
	v_lshl_add_u64 v[226:227], v[130:131], 1, v[132:133]
	global_load_dwordx4 v[248:251], v[226:227], off
	global_load_dwordx4 v[190:193], v[226:227], off offset:256
	v_add_co_u32_e32 v224, vcc, 0x8000, v226
	s_mov_b32 s17, 0x18000
	s_nop 0
	v_addc_co_u32_e32 v225, vcc, 0, v227, vcc
	global_load_dwordx4 v[186:189], v[224:225], off
	global_load_dwordx4 v[182:185], v[224:225], off offset:256
	s_nop 4
	s_and_b64 vcc, exec, s[12:13]
	s_cbranch_vccz .LBB0_709
	s_barrier

; #define PG8_STAGE(bufoff, gbase, voff) do { _Pragma("unroll") for (int _i = 0; _i < 2; ++_i) \
;         __builtin_amdgcn_global_load_lds((const unsigned*)((const char*)(gbase) + (voff)[_i]), (LAS unsigned*)(lds + (bufoff) + ldsw + _i * 8192), 16, 0, 0); } while (0)
; #define PG8_LDA(dst, b, h) do { _Pragma("unroll") for (int m = 0; m < 4; ++m) _Pragma("unroll") for (int k = 0; k < 2; ++k) dst[m][k] = *(const LAS bf16x8*)(lds + PG8_SA(b, h) + aoff + m * 2048 + k * 1024); } while (0)
; #define PG8_LDB(dst, b, h) do { _Pragma("unroll") for (int n = 0; n < 2; ++n) _Pragma("unroll") for (int k = 0; k < 2; ++k) dst[n][k] = *(const LAS bf16x8*)(lds + PG8_SB(b, h) + boff + n * 2048 + k * 1024); } while (0)
; #define PG8_MMA(ai, bj, At, Bt) do { __builtin_amdgcn_s_setprio(1); _Pragma("unroll") for (int m = 0; m < 4; ++m) _Pragma("unroll") for (int n = 0; n < 2; ++n) _Pragma("unroll") for (int k = 0; k < 2; ++k) \
;         acc[ai][bj][m][n] = __builtin_amdgcn_mfma_f32_16x16x32_bf16(Bt[n][k], At[m][k], acc[ai][bj][m][n], 0, 0, 0); __builtin_amdgcn_s_setprio(0); } while (0)
; #define PG8_BAR __builtin_amdgcn_s_barrier()
; template <class Epi, bool SEG>
; __device__ __forceinline__ void gemm_phase(LAS unsigned char* lds, const Gemm g, const int G, const int cidx, const Epi& E) {
;     ...
;         const bool has_next = S.next(ui + 1, nxt);
;         const char* nA = has_next ? (const char*)g.A + (long)nxt.pm * (long)tstepA + aoff0 : cA; const char* nB = has_next ? (const char*)g.Bt + (size_t)nxt.pn * tstepB : cB;
;         for (int t = 0; t < nt; t += 2) {
;             const bool last = (t == nt - 2);
;             const char* a1 = cA + (size_t)(t + 1) * kstep;
;             const char* a2 = last ? nA : cA + (size_t)(t + 2) * kstep; const char* b2 = last ? nB : cB + (size_t)(t + 2) * kstep;
;             const char* a3 = a2 + kstep; const char* b3 = b2 + kstep;
;             PG8_LDB(B0, 0, 0); PG8_LDB(B1, 0, 1); PG8_SCHED; PG8_LDA(At, 0, 0); PG8_STAGE(PG8_SA(1, 1), a1 + hstepA, voffA);
;             PG8_WAIT_V(8); PG8_WAIT_L(0); PG8_BAR; PG8_MMA(0, 0, At, B0); PG8_MMA(0, 1, At, B1); PG8_BAR; PG8_SCHED;
;             PG8_LDA(At, 0, 1); PG8_STAGE(PG8_SB(0, 0), b2, voffB); PG8_STAGE(PG8_SB(0, 1), b2 + hstepB, voffB); PG8_STAGE(PG8_SA(0, 0), a2, voffA);
;             PG8_WAIT_V(8); PG8_WAIT_L(0); PG8_BAR; PG8_MMA(1, 0, At, B0); PG8_MMA(1, 1, At, B1); PG8_BAR; PG8_SCHED;
.LBB0_785:
	s_ashr_i32 s15, s14, 31
	s_lshl_b64 s[18:19], s[14:15], 19
	v_readlane_b32 s15, v255, 15
	s_add_u32 s18, s15, s18
	v_readlane_b32 s15, v255, 16
	s_addc_u32 s19, s15, s19
	s_and_b64 s[6:7], s[6:7], exec
	s_cselect_b32 s15, s19, s23
	s_cselect_b32 s21, s18, s22
	s_add_u32 s6, s40, 0x3e080
	s_addc_u32 s7, s41, 0
	s_add_u32 s52, s22, 0x100
	s_addc_u32 s53, s23, 0
	s_mov_b32 s54, -2
	s_waitcnt vmcnt(0)
	s_add_u32 s22, s6, 0xfffc2080
	s_addc_u32 s23, s7, -1
	s_add_i32 s55, 0, 0x10000
	s_cmp_eq_u32 s54, 12
	s_cselect_b32 s41, s17, s23
	s_cselect_b32 s40, s16, s22
	s_cselect_b32 s23, s15, s53
	s_cselect_b32 s22, s21, s52
	s_add_i32 s58, 0, 0x14000
	v_add_u32_e32 v114, s55, v243
	v_add_u32_e32 v130, s58, v243
	ds_read_b128 v[102:105], v114
	ds_read_b128 v[106:109], v114 offset:1024
	ds_read_b128 v[110:113], v114 offset:2048
	ds_read_b128 v[114:117], v114 offset:3072
	ds_read_b128 v[118:121], v130
	ds_read_b128 v[122:125], v130 offset:1024
	ds_read_b128 v[126:129], v130 offset:2048
	ds_read_b128 v[130:133], v130 offset:3072
	v_lshl_add_u64 v[208:209], s[6:7], 0, v[198:199]
	s_add_i32 m0, s11, 0xc000
	ds_read_b128 v[166:169], v247
	ds_read_b128 v[170:173], v247 offset:1024
	ds_read_b128 v[174:177], v247 offset:2048
	ds_read_b128 v[178:181], v247 offset:3072
	ds_read_b128 v[182:185], v247 offset:4096
	ds_read_b128 v[186:189], v247 offset:5120
	ds_read_b128 v[212:215], v247 offset:6144
	ds_read_b128 v[216:219], v247 offset:7168
	global_load_lds_dwordx4 v[208:209], off
	v_lshl_add_u64 v[208:209], s[6:7], 0, v[200:201]
	s_add_i32 m0, s11, 0xe000
	s_nop 0
	global_load_lds_dwordx4 v[208:209], off
	s_waitcnt vmcnt(8)
	s_waitcnt lgkmcnt(0)
	s_setprio 1
	s_barrier
	v_mfma_f32_16x16x32_bf16 v[162:165], v[102:105], v[166:169], 0
	v_mfma_f32_16x16x32_bf16 v[66:69], v[110:113], v[166:169], 0
	v_mfma_f32_16x16x32_bf16 v[158:161], v[102:105], v[174:177], 0
	v_mfma_f32_16x16x32_bf16 v[62:65], v[110:113], v[174:177], 0
	v_mfma_f32_16x16x32_bf16 v[146:149], v[102:105], v[182:185], 0
	v_mfma_f32_16x16x32_bf16 v[50:53], v[110:113], v[182:185], 0
	v_mfma_f32_16x16x32_bf16 v[138:141], v[102:105], v[212:215], 0
	v_mfma_f32_16x16x32_bf16 v[42:45], v[110:113], v[212:215], 0
	v_mfma_f32_16x16x32_bf16 v[162:165], v[106:109], v[170:173], v[162:165]
	v_mfma_f32_16x16x32_bf16 v[66:69], v[114:117], v[170:173], v[66:69]
	v_mfma_f32_16x16x32_bf16 v[158:161], v[106:109], v[178:181], v[158:161]
	v_mfma_f32_16x16x32_bf16 v[62:65], v[114:117], v[178:181], v[62:65]
	v_mfma_f32_16x16x32_bf16 v[146:149], v[106:109], v[186:189], v[146:149]
	v_mfma_f32_16x16x32_bf16 v[50:53], v[114:117], v[186:189], v[50:53]
	v_mfma_f32_16x16x32_bf16 v[138:141], v[106:109], v[216:219], v[138:141]
	v_mfma_f32_16x16x32_bf16 v[42:45], v[114:117], v[216:219], v[42:45]
	v_mfma_f32_16x16x32_bf16 v[154:157], v[118:121], v[166:169], 0
	v_mfma_f32_16x16x32_bf16 v[58:61], v[126:129], v[166:169], 0
	v_mfma_f32_16x16x32_bf16 v[150:153], v[118:121], v[174:177], 0
	v_mfma_f32_16x16x32_bf16 v[54:57], v[126:129], v[174:177], 0
	v_mfma_f32_16x16x32_bf16 v[142:145], v[118:121], v[182:185], 0
	v_mfma_f32_16x16x32_bf16 v[46:49], v[126:129], v[182:185], 0
	v_mfma_f32_16x16x32_bf16 v[134:137], v[118:121], v[212:215], 0
	v_mfma_f32_16x16x32_bf16 v[38:41], v[126:129], v[212:215], 0
	v_mfma_f32_16x16x32_bf16 v[154:157], v[122:125], v[170:173], v[154:157]
	v_mfma_f32_16x16x32_bf16 v[58:61], v[130:133], v[170:173], v[58:61]
	v_mfma_f32_16x16x32_bf16 v[150:153], v[122:125], v[178:181], v[150:153]
	v_mfma_f32_16x16x32_bf16 v[54:57], v[130:133], v[178:181], v[54:57]
	v_mfma_f32_16x16x32_bf16 v[142:145], v[122:125], v[186:189], v[142:145]
	v_mfma_f32_16x16x32_bf16 v[46:49], v[130:133], v[186:189], v[46:49]
	v_mfma_f32_16x16x32_bf16 v[134:137], v[122:125], v[216:219], v[134:137]
	v_mfma_f32_16x16x32_bf16 v[38:41], v[130:133], v[216:219], v[38:41]
	s_barrier
	s_setprio 0
	s_add_i32 s55, s55, s10
	v_lshl_add_u64 v[208:209], s[22:23], 0, v[0:1]
	s_mov_b32 m0, s55
	ds_read_b128 v[166:169], v247 offset:16384
	ds_read_b128 v[170:173], v247 offset:17408
	ds_read_b128 v[174:177], v247 offset:18432
	ds_read_b128 v[178:181], v247 offset:19456
	ds_read_b128 v[182:185], v247 offset:20480
	ds_read_b128 v[186:189], v247 offset:21504
	ds_read_b128 v[212:215], v247 offset:22528
	ds_read_b128 v[216:219], v247 offset:23552
	global_load_lds_dwordx4 v[208:209], off
	s_add_i32 m0, s55, 0x2000
	s_add_u32 s56, s22, 0x40000
	v_lshl_add_u64 v[220:221], s[22:23], 0, v[192:193]
	s_addc_u32 s57, s23, 0
	s_add_i32 s55, s58, s10
	global_load_lds_dwordx4 v[220:221], off
	v_lshl_add_u64 v[222:223], s[56:57], 0, v[0:1]
	s_mov_b32 m0, s55
	v_lshl_add_u64 v[224:225], s[40:41], 0, v[190:191]
	global_load_lds_dwordx4 v[222:223], off
	v_lshl_add_u64 v[222:223], s[56:57], 0, v[192:193]
	s_add_i32 m0, s55, 0x2000
	s_nop 0
	global_load_lds_dwordx4 v[222:223], off
	v_lshl_add_u64 v[222:223], s[40:41], 0, v[14:15]
	s_mov_b32 m0, s11
	s_nop 0
	global_load_lds_dwordx4 v[222:223], off
	s_mov_b32 m0, s9
	s_nop 0
	global_load_lds_dwordx4 v[224:225], off
	s_waitcnt vmcnt(8)
	s_waitcnt lgkmcnt(0)
	s_setprio 1
	s_barrier
; #define PG8_STAGE(bufoff, gbase, voff) do { _Pragma("unroll") for (int _i = 0; _i < 2; ++_i) \
;         __builtin_amdgcn_global_load_lds((const unsigned*)((const char*)(gbase) + (voff)[_i]), (LAS unsigned*)(lds + (bufoff) + ldsw + _i * 8192), 16, 0, 0); } while (0)
; #define PG8_LDA(dst, b, h) do { _Pragma("unroll") for (int m = 0; m < 4; ++m) _Pragma("unroll") for (int k = 0; k < 2; ++k) dst[m][k] = *(const LAS bf16x8*)(lds + PG8_SA(b, h) + aoff + m * 2048 + k * 1024); } while (0)
; #define PG8_LDB(dst, b, h) do { _Pragma("unroll") for (int n = 0; n < 2; ++n) _Pragma("unroll") for (int k = 0; k < 2; ++k) dst[n][k] = *(const LAS bf16x8*)(lds + PG8_SB(b, h) + boff + n * 2048 + k * 1024); } while (0)
; #define PG8_MMA(ai, bj, At, Bt) do { __builtin_amdgcn_s_setprio(1); _Pragma("unroll") for (int m = 0; m < 4; ++m) _Pragma("unroll") for (int n = 0; n < 2; ++n) _Pragma("unroll") for (int k = 0; k < 2; ++k) \
;         acc[ai][bj][m][n] = __builtin_amdgcn_mfma_f32_16x16x32_bf16(Bt[n][k], At[m][k], acc[ai][bj][m][n], 0, 0, 0); __builtin_amdgcn_s_setprio(0); } while (0)
; #define PG8_WAIT_V(n) asm volatile("s_waitcnt vmcnt(" #n ")" ::: "memory")
; #define PG8_WAIT_L(n) asm volatile("s_waitcnt lgkmcnt(" #n ")" ::: "memory")
; #define PG8_BAR __builtin_amdgcn_s_barrier()
; #define PG8_SCHED __builtin_amdgcn_sched_barrier(0)
; template <class Epi, bool SEG>
; __device__ __forceinline__ void gemm_phase(LAS unsigned char* lds, const Gemm g, const int G, const int cidx, const Epi& E) {
;     ...
;             PG8_WAIT_V(8); PG8_WAIT_L(0); PG8_BAR; PG8_MMA(0, 0, At, B0); PG8_MMA(0, 1, At, B1); PG8_BAR; PG8_SCHED;
;             PG8_LDA(At, 0, 1); PG8_STAGE(PG8_SB(0, 0), b2, voffB); PG8_STAGE(PG8_SB(0, 1), b2 + hstepB, voffB); PG8_STAGE(PG8_SA(0, 0), a2, voffA);
;             PG8_WAIT_V(8); PG8_WAIT_L(0); PG8_BAR; PG8_MMA(1, 0, At, B0); PG8_MMA(1, 1, At, B1); PG8_BAR; PG8_SCHED;
;             PG8_LDB(B0, 1, 0); PG8_LDB(B1, 1, 1); PG8_SCHED; PG8_LDA(At, 1, 0); PG8_STAGE(PG8_SA(0, 1), a2 + hstepA, voffA);
;             PG8_WAIT_V(8); PG8_WAIT_L(0); PG8_BAR; PG8_MMA(0, 0, At, B0); PG8_MMA(0, 1, At, B1); PG8_BAR; PG8_SCHED;
	v_mfma_f32_16x16x32_bf16 v[98:101], v[102:105], v[166:169], 0
	v_mfma_f32_16x16x32_bf16 v[34:37], v[110:113], v[166:169], 0
	v_mfma_f32_16x16x32_bf16 v[94:97], v[102:105], v[174:177], 0
	v_mfma_f32_16x16x32_bf16 v[30:33], v[110:113], v[174:177], 0
	v_mfma_f32_16x16x32_bf16 v[82:85], v[102:105], v[182:185], 0
	v_mfma_f32_16x16x32_bf16 v[18:21], v[110:113], v[182:185], 0
	v_mfma_f32_16x16x32_bf16 v[74:77], v[102:105], v[212:215], 0
	v_mfma_f32_16x16x32_bf16 v[6:9], v[110:113], v[212:215], 0
	v_mfma_f32_16x16x32_bf16 v[98:101], v[106:109], v[170:173], v[98:101]
	v_mfma_f32_16x16x32_bf16 v[34:37], v[114:117], v[170:173], v[34:37]
	v_mfma_f32_16x16x32_bf16 v[94:97], v[106:109], v[178:181], v[94:97]
	v_mfma_f32_16x16x32_bf16 v[30:33], v[114:117], v[178:181], v[30:33]
	v_mfma_f32_16x16x32_bf16 v[82:85], v[106:109], v[186:189], v[82:85]
	v_mfma_f32_16x16x32_bf16 v[18:21], v[114:117], v[186:189], v[18:21]
	v_mfma_f32_16x16x32_bf16 v[74:77], v[106:109], v[216:219], v[74:77]
	v_mfma_f32_16x16x32_bf16 v[6:9], v[114:117], v[216:219], v[6:9]
	v_mfma_f32_16x16x32_bf16 v[90:93], v[118:121], v[166:169], 0
	v_mfma_f32_16x16x32_bf16 v[26:29], v[126:129], v[166:169], 0
	v_mfma_f32_16x16x32_bf16 v[86:89], v[118:121], v[174:177], 0
	v_mfma_f32_16x16x32_bf16 v[22:25], v[126:129], v[174:177], 0
	v_mfma_f32_16x16x32_bf16 v[78:81], v[118:121], v[182:185], 0
	v_mfma_f32_16x16x32_bf16 v[10:13], v[126:129], v[182:185], 0
	v_mfma_f32_16x16x32_bf16 v[70:73], v[118:121], v[212:215], 0
	v_mfma_f32_16x16x32_bf16 v[2:5], v[126:129], v[212:215], 0
	v_mfma_f32_16x16x32_bf16 v[90:93], v[122:125], v[170:173], v[90:93]
	v_mfma_f32_16x16x32_bf16 v[26:29], v[130:133], v[170:173], v[26:29]
	v_mfma_f32_16x16x32_bf16 v[86:89], v[122:125], v[178:181], v[86:89]
	v_mfma_f32_16x16x32_bf16 v[22:25], v[130:133], v[178:181], v[22:25]
	v_mfma_f32_16x16x32_bf16 v[78:81], v[122:125], v[186:189], v[78:81]
	v_mfma_f32_16x16x32_bf16 v[10:13], v[130:133], v[186:189], v[10:13]
	v_mfma_f32_16x16x32_bf16 v[70:73], v[122:125], v[216:219], v[70:73]
	v_mfma_f32_16x16x32_bf16 v[2:5], v[130:133], v[216:219], v[2:5]
	s_barrier
	s_setprio 0
	s_add_i32 s55, 0, 0x18000
	s_add_i32 s56, 0, 0x1c000
	v_add_u32_e32 v114, s55, v243
	v_add_u32_e32 v130, s56, v243
	ds_read_b128 v[102:105], v114
	ds_read_b128 v[106:109], v114 offset:1024
	ds_read_b128 v[110:113], v114 offset:2048
	ds_read_b128 v[114:117], v114 offset:3072
	ds_read_b128 v[118:121], v130
	ds_read_b128 v[122:125], v130 offset:1024
	ds_read_b128 v[126:129], v130 offset:2048
	ds_read_b128 v[130:133], v130 offset:3072
	s_add_u32 s40, s40, 0x3e000
	s_addc_u32 s41, s41, 0
	s_mov_b32 m0, s36
	v_lshl_add_u64 v[226:227], s[40:41], 0, v[14:15]
	ds_read_b128 v[166:169], v247 offset:32768
	ds_read_b128 v[170:173], v247 offset:33792
	ds_read_b128 v[174:177], v247 offset:34816
	ds_read_b128 v[178:181], v247 offset:35840
	ds_read_b128 v[182:185], v247 offset:36864
	ds_read_b128 v[186:189], v247 offset:37888
	ds_read_b128 v[212:215], v247 offset:38912
	ds_read_b128 v[216:219], v247 offset:39936
	global_load_lds_dwordx4 v[226:227], off
	v_lshl_add_u64 v[226:227], s[40:41], 0, v[190:191]
	s_mov_b32 m0, s12
	s_nop 0
	global_load_lds_dwordx4 v[226:227], off
	s_waitcnt vmcnt(8)
	s_waitcnt lgkmcnt(0)
	s_setprio 1
	s_barrier
	v_mfma_f32_16x16x32_bf16 v[162:165], v[102:105], v[166:169], v[162:165]
	v_mfma_f32_16x16x32_bf16 v[66:69], v[110:113], v[166:169], v[66:69]
	v_mfma_f32_16x16x32_bf16 v[158:161], v[102:105], v[174:177], v[158:161]
	v_mfma_f32_16x16x32_bf16 v[62:65], v[110:113], v[174:177], v[62:65]
	v_mfma_f32_16x16x32_bf16 v[146:149], v[102:105], v[182:185], v[146:149]
	v_mfma_f32_16x16x32_bf16 v[50:53], v[110:113], v[182:185], v[50:53]
	v_mfma_f32_16x16x32_bf16 v[138:141], v[102:105], v[212:215], v[138:141]
	v_mfma_f32_16x16x32_bf16 v[42:45], v[110:113], v[212:215], v[42:45]
	v_mfma_f32_16x16x32_bf16 v[162:165], v[106:109], v[170:173], v[162:165]
	v_mfma_f32_16x16x32_bf16 v[66:69], v[114:117], v[170:173], v[66:69]
	v_mfma_f32_16x16x32_bf16 v[158:161], v[106:109], v[178:181], v[158:161]
	v_mfma_f32_16x16x32_bf16 v[62:65], v[114:117], v[178:181], v[62:65]
	v_mfma_f32_16x16x32_bf16 v[146:149], v[106:109], v[186:189], v[146:149]
	v_mfma_f32_16x16x32_bf16 v[50:53], v[114:117], v[186:189], v[50:53]
	v_mfma_f32_16x16x32_bf16 v[138:141], v[106:109], v[216:219], v[138:141]
	v_mfma_f32_16x16x32_bf16 v[42:45], v[114:117], v[216:219], v[42:45]
	v_mfma_f32_16x16x32_bf16 v[154:157], v[118:121], v[166:169], v[154:157]
	v_mfma_f32_16x16x32_bf16 v[58:61], v[126:129], v[166:169], v[58:61]
	v_mfma_f32_16x16x32_bf16 v[150:153], v[118:121], v[174:177], v[150:153]
	v_mfma_f32_16x16x32_bf16 v[54:57], v[126:129], v[174:177], v[54:57]
	v_mfma_f32_16x16x32_bf16 v[142:145], v[118:121], v[182:185], v[142:145]
	v_mfma_f32_16x16x32_bf16 v[46:49], v[126:129], v[182:185], v[46:49]
	v_mfma_f32_16x16x32_bf16 v[134:137], v[118:121], v[212:215], v[134:137]
	v_mfma_f32_16x16x32_bf16 v[38:41], v[126:129], v[212:215], v[38:41]
	v_mfma_f32_16x16x32_bf16 v[154:157], v[122:125], v[170:173], v[154:157]
	v_mfma_f32_16x16x32_bf16 v[58:61], v[130:133], v[170:173], v[58:61]
	v_mfma_f32_16x16x32_bf16 v[150:153], v[122:125], v[178:181], v[150:153]
	v_mfma_f32_16x16x32_bf16 v[54:57], v[130:133], v[178:181], v[54:57]
	v_mfma_f32_16x16x32_bf16 v[142:145], v[122:125], v[186:189], v[142:145]
	v_mfma_f32_16x16x32_bf16 v[46:49], v[130:133], v[186:189], v[46:49]
	v_mfma_f32_16x16x32_bf16 v[134:137], v[122:125], v[216:219], v[134:137]
	v_mfma_f32_16x16x32_bf16 v[38:41], v[130:133], v[216:219], v[38:41]
	s_barrier
; #define PG8_STAGE(bufoff, gbase, voff) do { _Pragma("unroll") for (int _i = 0; _i < 2; ++_i) \
;         __builtin_amdgcn_global_load_lds((const unsigned*)((const char*)(gbase) + (voff)[_i]), (LAS unsigned*)(lds + (bufoff) + ldsw + _i * 8192), 16, 0, 0); } while (0)
; #define PG8_LDA(dst, b, h) do { _Pragma("unroll") for (int m = 0; m < 4; ++m) _Pragma("unroll") for (int k = 0; k < 2; ++k) dst[m][k] = *(const LAS bf16x8*)(lds + PG8_SA(b, h) + aoff + m * 2048 + k * 1024); } while (0)
; #define PG8_LDB(dst, b, h) do { _Pragma("unroll") for (int n = 0; n < 2; ++n) _Pragma("unroll") for (int k = 0; k < 2; ++k) dst[n][k] = *(const LAS bf16x8*)(lds + PG8_SB(b, h) + boff + n * 2048 + k * 1024); } while (0)
; #define PG8_MMA(ai, bj, At, Bt) do { __builtin_amdgcn_s_setprio(1); _Pragma("unroll") for (int m = 0; m < 4; ++m) _Pragma("unroll") for (int n = 0; n < 2; ++n) _Pragma("unroll") for (int k = 0; k < 2; ++k) \
;         acc[ai][bj][m][n] = __builtin_amdgcn_mfma_f32_16x16x32_bf16(Bt[n][k], At[m][k], acc[ai][bj][m][n], 0, 0, 0); __builtin_amdgcn_s_setprio(0); } while (0)
; #define PG8_WAIT_V(n) asm volatile("s_waitcnt vmcnt(" #n ")" ::: "memory")
; #define PG8_WAIT_L(n) asm volatile("s_waitcnt lgkmcnt(" #n ")" ::: "memory")
; template <class Epi, bool SEG>
; __device__ __forceinline__ void gemm_phase(LAS unsigned char* lds, const Gemm g, const int G, const int cidx, const Epi& E) {
;     ...
;         for (int t = 0; t < nt; t += 2) {
;             const bool last = (t == nt - 2);
;             const char* a1 = cA + (size_t)(t + 1) * kstep;
;             const char* a2 = last ? nA : cA + (size_t)(t + 2) * kstep; const char* b2 = last ? nB : cB + (size_t)(t + 2) * kstep;
;             const char* a3 = a2 + kstep; const char* b3 = b2 + kstep;
;             PG8_LDB(B0, 0, 0); PG8_LDB(B1, 0, 1); PG8_SCHED; PG8_LDA(At, 0, 0); PG8_STAGE(PG8_SA(1, 1), a1 + hstepA, voffA);
;             PG8_WAIT_V(8); PG8_WAIT_L(0); PG8_BAR; PG8_MMA(0, 0, At, B0); PG8_MMA(0, 1, At, B1); PG8_BAR; PG8_SCHED;
;     ...
;             PG8_WAIT_V(8); PG8_WAIT_L(0); PG8_BAR; PG8_MMA(0, 0, At, B0); PG8_MMA(0, 1, At, B1); PG8_BAR; PG8_SCHED;
;             PG8_LDA(At, 1, 1); PG8_STAGE(PG8_SB(1, 0), b3, voffB); PG8_STAGE(PG8_SB(1, 1), b3 + hstepB, voffB); PG8_STAGE(PG8_SA(1, 0), a3, voffA);
;             PG8_WAIT_V(8); PG8_WAIT_L(0); PG8_BAR; PG8_MMA(1, 0, At, B0); PG8_MMA(1, 1, At, B1); PG8_BAR; PG8_SCHED;
	s_setprio 0
	s_add_i32 s40, s55, s10
	v_lshl_add_u64 v[208:209], v[208:209], 0, s[28:29]
	s_mov_b32 m0, s40
	ds_read_b128 v[166:169], v247 offset:49152
	ds_read_b128 v[170:173], v247 offset:50176
	ds_read_b128 v[174:177], v247 offset:51200
	ds_read_b128 v[178:181], v247 offset:52224
	ds_read_b128 v[182:185], v247 offset:53248
	ds_read_b128 v[186:189], v247 offset:54272
	ds_read_b128 v[212:215], v247 offset:55296
	ds_read_b128 v[216:219], v247 offset:56320
	global_load_lds_dwordx4 v[208:209], off
	s_add_i32 m0, s40, 0x2000
	s_add_u32 s22, s22, 0x40080
	v_lshl_add_u64 v[208:209], v[220:221], 0, s[28:29]
	s_addc_u32 s23, s23, 0
	s_add_i32 s40, s56, s10
	global_load_lds_dwordx4 v[208:209], off
	v_lshl_add_u64 v[208:209], s[22:23], 0, v[0:1]
	s_mov_b32 m0, s40
	s_nop 0
	global_load_lds_dwordx4 v[208:209], off
	v_lshl_add_u64 v[208:209], s[22:23], 0, v[192:193]
	s_add_i32 m0, s40, 0x2000
	s_nop 0
	global_load_lds_dwordx4 v[208:209], off
	v_lshl_add_u64 v[208:209], v[222:223], 0, s[28:29]
	s_mov_b32 m0, s13
	s_nop 0
	global_load_lds_dwordx4 v[208:209], off
	v_lshl_add_u64 v[208:209], v[224:225], 0, s[28:29]
	s_mov_b32 m0, s8
	s_nop 0
	global_load_lds_dwordx4 v[208:209], off
	s_waitcnt vmcnt(8)
	s_waitcnt lgkmcnt(0)
	s_setprio 1
	s_barrier
	v_mfma_f32_16x16x32_bf16 v[98:101], v[102:105], v[166:169], v[98:101]
	v_mfma_f32_16x16x32_bf16 v[34:37], v[110:113], v[166:169], v[34:37]
	v_mfma_f32_16x16x32_bf16 v[94:97], v[102:105], v[174:177], v[94:97]
	v_mfma_f32_16x16x32_bf16 v[30:33], v[110:113], v[174:177], v[30:33]
	v_mfma_f32_16x16x32_bf16 v[82:85], v[102:105], v[182:185], v[82:85]
	v_mfma_f32_16x16x32_bf16 v[18:21], v[110:113], v[182:185], v[18:21]
	v_mfma_f32_16x16x32_bf16 v[74:77], v[102:105], v[212:215], v[74:77]
	v_mfma_f32_16x16x32_bf16 v[6:9], v[110:113], v[212:215], v[6:9]
	v_mfma_f32_16x16x32_bf16 v[98:101], v[106:109], v[170:173], v[98:101]
	v_mfma_f32_16x16x32_bf16 v[34:37], v[114:117], v[170:173], v[34:37]
	v_mfma_f32_16x16x32_bf16 v[94:97], v[106:109], v[178:181], v[94:97]
	v_mfma_f32_16x16x32_bf16 v[30:33], v[114:117], v[178:181], v[30:33]
	v_mfma_f32_16x16x32_bf16 v[82:85], v[106:109], v[186:189], v[82:85]
	v_mfma_f32_16x16x32_bf16 v[18:21], v[114:117], v[186:189], v[18:21]
	v_mfma_f32_16x16x32_bf16 v[74:77], v[106:109], v[216:219], v[74:77]
	v_mfma_f32_16x16x32_bf16 v[6:9], v[114:117], v[216:219], v[6:9]
	v_mfma_f32_16x16x32_bf16 v[90:93], v[118:121], v[166:169], v[90:93]
	v_mfma_f32_16x16x32_bf16 v[26:29], v[126:129], v[166:169], v[26:29]
	v_mfma_f32_16x16x32_bf16 v[86:89], v[118:121], v[174:177], v[86:89]
	v_mfma_f32_16x16x32_bf16 v[22:25], v[126:129], v[174:177], v[22:25]
	v_mfma_f32_16x16x32_bf16 v[78:81], v[118:121], v[182:185], v[78:81]
	v_mfma_f32_16x16x32_bf16 v[10:13], v[126:129], v[182:185], v[10:13]
	v_mfma_f32_16x16x32_bf16 v[70:73], v[118:121], v[212:215], v[70:73]
	v_mfma_f32_16x16x32_bf16 v[2:5], v[126:129], v[212:215], v[2:5]
	v_mfma_f32_16x16x32_bf16 v[90:93], v[122:125], v[170:173], v[90:93]
	v_mfma_f32_16x16x32_bf16 v[26:29], v[130:133], v[170:173], v[26:29]
	v_mfma_f32_16x16x32_bf16 v[86:89], v[122:125], v[178:181], v[86:89]
	v_mfma_f32_16x16x32_bf16 v[22:25], v[130:133], v[178:181], v[22:25]
	v_mfma_f32_16x16x32_bf16 v[78:81], v[122:125], v[186:189], v[78:81]
	v_mfma_f32_16x16x32_bf16 v[10:13], v[130:133], v[186:189], v[10:13]
	v_mfma_f32_16x16x32_bf16 v[70:73], v[122:125], v[216:219], v[70:73]
	v_mfma_f32_16x16x32_bf16 v[2:5], v[130:133], v[216:219], v[2:5]
	s_barrier
	s_setprio 0
	s_add_i32 s54, s54, 2
	s_add_u32 s6, s6, 0x100
	s_addc_u32 s7, s7, 0
	s_add_u32 s52, s52, 0x100
	s_addc_u32 s53, s53, 0
.LBB0_786:
	s_add_u32 s22, s6, 0xfffc2080
	s_addc_u32 s23, s7, -1
	s_add_i32 s55, 0, 0x10000
	s_cmp_eq_u32 s54, 12
	s_cselect_b32 s41, s17, s23
	s_cselect_b32 s40, s16, s22
	s_cselect_b32 s23, s15, s53
	s_cselect_b32 s22, s21, s52
	s_add_i32 s58, 0, 0x14000
	v_add_u32_e32 v114, s55, v243
	v_add_u32_e32 v130, s58, v243
	ds_read_b128 v[102:105], v114
	ds_read_b128 v[106:109], v114 offset:1024
	ds_read_b128 v[110:113], v114 offset:2048
	ds_read_b128 v[114:117], v114 offset:3072
	ds_read_b128 v[118:121], v130
	ds_read_b128 v[122:125], v130 offset:1024
	ds_read_b128 v[126:129], v130 offset:2048
	ds_read_b128 v[130:133], v130 offset:3072
	v_lshl_add_u64 v[208:209], s[6:7], 0, v[198:199]
	s_add_i32 m0, s11, 0xc000
	ds_read_b128 v[166:169], v247
	ds_read_b128 v[170:173], v247 offset:1024
	ds_read_b128 v[174:177], v247 offset:2048
	ds_read_b128 v[178:181], v247 offset:3072
	ds_read_b128 v[182:185], v247 offset:4096
	ds_read_b128 v[186:189], v247 offset:5120
	ds_read_b128 v[212:215], v247 offset:6144
	ds_read_b128 v[216:219], v247 offset:7168
	global_load_lds_dwordx4 v[208:209], off
	v_lshl_add_u64 v[208:209], s[6:7], 0, v[200:201]
	s_add_i32 m0, s11, 0xe000
	s_nop 0
	global_load_lds_dwordx4 v[208:209], off
	s_waitcnt vmcnt(8)
	s_waitcnt lgkmcnt(0)
	s_setprio 1
	s_barrier
; #define PG8_STAGE(bufoff, gbase, voff) do { _Pragma("unroll") for (int _i = 0; _i < 2; ++_i) \
;         __builtin_amdgcn_global_load_lds((const unsigned*)((const char*)(gbase) + (voff)[_i]), (LAS unsigned*)(lds + (bufoff) + ldsw + _i * 8192), 16, 0, 0); } while (0)
; #define PG8_LDA(dst, b, h) do { _Pragma("unroll") for (int m = 0; m < 4; ++m) _Pragma("unroll") for (int k = 0; k < 2; ++k) dst[m][k] = *(const LAS bf16x8*)(lds + PG8_SA(b, h) + aoff + m * 2048 + k * 1024); } while (0)
; #define PG8_LDB(dst, b, h) do { _Pragma("unroll") for (int n = 0; n < 2; ++n) _Pragma("unroll") for (int k = 0; k < 2; ++k) dst[n][k] = *(const LAS bf16x8*)(lds + PG8_SB(b, h) + boff + n * 2048 + k * 1024); } while (0)
; #define PG8_MMA(ai, bj, At, Bt) do { __builtin_amdgcn_s_setprio(1); _Pragma("unroll") for (int m = 0; m < 4; ++m) _Pragma("unroll") for (int n = 0; n < 2; ++n) _Pragma("unroll") for (int k = 0; k < 2; ++k) \
;         acc[ai][bj][m][n] = __builtin_amdgcn_mfma_f32_16x16x32_bf16(Bt[n][k], At[m][k], acc[ai][bj][m][n], 0, 0, 0); __builtin_amdgcn_s_setprio(0); } while (0)
; #define PG8_WAIT_V(n) asm volatile("s_waitcnt vmcnt(" #n ")" ::: "memory")
; #define PG8_WAIT_L(n) asm volatile("s_waitcnt lgkmcnt(" #n ")" ::: "memory")
; #define PG8_BAR __builtin_amdgcn_s_barrier()
; #define PG8_SCHED __builtin_amdgcn_sched_barrier(0)
; template <class Epi, bool SEG>
; __device__ __forceinline__ void gemm_phase(LAS unsigned char* lds, const Gemm g, const int G, const int cidx, const Epi& E) {
;     ...
;             PG8_WAIT_V(8); PG8_WAIT_L(0); PG8_BAR; PG8_MMA(0, 0, At, B0); PG8_MMA(0, 1, At, B1); PG8_BAR; PG8_SCHED;
;             PG8_LDA(At, 0, 1); PG8_STAGE(PG8_SB(0, 0), b2, voffB); PG8_STAGE(PG8_SB(0, 1), b2 + hstepB, voffB); PG8_STAGE(PG8_SA(0, 0), a2, voffA);
;             PG8_WAIT_V(8); PG8_WAIT_L(0); PG8_BAR; PG8_MMA(1, 0, At, B0); PG8_MMA(1, 1, At, B1); PG8_BAR; PG8_SCHED;
;             PG8_LDB(B0, 1, 0); PG8_LDB(B1, 1, 1); PG8_SCHED; PG8_LDA(At, 1, 0); PG8_STAGE(PG8_SA(0, 1), a2 + hstepA, voffA);
;             PG8_WAIT_V(8); PG8_WAIT_L(0); PG8_BAR; PG8_MMA(0, 0, At, B0); PG8_MMA(0, 1, At, B1); PG8_BAR; PG8_SCHED;
	v_mfma_f32_16x16x32_bf16 v[162:165], v[102:105], v[166:169], v[162:165]
	v_mfma_f32_16x16x32_bf16 v[66:69], v[110:113], v[166:169], v[66:69]
	v_mfma_f32_16x16x32_bf16 v[158:161], v[102:105], v[174:177], v[158:161]
	v_mfma_f32_16x16x32_bf16 v[62:65], v[110:113], v[174:177], v[62:65]
	v_mfma_f32_16x16x32_bf16 v[146:149], v[102:105], v[182:185], v[146:149]
	v_mfma_f32_16x16x32_bf16 v[50:53], v[110:113], v[182:185], v[50:53]
	v_mfma_f32_16x16x32_bf16 v[138:141], v[102:105], v[212:215], v[138:141]
	v_mfma_f32_16x16x32_bf16 v[42:45], v[110:113], v[212:215], v[42:45]
	v_mfma_f32_16x16x32_bf16 v[162:165], v[106:109], v[170:173], v[162:165]
	v_mfma_f32_16x16x32_bf16 v[66:69], v[114:117], v[170:173], v[66:69]
	v_mfma_f32_16x16x32_bf16 v[158:161], v[106:109], v[178:181], v[158:161]
	v_mfma_f32_16x16x32_bf16 v[62:65], v[114:117], v[178:181], v[62:65]
	v_mfma_f32_16x16x32_bf16 v[146:149], v[106:109], v[186:189], v[146:149]
	v_mfma_f32_16x16x32_bf16 v[50:53], v[114:117], v[186:189], v[50:53]
	v_mfma_f32_16x16x32_bf16 v[138:141], v[106:109], v[216:219], v[138:141]
	v_mfma_f32_16x16x32_bf16 v[42:45], v[114:117], v[216:219], v[42:45]
	v_mfma_f32_16x16x32_bf16 v[154:157], v[118:121], v[166:169], v[154:157]
	v_mfma_f32_16x16x32_bf16 v[58:61], v[126:129], v[166:169], v[58:61]
	v_mfma_f32_16x16x32_bf16 v[150:153], v[118:121], v[174:177], v[150:153]
	v_mfma_f32_16x16x32_bf16 v[54:57], v[126:129], v[174:177], v[54:57]
	v_mfma_f32_16x16x32_bf16 v[142:145], v[118:121], v[182:185], v[142:145]
	v_mfma_f32_16x16x32_bf16 v[46:49], v[126:129], v[182:185], v[46:49]
	v_mfma_f32_16x16x32_bf16 v[134:137], v[118:121], v[212:215], v[134:137]
	v_mfma_f32_16x16x32_bf16 v[38:41], v[126:129], v[212:215], v[38:41]
	v_mfma_f32_16x16x32_bf16 v[154:157], v[122:125], v[170:173], v[154:157]
	v_mfma_f32_16x16x32_bf16 v[58:61], v[130:133], v[170:173], v[58:61]
	v_mfma_f32_16x16x32_bf16 v[150:153], v[122:125], v[178:181], v[150:153]
	v_mfma_f32_16x16x32_bf16 v[54:57], v[130:133], v[178:181], v[54:57]
	v_mfma_f32_16x16x32_bf16 v[142:145], v[122:125], v[186:189], v[142:145]
	v_mfma_f32_16x16x32_bf16 v[46:49], v[130:133], v[186:189], v[46:49]
	v_mfma_f32_16x16x32_bf16 v[134:137], v[122:125], v[216:219], v[134:137]
	v_mfma_f32_16x16x32_bf16 v[38:41], v[130:133], v[216:219], v[38:41]
	s_barrier
	s_setprio 0
	s_add_i32 s55, s55, s10
	v_lshl_add_u64 v[208:209], s[22:23], 0, v[0:1]
	s_mov_b32 m0, s55
	ds_read_b128 v[166:169], v247 offset:16384
	ds_read_b128 v[170:173], v247 offset:17408
	ds_read_b128 v[174:177], v247 offset:18432
	ds_read_b128 v[178:181], v247 offset:19456
	ds_read_b128 v[182:185], v247 offset:20480
	ds_read_b128 v[186:189], v247 offset:21504
	ds_read_b128 v[212:215], v247 offset:22528
	ds_read_b128 v[216:219], v247 offset:23552
	global_load_lds_dwordx4 v[208:209], off
	s_add_i32 m0, s55, 0x2000
	s_add_u32 s56, s22, 0x40000
	v_lshl_add_u64 v[220:221], s[22:23], 0, v[192:193]
	s_addc_u32 s57, s23, 0
	s_add_i32 s55, s58, s10
	global_load_lds_dwordx4 v[220:221], off
	v_lshl_add_u64 v[222:223], s[56:57], 0, v[0:1]
	s_mov_b32 m0, s55
	v_lshl_add_u64 v[224:225], s[40:41], 0, v[190:191]
	global_load_lds_dwordx4 v[222:223], off
	v_lshl_add_u64 v[222:223], s[56:57], 0, v[192:193]
	s_add_i32 m0, s55, 0x2000
	s_nop 0
	global_load_lds_dwordx4 v[222:223], off
	v_lshl_add_u64 v[222:223], s[40:41], 0, v[14:15]
	s_mov_b32 m0, s11
	s_nop 0
	global_load_lds_dwordx4 v[222:223], off
	s_mov_b32 m0, s9
	s_nop 0
	global_load_lds_dwordx4 v[224:225], off
	s_waitcnt vmcnt(8)
	s_waitcnt lgkmcnt(0)
	s_setprio 1
	s_barrier
	v_mfma_f32_16x16x32_bf16 v[98:101], v[102:105], v[166:169], v[98:101]
	v_mfma_f32_16x16x32_bf16 v[34:37], v[110:113], v[166:169], v[34:37]
	v_mfma_f32_16x16x32_bf16 v[94:97], v[102:105], v[174:177], v[94:97]
	v_mfma_f32_16x16x32_bf16 v[30:33], v[110:113], v[174:177], v[30:33]
	v_mfma_f32_16x16x32_bf16 v[82:85], v[102:105], v[182:185], v[82:85]
	v_mfma_f32_16x16x32_bf16 v[18:21], v[110:113], v[182:185], v[18:21]
	v_mfma_f32_16x16x32_bf16 v[74:77], v[102:105], v[212:215], v[74:77]
	v_mfma_f32_16x16x32_bf16 v[6:9], v[110:113], v[212:215], v[6:9]
	v_mfma_f32_16x16x32_bf16 v[98:101], v[106:109], v[170:173], v[98:101]
	v_mfma_f32_16x16x32_bf16 v[34:37], v[114:117], v[170:173], v[34:37]
	v_mfma_f32_16x16x32_bf16 v[94:97], v[106:109], v[178:181], v[94:97]
	v_mfma_f32_16x16x32_bf16 v[30:33], v[114:117], v[178:181], v[30:33]
	v_mfma_f32_16x16x32_bf16 v[82:85], v[106:109], v[186:189], v[82:85]
	v_mfma_f32_16x16x32_bf16 v[18:21], v[114:117], v[186:189], v[18:21]
	v_mfma_f32_16x16x32_bf16 v[74:77], v[106:109], v[216:219], v[74:77]
	v_mfma_f32_16x16x32_bf16 v[6:9], v[114:117], v[216:219], v[6:9]
	v_mfma_f32_16x16x32_bf16 v[90:93], v[118:121], v[166:169], v[90:93]
	v_mfma_f32_16x16x32_bf16 v[26:29], v[126:129], v[166:169], v[26:29]
	v_mfma_f32_16x16x32_bf16 v[86:89], v[118:121], v[174:177], v[86:89]
	v_mfma_f32_16x16x32_bf16 v[22:25], v[126:129], v[174:177], v[22:25]
	v_mfma_f32_16x16x32_bf16 v[78:81], v[118:121], v[182:185], v[78:81]
	v_mfma_f32_16x16x32_bf16 v[10:13], v[126:129], v[182:185], v[10:13]
	v_mfma_f32_16x16x32_bf16 v[70:73], v[118:121], v[212:215], v[70:73]
	v_mfma_f32_16x16x32_bf16 v[2:5], v[126:129], v[212:215], v[2:5]
	v_mfma_f32_16x16x32_bf16 v[90:93], v[122:125], v[170:173], v[90:93]
	v_mfma_f32_16x16x32_bf16 v[26:29], v[130:133], v[170:173], v[26:29]
	v_mfma_f32_16x16x32_bf16 v[86:89], v[122:125], v[178:181], v[86:89]
	v_mfma_f32_16x16x32_bf16 v[22:25], v[130:133], v[178:181], v[22:25]
	v_mfma_f32_16x16x32_bf16 v[78:81], v[122:125], v[186:189], v[78:81]
	v_mfma_f32_16x16x32_bf16 v[10:13], v[130:133], v[186:189], v[10:13]
	v_mfma_f32_16x16x32_bf16 v[70:73], v[122:125], v[216:219], v[70:73]
	v_mfma_f32_16x16x32_bf16 v[2:5], v[130:133], v[216:219], v[2:5]
	s_barrier
; #define PG8_STAGE(bufoff, gbase, voff) do { _Pragma("unroll") for (int _i = 0; _i < 2; ++_i) \
;         __builtin_amdgcn_global_load_lds((const unsigned*)((const char*)(gbase) + (voff)[_i]), (LAS unsigned*)(lds + (bufoff) + ldsw + _i * 8192), 16, 0, 0); } while (0)
; #define PG8_LDA(dst, b, h) do { _Pragma("unroll") for (int m = 0; m < 4; ++m) _Pragma("unroll") for (int k = 0; k < 2; ++k) dst[m][k] = *(const LAS bf16x8*)(lds + PG8_SA(b, h) + aoff + m * 2048 + k * 1024); } while (0)
; #define PG8_LDB(dst, b, h) do { _Pragma("unroll") for (int n = 0; n < 2; ++n) _Pragma("unroll") for (int k = 0; k < 2; ++k) dst[n][k] = *(const LAS bf16x8*)(lds + PG8_SB(b, h) + boff + n * 2048 + k * 1024); } while (0)
; #define PG8_MMA(ai, bj, At, Bt) do { __builtin_amdgcn_s_setprio(1); _Pragma("unroll") for (int m = 0; m < 4; ++m) _Pragma("unroll") for (int n = 0; n < 2; ++n) _Pragma("unroll") for (int k = 0; k < 2; ++k) \
;         acc[ai][bj][m][n] = __builtin_amdgcn_mfma_f32_16x16x32_bf16(Bt[n][k], At[m][k], acc[ai][bj][m][n], 0, 0, 0); __builtin_amdgcn_s_setprio(0); } while (0)
; #define PG8_WAIT_V(n) asm volatile("s_waitcnt vmcnt(" #n ")" ::: "memory")
; #define PG8_WAIT_L(n) asm volatile("s_waitcnt lgkmcnt(" #n ")" ::: "memory")
; #define PG8_BAR __builtin_amdgcn_s_barrier()
; #define PG8_SCHED __builtin_amdgcn_sched_barrier(0)
; template <class Epi, bool SEG>
; __device__ __forceinline__ void gemm_phase(LAS unsigned char* lds, const Gemm g, const int G, const int cidx, const Epi& E) {
;     ...
;             PG8_LDB(B0, 1, 0); PG8_LDB(B1, 1, 1); PG8_SCHED; PG8_LDA(At, 1, 0); PG8_STAGE(PG8_SA(0, 1), a2 + hstepA, voffA);
;             PG8_WAIT_V(8); PG8_WAIT_L(0); PG8_BAR; PG8_MMA(0, 0, At, B0); PG8_MMA(0, 1, At, B1); PG8_BAR; PG8_SCHED;
;             PG8_LDA(At, 1, 1); PG8_STAGE(PG8_SB(1, 0), b3, voffB); PG8_STAGE(PG8_SB(1, 1), b3 + hstepB, voffB); PG8_STAGE(PG8_SA(1, 0), a3, voffA);
;             PG8_WAIT_V(8); PG8_WAIT_L(0); PG8_BAR; PG8_MMA(1, 0, At, B0); PG8_MMA(1, 1, At, B1); PG8_BAR; PG8_SCHED;
	s_setprio 0
	s_add_i32 s55, 0, 0x18000
	s_add_i32 s56, 0, 0x1c000
	v_add_u32_e32 v114, s55, v243
	v_add_u32_e32 v130, s56, v243
	ds_read_b128 v[102:105], v114
	ds_read_b128 v[106:109], v114 offset:1024
	ds_read_b128 v[110:113], v114 offset:2048
	ds_read_b128 v[114:117], v114 offset:3072
	ds_read_b128 v[118:121], v130
	ds_read_b128 v[122:125], v130 offset:1024
	ds_read_b128 v[126:129], v130 offset:2048
	ds_read_b128 v[130:133], v130 offset:3072
	s_add_u32 s40, s40, 0x3e000
	s_addc_u32 s41, s41, 0
	s_mov_b32 m0, s36
	v_lshl_add_u64 v[226:227], s[40:41], 0, v[14:15]
	ds_read_b128 v[166:169], v247 offset:32768
	ds_read_b128 v[170:173], v247 offset:33792
	ds_read_b128 v[174:177], v247 offset:34816
	ds_read_b128 v[178:181], v247 offset:35840
	ds_read_b128 v[182:185], v247 offset:36864
	ds_read_b128 v[186:189], v247 offset:37888
	ds_read_b128 v[212:215], v247 offset:38912
	ds_read_b128 v[216:219], v247 offset:39936
	global_load_lds_dwordx4 v[226:227], off
	v_lshl_add_u64 v[226:227], s[40:41], 0, v[190:191]
	s_mov_b32 m0, s12
	s_nop 0
	global_load_lds_dwordx4 v[226:227], off
	s_waitcnt vmcnt(8)
	s_waitcnt lgkmcnt(0)
	s_setprio 1
	s_barrier
	v_mfma_f32_16x16x32_bf16 v[162:165], v[102:105], v[166:169], v[162:165]
	v_mfma_f32_16x16x32_bf16 v[66:69], v[110:113], v[166:169], v[66:69]
	v_mfma_f32_16x16x32_bf16 v[158:161], v[102:105], v[174:177], v[158:161]
	v_mfma_f32_16x16x32_bf16 v[62:65], v[110:113], v[174:177], v[62:65]
	v_mfma_f32_16x16x32_bf16 v[146:149], v[102:105], v[182:185], v[146:149]
	v_mfma_f32_16x16x32_bf16 v[50:53], v[110:113], v[182:185], v[50:53]
	v_mfma_f32_16x16x32_bf16 v[138:141], v[102:105], v[212:215], v[138:141]
	v_mfma_f32_16x16x32_bf16 v[42:45], v[110:113], v[212:215], v[42:45]
	v_mfma_f32_16x16x32_bf16 v[162:165], v[106:109], v[170:173], v[162:165]
	v_mfma_f32_16x16x32_bf16 v[66:69], v[114:117], v[170:173], v[66:69]
	v_mfma_f32_16x16x32_bf16 v[158:161], v[106:109], v[178:181], v[158:161]
	v_mfma_f32_16x16x32_bf16 v[62:65], v[114:117], v[178:181], v[62:65]
	v_mfma_f32_16x16x32_bf16 v[146:149], v[106:109], v[186:189], v[146:149]
	v_mfma_f32_16x16x32_bf16 v[50:53], v[114:117], v[186:189], v[50:53]
	v_mfma_f32_16x16x32_bf16 v[138:141], v[106:109], v[216:219], v[138:141]
	v_mfma_f32_16x16x32_bf16 v[42:45], v[114:117], v[216:219], v[42:45]
	v_mfma_f32_16x16x32_bf16 v[154:157], v[118:121], v[166:169], v[154:157]
	v_mfma_f32_16x16x32_bf16 v[58:61], v[126:129], v[166:169], v[58:61]
	v_mfma_f32_16x16x32_bf16 v[150:153], v[118:121], v[174:177], v[150:153]
	v_mfma_f32_16x16x32_bf16 v[54:57], v[126:129], v[174:177], v[54:57]
	v_mfma_f32_16x16x32_bf16 v[142:145], v[118:121], v[182:185], v[142:145]
	v_mfma_f32_16x16x32_bf16 v[46:49], v[126:129], v[182:185], v[46:49]
	v_mfma_f32_16x16x32_bf16 v[134:137], v[118:121], v[212:215], v[134:137]
	v_mfma_f32_16x16x32_bf16 v[38:41], v[126:129], v[212:215], v[38:41]
	v_mfma_f32_16x16x32_bf16 v[154:157], v[122:125], v[170:173], v[154:157]
	v_mfma_f32_16x16x32_bf16 v[58:61], v[130:133], v[170:173], v[58:61]
	v_mfma_f32_16x16x32_bf16 v[150:153], v[122:125], v[178:181], v[150:153]
	v_mfma_f32_16x16x32_bf16 v[54:57], v[130:133], v[178:181], v[54:57]
	v_mfma_f32_16x16x32_bf16 v[142:145], v[122:125], v[186:189], v[142:145]
	v_mfma_f32_16x16x32_bf16 v[46:49], v[130:133], v[186:189], v[46:49]
	v_mfma_f32_16x16x32_bf16 v[134:137], v[122:125], v[216:219], v[134:137]
	v_mfma_f32_16x16x32_bf16 v[38:41], v[130:133], v[216:219], v[38:41]
	s_barrier
	s_setprio 0
	s_add_i32 s40, s55, s10
	v_lshl_add_u64 v[208:209], v[208:209], 0, s[28:29]
	s_mov_b32 m0, s40
	ds_read_b128 v[166:169], v247 offset:49152
	ds_read_b128 v[170:173], v247 offset:50176
	ds_read_b128 v[174:177], v247 offset:51200
	ds_read_b128 v[178:181], v247 offset:52224
	ds_read_b128 v[182:185], v247 offset:53248
	ds_read_b128 v[186:189], v247 offset:54272
	ds_read_b128 v[212:215], v247 offset:55296
	ds_read_b128 v[216:219], v247 offset:56320
	global_load_lds_dwordx4 v[208:209], off
	s_add_i32 m0, s40, 0x2000
	s_add_u32 s22, s22, 0x40080
	v_lshl_add_u64 v[208:209], v[220:221], 0, s[28:29]
	s_addc_u32 s23, s23, 0
	s_add_i32 s40, s56, s10
	global_load_lds_dwordx4 v[208:209], off
	v_lshl_add_u64 v[208:209], s[22:23], 0, v[0:1]
	s_mov_b32 m0, s40
	s_nop 0
	global_load_lds_dwordx4 v[208:209], off
	v_lshl_add_u64 v[208:209], s[22:23], 0, v[192:193]
	s_add_i32 m0, s40, 0x2000
	s_nop 0
	global_load_lds_dwordx4 v[208:209], off
	v_lshl_add_u64 v[208:209], v[222:223], 0, s[28:29]
	s_mov_b32 m0, s13
	s_nop 0
	global_load_lds_dwordx4 v[208:209], off
	v_lshl_add_u64 v[208:209], v[224:225], 0, s[28:29]
	s_mov_b32 m0, s8
	s_nop 0
	global_load_lds_dwordx4 v[208:209], off
	s_waitcnt vmcnt(8)
	s_waitcnt lgkmcnt(0)
	s_setprio 1
	s_barrier
; #define CONV_WLOAD(BUF, N_, JH_) do { _Pragma("unroll") for (int bj = 0; bj < 2; ++bj) { const float* wp = cwt + bj * 512 + 4 * (N_) + 2 * (JH_); \
;             wq[BUF][bj][0] = *(const f32x2*)(wp); wq[BUF][bj][1] = *(const f32x2*)(wp + 128); wq[BUF][bj][2] = *(const f32x2*)(wp + 256); wq[BUF][bj][3] = *(const f32x2*)(wp + 384); } } while (0)
; #define PG8_STAGE(bufoff, gbase, voff) do { _Pragma("unroll") for (int _i = 0; _i < 2; ++_i) \
;         __builtin_amdgcn_global_load_lds((const unsigned*)((const char*)(gbase) + (voff)[_i]), (LAS unsigned*)(lds + (bufoff) + ldsw + _i * 8192), 16, 0, 0); } while (0)
; #define PG8_LDA(dst, b, h) do { _Pragma("unroll") for (int m = 0; m < 4; ++m) _Pragma("unroll") for (int k = 0; k < 2; ++k) dst[m][k] = *(const LAS bf16x8*)(lds + PG8_SA(b, h) + aoff + m * 2048 + k * 1024); } while (0)
; #define PG8_MMA(ai, bj, At, Bt) do { __builtin_amdgcn_s_setprio(1); _Pragma("unroll") for (int m = 0; m < 4; ++m) _Pragma("unroll") for (int n = 0; n < 2; ++n) _Pragma("unroll") for (int k = 0; k < 2; ++k) \
;         acc[ai][bj][m][n] = __builtin_amdgcn_mfma_f32_16x16x32_bf16(Bt[n][k], At[m][k], acc[ai][bj][m][n], 0, 0, 0); __builtin_amdgcn_s_setprio(0); } while (0)
; #define PG8_WAIT_V(n) asm volatile("s_waitcnt vmcnt(" #n ")" ::: "memory")
; #define PG8_BAR __builtin_amdgcn_s_barrier()
;     __device__ __forceinline__ void operator()(f32x4 (&acc)[2][2][4][2], const Unit& u, int wr, int wc, int fr, int fq) const {
;     ...
;         f32x4 qs[8];
; #pragma unroll
;         for (int i = 0; i < 8; ++i) { const int tok = u.pm * 248 + 62 * (2 * (i >> 2) + wr) - 1 + 16 * (i & 3) + fr; int tc = tok < 0 ? 0 : tok; tc = tc > ntok - 1 ? ntok - 1 : tc;
;             qs[i] = *(const f32x4*)(ss + (size_t)tc * 4); }
;     ...
;         f32x2 wq[2][2][4];
;     ...
;         CONV_WLOAD(0, 0, 0);
; template <class Epi, bool SEG>
; __device__ __forceinline__ void gemm_phase(LAS unsigned char* lds, const Gemm g, const int G, const int cidx, const Epi& E) {
;     ...
;             PG8_WAIT_V(8); PG8_WAIT_L(0); PG8_BAR; PG8_MMA(0, 0, At, B0); PG8_MMA(0, 1, At, B1); PG8_BAR; PG8_SCHED;
;             PG8_LDA(At, 1, 1); PG8_STAGE(PG8_SB(1, 0), b3, voffB); PG8_STAGE(PG8_SB(1, 1), b3 + hstepB, voffB); PG8_STAGE(PG8_SA(1, 0), a3, voffA);
;             PG8_WAIT_V(8); PG8_WAIT_L(0); PG8_BAR; PG8_MMA(1, 0, At, B0); PG8_MMA(1, 1, At, B1); PG8_BAR; PG8_SCHED;
;         }
	v_mfma_f32_16x16x32_bf16 v[98:101], v[102:105], v[166:169], v[98:101]
	v_mfma_f32_16x16x32_bf16 v[34:37], v[110:113], v[166:169], v[34:37]
	v_mfma_f32_16x16x32_bf16 v[94:97], v[102:105], v[174:177], v[94:97]
	v_mfma_f32_16x16x32_bf16 v[30:33], v[110:113], v[174:177], v[30:33]
	v_mfma_f32_16x16x32_bf16 v[82:85], v[102:105], v[182:185], v[82:85]
	v_mfma_f32_16x16x32_bf16 v[18:21], v[110:113], v[182:185], v[18:21]
	v_mfma_f32_16x16x32_bf16 v[74:77], v[102:105], v[212:215], v[74:77]
	v_mfma_f32_16x16x32_bf16 v[6:9], v[110:113], v[212:215], v[6:9]
	v_mfma_f32_16x16x32_bf16 v[98:101], v[106:109], v[170:173], v[98:101]
	v_mfma_f32_16x16x32_bf16 v[34:37], v[114:117], v[170:173], v[34:37]
	v_mfma_f32_16x16x32_bf16 v[94:97], v[106:109], v[178:181], v[94:97]
	v_mfma_f32_16x16x32_bf16 v[30:33], v[114:117], v[178:181], v[30:33]
	v_mfma_f32_16x16x32_bf16 v[82:85], v[106:109], v[186:189], v[82:85]
	v_mfma_f32_16x16x32_bf16 v[18:21], v[114:117], v[186:189], v[18:21]
	v_mfma_f32_16x16x32_bf16 v[74:77], v[106:109], v[216:219], v[74:77]
	v_mfma_f32_16x16x32_bf16 v[6:9], v[114:117], v[216:219], v[6:9]
	v_mfma_f32_16x16x32_bf16 v[90:93], v[118:121], v[166:169], v[90:93]
	v_mfma_f32_16x16x32_bf16 v[26:29], v[126:129], v[166:169], v[26:29]
	v_mfma_f32_16x16x32_bf16 v[86:89], v[118:121], v[174:177], v[86:89]
	v_mfma_f32_16x16x32_bf16 v[22:25], v[126:129], v[174:177], v[22:25]
	v_mfma_f32_16x16x32_bf16 v[78:81], v[118:121], v[182:185], v[78:81]
	v_mfma_f32_16x16x32_bf16 v[10:13], v[126:129], v[182:185], v[10:13]
	v_mfma_f32_16x16x32_bf16 v[70:73], v[118:121], v[212:215], v[70:73]
	v_mfma_f32_16x16x32_bf16 v[2:5], v[126:129], v[212:215], v[2:5]
	v_mfma_f32_16x16x32_bf16 v[90:93], v[122:125], v[170:173], v[90:93]
	v_mfma_f32_16x16x32_bf16 v[26:29], v[130:133], v[170:173], v[26:29]
	v_mfma_f32_16x16x32_bf16 v[86:89], v[122:125], v[178:181], v[86:89]
	v_mfma_f32_16x16x32_bf16 v[22:25], v[130:133], v[178:181], v[22:25]
	v_mfma_f32_16x16x32_bf16 v[78:81], v[122:125], v[186:189], v[78:81]
	v_mfma_f32_16x16x32_bf16 v[10:13], v[130:133], v[186:189], v[10:13]
	v_mfma_f32_16x16x32_bf16 v[70:73], v[122:125], v[216:219], v[70:73]
	v_mfma_f32_16x16x32_bf16 v[2:5], v[130:133], v[216:219], v[2:5]
	s_barrier
	s_setprio 0
	s_add_i32 s54, s54, 2
	s_add_u32 s6, s6, 0x100
	s_addc_u32 s7, s7, 0
	s_add_u32 s52, s52, 0x100
	s_addc_u32 s53, s53, 0
	s_cmp_gt_u32 s54, 13
	s_cbranch_scc0 .LBB0_786
	s_mul_i32 s15, s31, 0xf8
	s_add_i32 s15, s15, -1
	v_add_u32_e32 v102, s15, v17
	v_add_u32_e32 v104, 16, v102
	v_add_u32_e32 v105, s1, v104
	v_med3_i32 v105, v105, 0, v242
	v_add_u32_e32 v104, s38, v104
	v_lshlrev_b32_e32 v106, 4, v105
	v_add_u32_e32 v105, 32, v102
	v_med3_i32 v104, v104, 0, v242
	v_lshlrev_b32_e32 v110, 4, v104
	v_add_u32_e32 v104, s38, v105
	s_ashr_i32 s21, s20, 31
	v_add_u32_e32 v108, 48, v102
	v_med3_i32 v104, v104, 0, v242
	s_lshl_b64 s[6:7], s[20:21], 12
	v_add_u32_e32 v103, s1, v102
	v_add_u32_e32 v107, s1, v105
	v_add_u32_e32 v109, s1, v108
	v_add_u32_e32 v102, s38, v102
	v_lshlrev_b32_e32 v111, 4, v104
	v_add_u32_e32 v104, s38, v108
	v_med3_i32 v103, v103, 0, v242
	v_med3_i32 v107, v107, 0, v242
	v_med3_i32 v109, v109, 0, v242
	v_med3_i32 v102, v102, 0, v242
	v_med3_i32 v104, v104, 0, v242
	v_lshl_add_u64 v[214:215], v[194:195], 0, s[6:7]
	v_readlane_b32 s6, v253, 24
	v_lshlrev_b32_e32 v103, 4, v103
	v_lshlrev_b32_e32 v107, 4, v107
	v_lshlrev_b32_e32 v109, 4, v109
	v_lshlrev_b32_e32 v102, 4, v102
	v_lshlrev_b32_e32 v108, 4, v104
	v_readlane_b32 s7, v253, 25
	s_nop 4
	global_load_dwordx4 v[174:177], v102, s[6:7]
	s_nop 0
	global_load_dwordx4 v[216:219], v103, s[6:7]
	s_nop 0
	global_load_dwordx4 v[166:169], v108, s[6:7]
	global_load_dwordx4 v[170:173], v111, s[6:7]
	global_load_dwordx4 v[178:181], v110, s[6:7]
	global_load_dwordx4 v[182:185], v109, s[6:7]
	global_load_dwordx4 v[186:189], v107, s[6:7]
	s_nop 0
	global_load_dwordx4 v[220:223], v106, s[6:7]
	global_load_dwordx4 v[114:117], v[214:215], off offset:1024
	global_load_dwordx4 v[110:113], v[214:215], off offset:3072
	global_load_dwordx4 v[130:133], v[214:215], off offset:512
	global_load_dwordx4 v[102:105], v[214:215], off offset:1536
	global_load_dwordx4 v[126:129], v[214:215], off offset:2560
	global_load_dwordx4 v[106:109], v[214:215], off offset:3584
	global_load_dwordx4 v[122:125], v[214:215], off
	global_load_dwordx4 v[118:121], v[214:215], off offset:2048
	v_readlane_b32 s6, v255, 19
	v_readlane_b32 s7, v255, 20
	s_mov_b64 s[46:47], s[82:83]
	s_and_b64 vcc, exec, s[6:7]
	s_cbranch_vccz .LBB0_789
	s_barrier

; #define PG8_STAGE(bufoff, gbase, voff) do { _Pragma("unroll") for (int _i = 0; _i < 2; ++_i) \
;         __builtin_amdgcn_global_load_lds((const unsigned*)((const char*)(gbase) + (voff)[_i]), (LAS unsigned*)(lds + (bufoff) + ldsw + _i * 8192), 16, 0, 0); } while (0)
; #define PG8_LDA(dst, b, h) do { _Pragma("unroll") for (int m = 0; m < 4; ++m) _Pragma("unroll") for (int k = 0; k < 2; ++k) dst[m][k] = *(const LAS bf16x8*)(lds + PG8_SA(b, h) + aoff + m * 2048 + k * 1024); } while (0)
; #define PG8_LDB(dst, b, h) do { _Pragma("unroll") for (int n = 0; n < 2; ++n) _Pragma("unroll") for (int k = 0; k < 2; ++k) dst[n][k] = *(const LAS bf16x8*)(lds + PG8_SB(b, h) + boff + n * 2048 + k * 1024); } while (0)
; #define PG8_MMA(ai, bj, At, Bt) do { __builtin_amdgcn_s_setprio(1); _Pragma("unroll") for (int m = 0; m < 4; ++m) _Pragma("unroll") for (int n = 0; n < 2; ++n) _Pragma("unroll") for (int k = 0; k < 2; ++k) \
;         acc[ai][bj][m][n] = __builtin_amdgcn_mfma_f32_16x16x32_bf16(Bt[n][k], At[m][k], acc[ai][bj][m][n], 0, 0, 0); __builtin_amdgcn_s_setprio(0); } while (0)
; #define PG8_BAR __builtin_amdgcn_s_barrier()
; template <class Epi, bool SEG>
; __device__ __forceinline__ void gemm_phase(LAS unsigned char* lds, const Gemm g, const int G, const int cidx, const Epi& E) {
;     ...
;         const bool has_next = S.next(ui + 1, nxt);
;         const char* nA = has_next ? (const char*)g.A + (long)nxt.pm * (long)tstepA + aoff0 : cA; const char* nB = has_next ? (const char*)g.Bt + (size_t)nxt.pn * tstepB : cB;
;         for (int t = 0; t < nt; t += 2) {
;             const bool last = (t == nt - 2);
;             const char* a1 = cA + (size_t)(t + 1) * kstep;
;             const char* a2 = last ? nA : cA + (size_t)(t + 2) * kstep; const char* b2 = last ? nB : cB + (size_t)(t + 2) * kstep;
;             const char* a3 = a2 + kstep; const char* b3 = b2 + kstep;
;             PG8_LDB(B0, 0, 0); PG8_LDB(B1, 0, 1); PG8_SCHED; PG8_LDA(At, 0, 0); PG8_STAGE(PG8_SA(1, 1), a1 + hstepA, voffA);
;             PG8_WAIT_V(8); PG8_WAIT_L(0); PG8_BAR; PG8_MMA(0, 0, At, B0); PG8_MMA(0, 1, At, B1); PG8_BAR; PG8_SCHED;
;             PG8_LDA(At, 0, 1); PG8_STAGE(PG8_SB(0, 0), b2, voffB); PG8_STAGE(PG8_SB(0, 1), b2 + hstepB, voffB); PG8_STAGE(PG8_SA(0, 0), a2, voffA);
;             PG8_WAIT_V(8); PG8_WAIT_L(0); PG8_BAR; PG8_MMA(1, 0, At, B0); PG8_MMA(1, 1, At, B1); PG8_BAR; PG8_SCHED;
.LBB0_957:
	s_add_u32 s52, s20, 0x100
	s_addc_u32 s53, s21, 0
	s_mov_b32 s54, -2
	s_waitcnt lgkmcnt(0)
	s_waitcnt vmcnt(0)
	s_add_u32 s20, s18, 0x100
	s_addc_u32 s21, s19, 0
	s_add_i32 s55, 0, 0x10000
	s_cmp_eq_u32 s54, 40
	s_cselect_b32 s47, s7, s21
	s_cselect_b32 s46, s6, s20
	s_cselect_b32 s23, s17, s53
	s_cselect_b32 s22, s16, s52
	s_add_i32 s56, 0, 0x14000
	v_add_u32_e32 v146, s55, v228
	v_add_u32_e32 v162, s56, v228
	ds_read_b128 v[130:133], v146
	ds_read_b128 v[138:141], v146 offset:1024
	ds_read_b128 v[142:145], v146 offset:2048
	ds_read_b128 v[146:149], v146 offset:3072
	ds_read_b128 v[150:153], v162
	ds_read_b128 v[154:157], v162 offset:1024
	ds_read_b128 v[158:161], v162 offset:2048
	ds_read_b128 v[162:165], v162 offset:3072
	v_lshl_add_u64 v[208:209], s[18:19], 0, v[198:199]
	s_add_i32 m0, s30, 0xc000
	ds_read_b128 v[166:169], v244
	ds_read_b128 v[170:173], v244 offset:1024
	ds_read_b128 v[174:177], v244 offset:2048
	ds_read_b128 v[178:181], v244 offset:3072
	ds_read_b128 v[182:185], v244 offset:4096
	ds_read_b128 v[186:189], v244 offset:5120
	ds_read_b128 v[190:193], v244 offset:6144
	ds_read_b128 v[212:215], v244 offset:7168
	global_load_lds_dwordx4 v[208:209], off
	v_lshl_add_u64 v[208:209], s[18:19], 0, v[200:201]
	s_add_i32 m0, s30, 0xe000
	s_nop 0
	global_load_lds_dwordx4 v[208:209], off
	s_waitcnt vmcnt(8)
	s_waitcnt lgkmcnt(0)
	s_setprio 1
	s_barrier
	v_mfma_f32_16x16x32_bf16 v[134:137], v[130:133], v[166:169], 0
	v_mfma_f32_16x16x32_bf16 v[126:129], v[142:145], v[166:169], 0
	v_mfma_f32_16x16x32_bf16 v[114:117], v[130:133], v[174:177], 0
	v_mfma_f32_16x16x32_bf16 v[110:113], v[142:145], v[174:177], 0
	v_mfma_f32_16x16x32_bf16 v[98:101], v[130:133], v[182:185], 0
	v_mfma_f32_16x16x32_bf16 v[94:97], v[142:145], v[182:185], 0
	v_mfma_f32_16x16x32_bf16 v[82:85], v[130:133], v[190:193], 0
	v_mfma_f32_16x16x32_bf16 v[78:81], v[142:145], v[190:193], 0
	v_mfma_f32_16x16x32_bf16 v[134:137], v[138:141], v[170:173], v[134:137]
	v_mfma_f32_16x16x32_bf16 v[126:129], v[146:149], v[170:173], v[126:129]
	v_mfma_f32_16x16x32_bf16 v[114:117], v[138:141], v[178:181], v[114:117]
	v_mfma_f32_16x16x32_bf16 v[110:113], v[146:149], v[178:181], v[110:113]
	v_mfma_f32_16x16x32_bf16 v[98:101], v[138:141], v[186:189], v[98:101]
	v_mfma_f32_16x16x32_bf16 v[94:97], v[146:149], v[186:189], v[94:97]
	v_mfma_f32_16x16x32_bf16 v[82:85], v[138:141], v[212:215], v[82:85]
	v_mfma_f32_16x16x32_bf16 v[78:81], v[146:149], v[212:215], v[78:81]
	v_mfma_f32_16x16x32_bf16 v[122:125], v[150:153], v[166:169], 0
	v_mfma_f32_16x16x32_bf16 v[118:121], v[158:161], v[166:169], 0
	v_mfma_f32_16x16x32_bf16 v[106:109], v[150:153], v[174:177], 0
	v_mfma_f32_16x16x32_bf16 v[102:105], v[158:161], v[174:177], 0
	v_mfma_f32_16x16x32_bf16 v[90:93], v[150:153], v[182:185], 0
	v_mfma_f32_16x16x32_bf16 v[86:89], v[158:161], v[182:185], 0
	v_mfma_f32_16x16x32_bf16 v[74:77], v[150:153], v[190:193], 0
	v_mfma_f32_16x16x32_bf16 v[70:73], v[158:161], v[190:193], 0
	v_mfma_f32_16x16x32_bf16 v[122:125], v[154:157], v[170:173], v[122:125]
	v_mfma_f32_16x16x32_bf16 v[118:121], v[162:165], v[170:173], v[118:121]
	v_mfma_f32_16x16x32_bf16 v[106:109], v[154:157], v[178:181], v[106:109]
	v_mfma_f32_16x16x32_bf16 v[102:105], v[162:165], v[178:181], v[102:105]
	v_mfma_f32_16x16x32_bf16 v[90:93], v[154:157], v[186:189], v[90:93]
	v_mfma_f32_16x16x32_bf16 v[86:89], v[162:165], v[186:189], v[86:89]
	v_mfma_f32_16x16x32_bf16 v[74:77], v[154:157], v[212:215], v[74:77]
	v_mfma_f32_16x16x32_bf16 v[70:73], v[162:165], v[212:215], v[70:73]
	s_barrier
	s_setprio 0
	s_add_i32 s18, s55, s9
	v_lshl_add_u64 v[208:209], s[22:23], 0, v[0:1]
	s_mov_b32 m0, s18
	ds_read_b128 v[166:169], v244 offset:16384
	ds_read_b128 v[170:173], v244 offset:17408
	ds_read_b128 v[174:177], v244 offset:18432
	ds_read_b128 v[178:181], v244 offset:19456
	ds_read_b128 v[182:185], v244 offset:20480
	ds_read_b128 v[186:189], v244 offset:21504
	ds_read_b128 v[190:193], v244 offset:22528
	ds_read_b128 v[212:215], v244 offset:23552
	global_load_lds_dwordx4 v[208:209], off
	s_add_i32 m0, s18, 0x2000
	s_add_u32 s18, s22, 0xb0000
	v_lshl_add_u64 v[216:217], s[22:23], 0, v[14:15]
	s_addc_u32 s19, s23, 0
	s_add_i32 s55, s56, s9
	global_load_lds_dwordx4 v[216:217], off
	v_lshl_add_u64 v[218:219], s[18:19], 0, v[0:1]
	s_mov_b32 m0, s55
	v_lshl_add_u64 v[220:221], s[46:47], 0, v[194:195]
	global_load_lds_dwordx4 v[218:219], off
	v_lshl_add_u64 v[218:219], s[18:19], 0, v[14:15]
	s_add_i32 m0, s55, 0x2000
	s_nop 0
	global_load_lds_dwordx4 v[218:219], off
	v_lshl_add_u64 v[218:219], s[46:47], 0, v[196:197]
	s_mov_b32 m0, s30
	s_nop 0
	global_load_lds_dwordx4 v[218:219], off
	s_mov_b32 m0, s31
	s_nop 0
	global_load_lds_dwordx4 v[220:221], off
	s_waitcnt vmcnt(8)
	s_waitcnt lgkmcnt(0)
	s_setprio 1
	s_barrier
; #define PG8_STAGE(bufoff, gbase, voff) do { _Pragma("unroll") for (int _i = 0; _i < 2; ++_i) \
;         __builtin_amdgcn_global_load_lds((const unsigned*)((const char*)(gbase) + (voff)[_i]), (LAS unsigned*)(lds + (bufoff) + ldsw + _i * 8192), 16, 0, 0); } while (0)
; #define PG8_LDA(dst, b, h) do { _Pragma("unroll") for (int m = 0; m < 4; ++m) _Pragma("unroll") for (int k = 0; k < 2; ++k) dst[m][k] = *(const LAS bf16x8*)(lds + PG8_SA(b, h) + aoff + m * 2048 + k * 1024); } while (0)
; #define PG8_LDB(dst, b, h) do { _Pragma("unroll") for (int n = 0; n < 2; ++n) _Pragma("unroll") for (int k = 0; k < 2; ++k) dst[n][k] = *(const LAS bf16x8*)(lds + PG8_SB(b, h) + boff + n * 2048 + k * 1024); } while (0)
; #define PG8_MMA(ai, bj, At, Bt) do { __builtin_amdgcn_s_setprio(1); _Pragma("unroll") for (int m = 0; m < 4; ++m) _Pragma("unroll") for (int n = 0; n < 2; ++n) _Pragma("unroll") for (int k = 0; k < 2; ++k) \
;         acc[ai][bj][m][n] = __builtin_amdgcn_mfma_f32_16x16x32_bf16(Bt[n][k], At[m][k], acc[ai][bj][m][n], 0, 0, 0); __builtin_amdgcn_s_setprio(0); } while (0)
; #define PG8_WAIT_V(n) asm volatile("s_waitcnt vmcnt(" #n ")" ::: "memory")
; #define PG8_WAIT_L(n) asm volatile("s_waitcnt lgkmcnt(" #n ")" ::: "memory")
; #define PG8_BAR __builtin_amdgcn_s_barrier()
; #define PG8_SCHED __builtin_amdgcn_sched_barrier(0)
; template <class Epi, bool SEG>
; __device__ __forceinline__ void gemm_phase(LAS unsigned char* lds, const Gemm g, const int G, const int cidx, const Epi& E) {
;     ...
;             PG8_WAIT_V(8); PG8_WAIT_L(0); PG8_BAR; PG8_MMA(0, 0, At, B0); PG8_MMA(0, 1, At, B1); PG8_BAR; PG8_SCHED;
;             PG8_LDA(At, 0, 1); PG8_STAGE(PG8_SB(0, 0), b2, voffB); PG8_STAGE(PG8_SB(0, 1), b2 + hstepB, voffB); PG8_STAGE(PG8_SA(0, 0), a2, voffA);
;             PG8_WAIT_V(8); PG8_WAIT_L(0); PG8_BAR; PG8_MMA(1, 0, At, B0); PG8_MMA(1, 1, At, B1); PG8_BAR; PG8_SCHED;
;             PG8_LDB(B0, 1, 0); PG8_LDB(B1, 1, 1); PG8_SCHED; PG8_LDA(At, 1, 0); PG8_STAGE(PG8_SA(0, 1), a2 + hstepA, voffA);
;             PG8_WAIT_V(8); PG8_WAIT_L(0); PG8_BAR; PG8_MMA(0, 0, At, B0); PG8_MMA(0, 1, At, B1); PG8_BAR; PG8_SCHED;
	v_mfma_f32_16x16x32_bf16 v[66:69], v[130:133], v[166:169], 0
	v_mfma_f32_16x16x32_bf16 v[62:65], v[142:145], v[166:169], 0
	v_mfma_f32_16x16x32_bf16 v[50:53], v[130:133], v[174:177], 0
	v_mfma_f32_16x16x32_bf16 v[46:49], v[142:145], v[174:177], 0
	v_mfma_f32_16x16x32_bf16 v[34:37], v[130:133], v[182:185], 0
	v_mfma_f32_16x16x32_bf16 v[30:33], v[142:145], v[182:185], 0
	v_mfma_f32_16x16x32_bf16 v[18:21], v[130:133], v[190:193], 0
	v_mfma_f32_16x16x32_bf16 v[10:13], v[142:145], v[190:193], 0
	v_mfma_f32_16x16x32_bf16 v[66:69], v[138:141], v[170:173], v[66:69]
	v_mfma_f32_16x16x32_bf16 v[62:65], v[146:149], v[170:173], v[62:65]
	v_mfma_f32_16x16x32_bf16 v[50:53], v[138:141], v[178:181], v[50:53]
	v_mfma_f32_16x16x32_bf16 v[46:49], v[146:149], v[178:181], v[46:49]
	v_mfma_f32_16x16x32_bf16 v[34:37], v[138:141], v[186:189], v[34:37]
	v_mfma_f32_16x16x32_bf16 v[30:33], v[146:149], v[186:189], v[30:33]
	v_mfma_f32_16x16x32_bf16 v[18:21], v[138:141], v[212:215], v[18:21]
	v_mfma_f32_16x16x32_bf16 v[10:13], v[146:149], v[212:215], v[10:13]
	v_mfma_f32_16x16x32_bf16 v[58:61], v[150:153], v[166:169], 0
	v_mfma_f32_16x16x32_bf16 v[54:57], v[158:161], v[166:169], 0
	v_mfma_f32_16x16x32_bf16 v[42:45], v[150:153], v[174:177], 0
	v_mfma_f32_16x16x32_bf16 v[38:41], v[158:161], v[174:177], 0
	v_mfma_f32_16x16x32_bf16 v[26:29], v[150:153], v[182:185], 0
	v_mfma_f32_16x16x32_bf16 v[22:25], v[158:161], v[182:185], 0
	v_mfma_f32_16x16x32_bf16 v[6:9], v[150:153], v[190:193], 0
	v_mfma_f32_16x16x32_bf16 v[2:5], v[158:161], v[190:193], 0
	v_mfma_f32_16x16x32_bf16 v[58:61], v[154:157], v[170:173], v[58:61]
	v_mfma_f32_16x16x32_bf16 v[54:57], v[162:165], v[170:173], v[54:57]
	v_mfma_f32_16x16x32_bf16 v[42:45], v[154:157], v[178:181], v[42:45]
	v_mfma_f32_16x16x32_bf16 v[38:41], v[162:165], v[178:181], v[38:41]
	v_mfma_f32_16x16x32_bf16 v[26:29], v[154:157], v[186:189], v[26:29]
	v_mfma_f32_16x16x32_bf16 v[22:25], v[162:165], v[186:189], v[22:25]
	v_mfma_f32_16x16x32_bf16 v[6:9], v[154:157], v[212:215], v[6:9]
	v_mfma_f32_16x16x32_bf16 v[2:5], v[162:165], v[212:215], v[2:5]
	s_barrier
	s_setprio 0
	s_add_i32 s55, 0, 0x18000
	s_add_i32 s56, 0, 0x1c000
	v_add_u32_e32 v146, s55, v228
	v_add_u32_e32 v162, s56, v228
	ds_read_b128 v[130:133], v146
	ds_read_b128 v[138:141], v146 offset:1024
	ds_read_b128 v[142:145], v146 offset:2048
	ds_read_b128 v[146:149], v146 offset:3072
	ds_read_b128 v[150:153], v162
	ds_read_b128 v[154:157], v162 offset:1024
	ds_read_b128 v[158:161], v162 offset:2048
	ds_read_b128 v[162:165], v162 offset:3072
	s_add_u32 s18, s46, 0xb0000
	s_addc_u32 s19, s47, 0
	s_mov_b32 m0, s36
	v_lshl_add_u64 v[222:223], s[18:19], 0, v[196:197]
	ds_read_b128 v[166:169], v244 offset:32768
	ds_read_b128 v[170:173], v244 offset:33792
	ds_read_b128 v[174:177], v244 offset:34816
	ds_read_b128 v[178:181], v244 offset:35840
	ds_read_b128 v[182:185], v244 offset:36864
	ds_read_b128 v[186:189], v244 offset:37888
	ds_read_b128 v[190:193], v244 offset:38912
	ds_read_b128 v[212:215], v244 offset:39936
	global_load_lds_dwordx4 v[222:223], off
	v_lshl_add_u64 v[222:223], s[18:19], 0, v[194:195]
	s_mov_b32 m0, s38
	s_nop 0
	global_load_lds_dwordx4 v[222:223], off
	s_waitcnt vmcnt(8)
	s_waitcnt lgkmcnt(0)
	s_setprio 1
	s_barrier
	v_mfma_f32_16x16x32_bf16 v[134:137], v[130:133], v[166:169], v[134:137]
	v_mfma_f32_16x16x32_bf16 v[126:129], v[142:145], v[166:169], v[126:129]
	v_mfma_f32_16x16x32_bf16 v[114:117], v[130:133], v[174:177], v[114:117]
	v_mfma_f32_16x16x32_bf16 v[110:113], v[142:145], v[174:177], v[110:113]
	v_mfma_f32_16x16x32_bf16 v[98:101], v[130:133], v[182:185], v[98:101]
	v_mfma_f32_16x16x32_bf16 v[94:97], v[142:145], v[182:185], v[94:97]
	v_mfma_f32_16x16x32_bf16 v[82:85], v[130:133], v[190:193], v[82:85]
	v_mfma_f32_16x16x32_bf16 v[78:81], v[142:145], v[190:193], v[78:81]
	v_mfma_f32_16x16x32_bf16 v[134:137], v[138:141], v[170:173], v[134:137]
	v_mfma_f32_16x16x32_bf16 v[126:129], v[146:149], v[170:173], v[126:129]
	v_mfma_f32_16x16x32_bf16 v[114:117], v[138:141], v[178:181], v[114:117]
	v_mfma_f32_16x16x32_bf16 v[110:113], v[146:149], v[178:181], v[110:113]
	v_mfma_f32_16x16x32_bf16 v[98:101], v[138:141], v[186:189], v[98:101]
	v_mfma_f32_16x16x32_bf16 v[94:97], v[146:149], v[186:189], v[94:97]
	v_mfma_f32_16x16x32_bf16 v[82:85], v[138:141], v[212:215], v[82:85]
	v_mfma_f32_16x16x32_bf16 v[78:81], v[146:149], v[212:215], v[78:81]
	v_mfma_f32_16x16x32_bf16 v[122:125], v[150:153], v[166:169], v[122:125]
	v_mfma_f32_16x16x32_bf16 v[118:121], v[158:161], v[166:169], v[118:121]
	v_mfma_f32_16x16x32_bf16 v[106:109], v[150:153], v[174:177], v[106:109]
	v_mfma_f32_16x16x32_bf16 v[102:105], v[158:161], v[174:177], v[102:105]
	v_mfma_f32_16x16x32_bf16 v[90:93], v[150:153], v[182:185], v[90:93]
	v_mfma_f32_16x16x32_bf16 v[86:89], v[158:161], v[182:185], v[86:89]
	v_mfma_f32_16x16x32_bf16 v[74:77], v[150:153], v[190:193], v[74:77]
	v_mfma_f32_16x16x32_bf16 v[70:73], v[158:161], v[190:193], v[70:73]
	v_mfma_f32_16x16x32_bf16 v[122:125], v[154:157], v[170:173], v[122:125]
	v_mfma_f32_16x16x32_bf16 v[118:121], v[162:165], v[170:173], v[118:121]
	v_mfma_f32_16x16x32_bf16 v[106:109], v[154:157], v[178:181], v[106:109]
	v_mfma_f32_16x16x32_bf16 v[102:105], v[162:165], v[178:181], v[102:105]
	v_mfma_f32_16x16x32_bf16 v[90:93], v[154:157], v[186:189], v[90:93]
	v_mfma_f32_16x16x32_bf16 v[86:89], v[162:165], v[186:189], v[86:89]
	v_mfma_f32_16x16x32_bf16 v[74:77], v[154:157], v[212:215], v[74:77]
	v_mfma_f32_16x16x32_bf16 v[70:73], v[162:165], v[212:215], v[70:73]
	s_barrier
; #define PG8_STAGE(bufoff, gbase, voff) do { _Pragma("unroll") for (int _i = 0; _i < 2; ++_i) \
;         __builtin_amdgcn_global_load_lds((const unsigned*)((const char*)(gbase) + (voff)[_i]), (LAS unsigned*)(lds + (bufoff) + ldsw + _i * 8192), 16, 0, 0); } while (0)
; #define PG8_LDA(dst, b, h) do { _Pragma("unroll") for (int m = 0; m < 4; ++m) _Pragma("unroll") for (int k = 0; k < 2; ++k) dst[m][k] = *(const LAS bf16x8*)(lds + PG8_SA(b, h) + aoff + m * 2048 + k * 1024); } while (0)
; #define PG8_LDB(dst, b, h) do { _Pragma("unroll") for (int n = 0; n < 2; ++n) _Pragma("unroll") for (int k = 0; k < 2; ++k) dst[n][k] = *(const LAS bf16x8*)(lds + PG8_SB(b, h) + boff + n * 2048 + k * 1024); } while (0)
; #define PG8_MMA(ai, bj, At, Bt) do { __builtin_amdgcn_s_setprio(1); _Pragma("unroll") for (int m = 0; m < 4; ++m) _Pragma("unroll") for (int n = 0; n < 2; ++n) _Pragma("unroll") for (int k = 0; k < 2; ++k) \
;         acc[ai][bj][m][n] = __builtin_amdgcn_mfma_f32_16x16x32_bf16(Bt[n][k], At[m][k], acc[ai][bj][m][n], 0, 0, 0); __builtin_amdgcn_s_setprio(0); } while (0)
; #define PG8_WAIT_V(n) asm volatile("s_waitcnt vmcnt(" #n ")" ::: "memory")
; #define PG8_WAIT_L(n) asm volatile("s_waitcnt lgkmcnt(" #n ")" ::: "memory")
; template <class Epi, bool SEG>
; __device__ __forceinline__ void gemm_phase(LAS unsigned char* lds, const Gemm g, const int G, const int cidx, const Epi& E) {
;     ...
;         for (int t = 0; t < nt; t += 2) {
;             const bool last = (t == nt - 2);
;             const char* a1 = cA + (size_t)(t + 1) * kstep;
;             const char* a2 = last ? nA : cA + (size_t)(t + 2) * kstep; const char* b2 = last ? nB : cB + (size_t)(t + 2) * kstep;
;             const char* a3 = a2 + kstep; const char* b3 = b2 + kstep;
;             PG8_LDB(B0, 0, 0); PG8_LDB(B1, 0, 1); PG8_SCHED; PG8_LDA(At, 0, 0); PG8_STAGE(PG8_SA(1, 1), a1 + hstepA, voffA);
;             PG8_WAIT_V(8); PG8_WAIT_L(0); PG8_BAR; PG8_MMA(0, 0, At, B0); PG8_MMA(0, 1, At, B1); PG8_BAR; PG8_SCHED;
;     ...
;             PG8_WAIT_V(8); PG8_WAIT_L(0); PG8_BAR; PG8_MMA(0, 0, At, B0); PG8_MMA(0, 1, At, B1); PG8_BAR; PG8_SCHED;
;             PG8_LDA(At, 1, 1); PG8_STAGE(PG8_SB(1, 0), b3, voffB); PG8_STAGE(PG8_SB(1, 1), b3 + hstepB, voffB); PG8_STAGE(PG8_SA(1, 0), a3, voffA);
;             PG8_WAIT_V(8); PG8_WAIT_L(0); PG8_BAR; PG8_MMA(1, 0, At, B0); PG8_MMA(1, 1, At, B1); PG8_BAR; PG8_SCHED;
	s_setprio 0
	s_add_i32 s18, s55, s9
	v_lshl_add_u64 v[208:209], v[208:209], 0, s[28:29]
	s_mov_b32 m0, s18
	ds_read_b128 v[166:169], v244 offset:49152
	ds_read_b128 v[170:173], v244 offset:50176
	ds_read_b128 v[174:177], v244 offset:51200
	ds_read_b128 v[178:181], v244 offset:52224
	ds_read_b128 v[182:185], v244 offset:53248
	ds_read_b128 v[186:189], v244 offset:54272
	ds_read_b128 v[190:193], v244 offset:55296
	ds_read_b128 v[212:215], v244 offset:56320
	global_load_lds_dwordx4 v[208:209], off
	s_add_i32 m0, s18, 0x2000
	s_add_u32 s18, s22, 0xb0080
	v_lshl_add_u64 v[208:209], v[216:217], 0, s[28:29]
	s_addc_u32 s19, s23, 0
	s_add_i32 s22, s56, s9
	global_load_lds_dwordx4 v[208:209], off
	v_lshl_add_u64 v[208:209], s[18:19], 0, v[0:1]
	s_mov_b32 m0, s22
	s_nop 0
	global_load_lds_dwordx4 v[208:209], off
	v_lshl_add_u64 v[208:209], s[18:19], 0, v[14:15]
	s_add_i32 m0, s22, 0x2000
	s_nop 0
	global_load_lds_dwordx4 v[208:209], off
	v_lshl_add_u64 v[208:209], v[218:219], 0, s[28:29]
	s_mov_b32 m0, s39
	s_nop 0
	global_load_lds_dwordx4 v[208:209], off
	v_lshl_add_u64 v[208:209], v[220:221], 0, s[28:29]
	s_mov_b32 m0, s48
	s_nop 0
	global_load_lds_dwordx4 v[208:209], off
	s_waitcnt vmcnt(8)
	s_waitcnt lgkmcnt(0)
	s_setprio 1
	s_barrier
	v_mfma_f32_16x16x32_bf16 v[66:69], v[130:133], v[166:169], v[66:69]
	v_mfma_f32_16x16x32_bf16 v[62:65], v[142:145], v[166:169], v[62:65]
	v_mfma_f32_16x16x32_bf16 v[50:53], v[130:133], v[174:177], v[50:53]
	v_mfma_f32_16x16x32_bf16 v[46:49], v[142:145], v[174:177], v[46:49]
	v_mfma_f32_16x16x32_bf16 v[34:37], v[130:133], v[182:185], v[34:37]
	v_mfma_f32_16x16x32_bf16 v[30:33], v[142:145], v[182:185], v[30:33]
	v_mfma_f32_16x16x32_bf16 v[18:21], v[130:133], v[190:193], v[18:21]
	v_mfma_f32_16x16x32_bf16 v[10:13], v[142:145], v[190:193], v[10:13]
	v_mfma_f32_16x16x32_bf16 v[66:69], v[138:141], v[170:173], v[66:69]
	v_mfma_f32_16x16x32_bf16 v[62:65], v[146:149], v[170:173], v[62:65]
	v_mfma_f32_16x16x32_bf16 v[50:53], v[138:141], v[178:181], v[50:53]
	v_mfma_f32_16x16x32_bf16 v[46:49], v[146:149], v[178:181], v[46:49]
	v_mfma_f32_16x16x32_bf16 v[34:37], v[138:141], v[186:189], v[34:37]
	v_mfma_f32_16x16x32_bf16 v[30:33], v[146:149], v[186:189], v[30:33]
	v_mfma_f32_16x16x32_bf16 v[18:21], v[138:141], v[212:215], v[18:21]
	v_mfma_f32_16x16x32_bf16 v[10:13], v[146:149], v[212:215], v[10:13]
	v_mfma_f32_16x16x32_bf16 v[58:61], v[150:153], v[166:169], v[58:61]
	v_mfma_f32_16x16x32_bf16 v[54:57], v[158:161], v[166:169], v[54:57]
	v_mfma_f32_16x16x32_bf16 v[42:45], v[150:153], v[174:177], v[42:45]
	v_mfma_f32_16x16x32_bf16 v[38:41], v[158:161], v[174:177], v[38:41]
	v_mfma_f32_16x16x32_bf16 v[26:29], v[150:153], v[182:185], v[26:29]
	v_mfma_f32_16x16x32_bf16 v[22:25], v[158:161], v[182:185], v[22:25]
	v_mfma_f32_16x16x32_bf16 v[6:9], v[150:153], v[190:193], v[6:9]
	v_mfma_f32_16x16x32_bf16 v[2:5], v[158:161], v[190:193], v[2:5]
	v_mfma_f32_16x16x32_bf16 v[58:61], v[154:157], v[170:173], v[58:61]
	v_mfma_f32_16x16x32_bf16 v[54:57], v[162:165], v[170:173], v[54:57]
	v_mfma_f32_16x16x32_bf16 v[42:45], v[154:157], v[178:181], v[42:45]
	v_mfma_f32_16x16x32_bf16 v[38:41], v[162:165], v[178:181], v[38:41]
	v_mfma_f32_16x16x32_bf16 v[26:29], v[154:157], v[186:189], v[26:29]
	v_mfma_f32_16x16x32_bf16 v[22:25], v[162:165], v[186:189], v[22:25]
	v_mfma_f32_16x16x32_bf16 v[6:9], v[154:157], v[212:215], v[6:9]
	v_mfma_f32_16x16x32_bf16 v[2:5], v[162:165], v[212:215], v[2:5]
	s_barrier
	s_setprio 0
	s_add_i32 s54, s54, 2
	s_add_u32 s52, s52, 0x100
	s_addc_u32 s53, s53, 0
	s_mov_b64 s[18:19], s[20:21]
.LBB0_958:
	s_add_u32 s20, s18, 0x100
	s_addc_u32 s21, s19, 0
	s_add_i32 s55, 0, 0x10000
	s_cmp_eq_u32 s54, 40
	s_cselect_b32 s47, s7, s21
	s_cselect_b32 s46, s6, s20
	s_cselect_b32 s23, s17, s53
	s_cselect_b32 s22, s16, s52
	s_add_i32 s56, 0, 0x14000
	v_add_u32_e32 v146, s55, v228
	v_add_u32_e32 v162, s56, v228
	ds_read_b128 v[130:133], v146
	ds_read_b128 v[138:141], v146 offset:1024
	ds_read_b128 v[142:145], v146 offset:2048
	ds_read_b128 v[146:149], v146 offset:3072
	ds_read_b128 v[150:153], v162
	ds_read_b128 v[154:157], v162 offset:1024
	ds_read_b128 v[158:161], v162 offset:2048
	ds_read_b128 v[162:165], v162 offset:3072
	v_lshl_add_u64 v[208:209], s[18:19], 0, v[198:199]
	s_add_i32 m0, s30, 0xc000
	ds_read_b128 v[166:169], v244
	ds_read_b128 v[170:173], v244 offset:1024
	ds_read_b128 v[174:177], v244 offset:2048
	ds_read_b128 v[178:181], v244 offset:3072
	ds_read_b128 v[182:185], v244 offset:4096
	ds_read_b128 v[186:189], v244 offset:5120
	ds_read_b128 v[190:193], v244 offset:6144
	ds_read_b128 v[212:215], v244 offset:7168
	global_load_lds_dwordx4 v[208:209], off
	v_lshl_add_u64 v[208:209], s[18:19], 0, v[200:201]
	s_add_i32 m0, s30, 0xe000
	s_nop 0
	global_load_lds_dwordx4 v[208:209], off
	s_waitcnt vmcnt(8)
	s_waitcnt lgkmcnt(0)
	s_setprio 1
	s_barrier
; #define PG8_STAGE(bufoff, gbase, voff) do { _Pragma("unroll") for (int _i = 0; _i < 2; ++_i) \
;         __builtin_amdgcn_global_load_lds((const unsigned*)((const char*)(gbase) + (voff)[_i]), (LAS unsigned*)(lds + (bufoff) + ldsw + _i * 8192), 16, 0, 0); } while (0)
; #define PG8_LDA(dst, b, h) do { _Pragma("unroll") for (int m = 0; m < 4; ++m) _Pragma("unroll") for (int k = 0; k < 2; ++k) dst[m][k] = *(const LAS bf16x8*)(lds + PG8_SA(b, h) + aoff + m * 2048 + k * 1024); } while (0)
; #define PG8_LDB(dst, b, h) do { _Pragma("unroll") for (int n = 0; n < 2; ++n) _Pragma("unroll") for (int k = 0; k < 2; ++k) dst[n][k] = *(const LAS bf16x8*)(lds + PG8_SB(b, h) + boff + n * 2048 + k * 1024); } while (0)
; #define PG8_MMA(ai, bj, At, Bt) do { __builtin_amdgcn_s_setprio(1); _Pragma("unroll") for (int m = 0; m < 4; ++m) _Pragma("unroll") for (int n = 0; n < 2; ++n) _Pragma("unroll") for (int k = 0; k < 2; ++k) \
;         acc[ai][bj][m][n] = __builtin_amdgcn_mfma_f32_16x16x32_bf16(Bt[n][k], At[m][k], acc[ai][bj][m][n], 0, 0, 0); __builtin_amdgcn_s_setprio(0); } while (0)
; #define PG8_WAIT_V(n) asm volatile("s_waitcnt vmcnt(" #n ")" ::: "memory")
; #define PG8_WAIT_L(n) asm volatile("s_waitcnt lgkmcnt(" #n ")" ::: "memory")
; #define PG8_BAR __builtin_amdgcn_s_barrier()
; #define PG8_SCHED __builtin_amdgcn_sched_barrier(0)
; template <class Epi, bool SEG>
; __device__ __forceinline__ void gemm_phase(LAS unsigned char* lds, const Gemm g, const int G, const int cidx, const Epi& E) {
;     ...
;             PG8_WAIT_V(8); PG8_WAIT_L(0); PG8_BAR; PG8_MMA(0, 0, At, B0); PG8_MMA(0, 1, At, B1); PG8_BAR; PG8_SCHED;
;             PG8_LDA(At, 0, 1); PG8_STAGE(PG8_SB(0, 0), b2, voffB); PG8_STAGE(PG8_SB(0, 1), b2 + hstepB, voffB); PG8_STAGE(PG8_SA(0, 0), a2, voffA);
;             PG8_WAIT_V(8); PG8_WAIT_L(0); PG8_BAR; PG8_MMA(1, 0, At, B0); PG8_MMA(1, 1, At, B1); PG8_BAR; PG8_SCHED;
;             PG8_LDB(B0, 1, 0); PG8_LDB(B1, 1, 1); PG8_SCHED; PG8_LDA(At, 1, 0); PG8_STAGE(PG8_SA(0, 1), a2 + hstepA, voffA);
;             PG8_WAIT_V(8); PG8_WAIT_L(0); PG8_BAR; PG8_MMA(0, 0, At, B0); PG8_MMA(0, 1, At, B1); PG8_BAR; PG8_SCHED;
	v_mfma_f32_16x16x32_bf16 v[134:137], v[130:133], v[166:169], v[134:137]
	v_mfma_f32_16x16x32_bf16 v[126:129], v[142:145], v[166:169], v[126:129]
	v_mfma_f32_16x16x32_bf16 v[114:117], v[130:133], v[174:177], v[114:117]
	v_mfma_f32_16x16x32_bf16 v[110:113], v[142:145], v[174:177], v[110:113]
	v_mfma_f32_16x16x32_bf16 v[98:101], v[130:133], v[182:185], v[98:101]
	v_mfma_f32_16x16x32_bf16 v[94:97], v[142:145], v[182:185], v[94:97]
	v_mfma_f32_16x16x32_bf16 v[82:85], v[130:133], v[190:193], v[82:85]
	v_mfma_f32_16x16x32_bf16 v[78:81], v[142:145], v[190:193], v[78:81]
	v_mfma_f32_16x16x32_bf16 v[134:137], v[138:141], v[170:173], v[134:137]
	v_mfma_f32_16x16x32_bf16 v[126:129], v[146:149], v[170:173], v[126:129]
	v_mfma_f32_16x16x32_bf16 v[114:117], v[138:141], v[178:181], v[114:117]
	v_mfma_f32_16x16x32_bf16 v[110:113], v[146:149], v[178:181], v[110:113]
	v_mfma_f32_16x16x32_bf16 v[98:101], v[138:141], v[186:189], v[98:101]
	v_mfma_f32_16x16x32_bf16 v[94:97], v[146:149], v[186:189], v[94:97]
	v_mfma_f32_16x16x32_bf16 v[82:85], v[138:141], v[212:215], v[82:85]
	v_mfma_f32_16x16x32_bf16 v[78:81], v[146:149], v[212:215], v[78:81]
	v_mfma_f32_16x16x32_bf16 v[122:125], v[150:153], v[166:169], v[122:125]
	v_mfma_f32_16x16x32_bf16 v[118:121], v[158:161], v[166:169], v[118:121]
	v_mfma_f32_16x16x32_bf16 v[106:109], v[150:153], v[174:177], v[106:109]
	v_mfma_f32_16x16x32_bf16 v[102:105], v[158:161], v[174:177], v[102:105]
	v_mfma_f32_16x16x32_bf16 v[90:93], v[150:153], v[182:185], v[90:93]
	v_mfma_f32_16x16x32_bf16 v[86:89], v[158:161], v[182:185], v[86:89]
	v_mfma_f32_16x16x32_bf16 v[74:77], v[150:153], v[190:193], v[74:77]
	v_mfma_f32_16x16x32_bf16 v[70:73], v[158:161], v[190:193], v[70:73]
	v_mfma_f32_16x16x32_bf16 v[122:125], v[154:157], v[170:173], v[122:125]
	v_mfma_f32_16x16x32_bf16 v[118:121], v[162:165], v[170:173], v[118:121]
	v_mfma_f32_16x16x32_bf16 v[106:109], v[154:157], v[178:181], v[106:109]
	v_mfma_f32_16x16x32_bf16 v[102:105], v[162:165], v[178:181], v[102:105]
	v_mfma_f32_16x16x32_bf16 v[90:93], v[154:157], v[186:189], v[90:93]
	v_mfma_f32_16x16x32_bf16 v[86:89], v[162:165], v[186:189], v[86:89]
	v_mfma_f32_16x16x32_bf16 v[74:77], v[154:157], v[212:215], v[74:77]
	v_mfma_f32_16x16x32_bf16 v[70:73], v[162:165], v[212:215], v[70:73]
	s_barrier
	s_setprio 0
	s_add_i32 s18, s55, s9
	v_lshl_add_u64 v[208:209], s[22:23], 0, v[0:1]
	s_mov_b32 m0, s18
	ds_read_b128 v[166:169], v244 offset:16384
	ds_read_b128 v[170:173], v244 offset:17408
	ds_read_b128 v[174:177], v244 offset:18432
	ds_read_b128 v[178:181], v244 offset:19456
	ds_read_b128 v[182:185], v244 offset:20480
	ds_read_b128 v[186:189], v244 offset:21504
	ds_read_b128 v[190:193], v244 offset:22528
	ds_read_b128 v[212:215], v244 offset:23552
	global_load_lds_dwordx4 v[208:209], off
	s_add_i32 m0, s18, 0x2000
	s_add_u32 s18, s22, 0xb0000
	v_lshl_add_u64 v[216:217], s[22:23], 0, v[14:15]
	s_addc_u32 s19, s23, 0
	s_add_i32 s55, s56, s9
	global_load_lds_dwordx4 v[216:217], off
	v_lshl_add_u64 v[218:219], s[18:19], 0, v[0:1]
	s_mov_b32 m0, s55
	v_lshl_add_u64 v[220:221], s[46:47], 0, v[194:195]
	global_load_lds_dwordx4 v[218:219], off
	v_lshl_add_u64 v[218:219], s[18:19], 0, v[14:15]
	s_add_i32 m0, s55, 0x2000
	s_nop 0
	global_load_lds_dwordx4 v[218:219], off
	v_lshl_add_u64 v[218:219], s[46:47], 0, v[196:197]
	s_mov_b32 m0, s30
	s_nop 0
	global_load_lds_dwordx4 v[218:219], off
	s_mov_b32 m0, s31
	s_nop 0
	global_load_lds_dwordx4 v[220:221], off
	s_waitcnt vmcnt(8)
	s_waitcnt lgkmcnt(0)
	s_setprio 1
	s_barrier
	v_mfma_f32_16x16x32_bf16 v[66:69], v[130:133], v[166:169], v[66:69]
	v_mfma_f32_16x16x32_bf16 v[62:65], v[142:145], v[166:169], v[62:65]
	v_mfma_f32_16x16x32_bf16 v[50:53], v[130:133], v[174:177], v[50:53]
	v_mfma_f32_16x16x32_bf16 v[46:49], v[142:145], v[174:177], v[46:49]
	v_mfma_f32_16x16x32_bf16 v[34:37], v[130:133], v[182:185], v[34:37]
	v_mfma_f32_16x16x32_bf16 v[30:33], v[142:145], v[182:185], v[30:33]
	v_mfma_f32_16x16x32_bf16 v[18:21], v[130:133], v[190:193], v[18:21]
	v_mfma_f32_16x16x32_bf16 v[10:13], v[142:145], v[190:193], v[10:13]
	v_mfma_f32_16x16x32_bf16 v[66:69], v[138:141], v[170:173], v[66:69]
	v_mfma_f32_16x16x32_bf16 v[62:65], v[146:149], v[170:173], v[62:65]
	v_mfma_f32_16x16x32_bf16 v[50:53], v[138:141], v[178:181], v[50:53]
	v_mfma_f32_16x16x32_bf16 v[46:49], v[146:149], v[178:181], v[46:49]
	v_mfma_f32_16x16x32_bf16 v[34:37], v[138:141], v[186:189], v[34:37]
	v_mfma_f32_16x16x32_bf16 v[30:33], v[146:149], v[186:189], v[30:33]
	v_mfma_f32_16x16x32_bf16 v[18:21], v[138:141], v[212:215], v[18:21]
	v_mfma_f32_16x16x32_bf16 v[10:13], v[146:149], v[212:215], v[10:13]
	v_mfma_f32_16x16x32_bf16 v[58:61], v[150:153], v[166:169], v[58:61]
	v_mfma_f32_16x16x32_bf16 v[54:57], v[158:161], v[166:169], v[54:57]
	v_mfma_f32_16x16x32_bf16 v[42:45], v[150:153], v[174:177], v[42:45]
	v_mfma_f32_16x16x32_bf16 v[38:41], v[158:161], v[174:177], v[38:41]
	v_mfma_f32_16x16x32_bf16 v[26:29], v[150:153], v[182:185], v[26:29]
	v_mfma_f32_16x16x32_bf16 v[22:25], v[158:161], v[182:185], v[22:25]
	v_mfma_f32_16x16x32_bf16 v[6:9], v[150:153], v[190:193], v[6:9]
	v_mfma_f32_16x16x32_bf16 v[2:5], v[158:161], v[190:193], v[2:5]
	v_mfma_f32_16x16x32_bf16 v[58:61], v[154:157], v[170:173], v[58:61]
	v_mfma_f32_16x16x32_bf16 v[54:57], v[162:165], v[170:173], v[54:57]
	v_mfma_f32_16x16x32_bf16 v[42:45], v[154:157], v[178:181], v[42:45]
	v_mfma_f32_16x16x32_bf16 v[38:41], v[162:165], v[178:181], v[38:41]
	v_mfma_f32_16x16x32_bf16 v[26:29], v[154:157], v[186:189], v[26:29]
	v_mfma_f32_16x16x32_bf16 v[22:25], v[162:165], v[186:189], v[22:25]
	v_mfma_f32_16x16x32_bf16 v[6:9], v[154:157], v[212:215], v[6:9]
	v_mfma_f32_16x16x32_bf16 v[2:5], v[162:165], v[212:215], v[2:5]
	s_barrier
; #define PG8_STAGE(bufoff, gbase, voff) do { _Pragma("unroll") for (int _i = 0; _i < 2; ++_i) \
;         __builtin_amdgcn_global_load_lds((const unsigned*)((const char*)(gbase) + (voff)[_i]), (LAS unsigned*)(lds + (bufoff) + ldsw + _i * 8192), 16, 0, 0); } while (0)
; #define PG8_LDA(dst, b, h) do { _Pragma("unroll") for (int m = 0; m < 4; ++m) _Pragma("unroll") for (int k = 0; k < 2; ++k) dst[m][k] = *(const LAS bf16x8*)(lds + PG8_SA(b, h) + aoff + m * 2048 + k * 1024); } while (0)
; #define PG8_LDB(dst, b, h) do { _Pragma("unroll") for (int n = 0; n < 2; ++n) _Pragma("unroll") for (int k = 0; k < 2; ++k) dst[n][k] = *(const LAS bf16x8*)(lds + PG8_SB(b, h) + boff + n * 2048 + k * 1024); } while (0)
; #define PG8_MMA(ai, bj, At, Bt) do { __builtin_amdgcn_s_setprio(1); _Pragma("unroll") for (int m = 0; m < 4; ++m) _Pragma("unroll") for (int n = 0; n < 2; ++n) _Pragma("unroll") for (int k = 0; k < 2; ++k) \
;         acc[ai][bj][m][n] = __builtin_amdgcn_mfma_f32_16x16x32_bf16(Bt[n][k], At[m][k], acc[ai][bj][m][n], 0, 0, 0); __builtin_amdgcn_s_setprio(0); } while (0)
; #define PG8_WAIT_V(n) asm volatile("s_waitcnt vmcnt(" #n ")" ::: "memory")
; #define PG8_WAIT_L(n) asm volatile("s_waitcnt lgkmcnt(" #n ")" ::: "memory")
; #define PG8_BAR __builtin_amdgcn_s_barrier()
; #define PG8_SCHED __builtin_amdgcn_sched_barrier(0)
; template <class Epi, bool SEG>
; __device__ __forceinline__ void gemm_phase(LAS unsigned char* lds, const Gemm g, const int G, const int cidx, const Epi& E) {
;     ...
;             PG8_LDB(B0, 1, 0); PG8_LDB(B1, 1, 1); PG8_SCHED; PG8_LDA(At, 1, 0); PG8_STAGE(PG8_SA(0, 1), a2 + hstepA, voffA);
;             PG8_WAIT_V(8); PG8_WAIT_L(0); PG8_BAR; PG8_MMA(0, 0, At, B0); PG8_MMA(0, 1, At, B1); PG8_BAR; PG8_SCHED;
	s_setprio 0
	s_add_i32 s55, 0, 0x18000
	s_add_i32 s56, 0, 0x1c000
	v_add_u32_e32 v146, s55, v228
	v_add_u32_e32 v162, s56, v228
	ds_read_b128 v[130:133], v146
	ds_read_b128 v[138:141], v146 offset:1024
	ds_read_b128 v[142:145], v146 offset:2048
	ds_read_b128 v[146:149], v146 offset:3072
	ds_read_b128 v[150:153], v162
	ds_read_b128 v[154:157], v162 offset:1024
	ds_read_b128 v[158:161], v162 offset:2048
	ds_read_b128 v[162:165], v162 offset:3072
	s_add_u32 s18, s46, 0xb0000
	s_addc_u32 s19, s47, 0
	s_mov_b32 m0, s36
	v_lshl_add_u64 v[222:223], s[18:19], 0, v[196:197]
	ds_read_b128 v[166:169], v244 offset:32768
	ds_read_b128 v[170:173], v244 offset:33792
	ds_read_b128 v[174:177], v244 offset:34816
	ds_read_b128 v[178:181], v244 offset:35840
	ds_read_b128 v[182:185], v244 offset:36864
	ds_read_b128 v[186:189], v244 offset:37888
	ds_read_b128 v[190:193], v244 offset:38912
	ds_read_b128 v[212:215], v244 offset:39936
	global_load_lds_dwordx4 v[222:223], off
	v_lshl_add_u64 v[222:223], s[18:19], 0, v[194:195]
	s_mov_b32 m0, s38
	s_nop 0
	global_load_lds_dwordx4 v[222:223], off
	s_waitcnt vmcnt(8)
	s_waitcnt lgkmcnt(0)
	s_setprio 1
	s_barrier
	v_mfma_f32_16x16x32_bf16 v[134:137], v[130:133], v[166:169], v[134:137]
	v_mfma_f32_16x16x32_bf16 v[126:129], v[142:145], v[166:169], v[126:129]
	v_mfma_f32_16x16x32_bf16 v[114:117], v[130:133], v[174:177], v[114:117]
	v_mfma_f32_16x16x32_bf16 v[110:113], v[142:145], v[174:177], v[110:113]
	v_mfma_f32_16x16x32_bf16 v[98:101], v[130:133], v[182:185], v[98:101]
	v_mfma_f32_16x16x32_bf16 v[94:97], v[142:145], v[182:185], v[94:97]
	v_mfma_f32_16x16x32_bf16 v[82:85], v[130:133], v[190:193], v[82:85]
	v_mfma_f32_16x16x32_bf16 v[78:81], v[142:145], v[190:193], v[78:81]
	v_mfma_f32_16x16x32_bf16 v[134:137], v[138:141], v[170:173], v[134:137]
	v_mfma_f32_16x16x32_bf16 v[126:129], v[146:149], v[170:173], v[126:129]
	v_mfma_f32_16x16x32_bf16 v[114:117], v[138:141], v[178:181], v[114:117]
	v_mfma_f32_16x16x32_bf16 v[110:113], v[146:149], v[178:181], v[110:113]
	v_mfma_f32_16x16x32_bf16 v[98:101], v[138:141], v[186:189], v[98:101]
	v_mfma_f32_16x16x32_bf16 v[94:97], v[146:149], v[186:189], v[94:97]
	v_mfma_f32_16x16x32_bf16 v[82:85], v[138:141], v[212:215], v[82:85]
	v_mfma_f32_16x16x32_bf16 v[78:81], v[146:149], v[212:215], v[78:81]
	v_mfma_f32_16x16x32_bf16 v[122:125], v[150:153], v[166:169], v[122:125]
	v_mfma_f32_16x16x32_bf16 v[118:121], v[158:161], v[166:169], v[118:121]
	v_mfma_f32_16x16x32_bf16 v[106:109], v[150:153], v[174:177], v[106:109]
	v_mfma_f32_16x16x32_bf16 v[102:105], v[158:161], v[174:177], v[102:105]
	v_mfma_f32_16x16x32_bf16 v[90:93], v[150:153], v[182:185], v[90:93]
	v_mfma_f32_16x16x32_bf16 v[86:89], v[158:161], v[182:185], v[86:89]
	v_mfma_f32_16x16x32_bf16 v[74:77], v[150:153], v[190:193], v[74:77]
	v_mfma_f32_16x16x32_bf16 v[70:73], v[158:161], v[190:193], v[70:73]
	v_mfma_f32_16x16x32_bf16 v[122:125], v[154:157], v[170:173], v[122:125]
	v_mfma_f32_16x16x32_bf16 v[118:121], v[162:165], v[170:173], v[118:121]
	v_mfma_f32_16x16x32_bf16 v[106:109], v[154:157], v[178:181], v[106:109]
	v_mfma_f32_16x16x32_bf16 v[102:105], v[162:165], v[178:181], v[102:105]
	v_mfma_f32_16x16x32_bf16 v[90:93], v[154:157], v[186:189], v[90:93]
	v_mfma_f32_16x16x32_bf16 v[86:89], v[162:165], v[186:189], v[86:89]
	v_mfma_f32_16x16x32_bf16 v[74:77], v[154:157], v[212:215], v[74:77]
	v_mfma_f32_16x16x32_bf16 v[70:73], v[162:165], v[212:215], v[70:73]
	s_barrier
; #define PG8_STAGE(bufoff, gbase, voff) do { _Pragma("unroll") for (int _i = 0; _i < 2; ++_i) \
;         __builtin_amdgcn_global_load_lds((const unsigned*)((const char*)(gbase) + (voff)[_i]), (LAS unsigned*)(lds + (bufoff) + ldsw + _i * 8192), 16, 0, 0); } while (0)
; #define PG8_LDA(dst, b, h) do { _Pragma("unroll") for (int m = 0; m < 4; ++m) _Pragma("unroll") for (int k = 0; k < 2; ++k) dst[m][k] = *(const LAS bf16x8*)(lds + PG8_SA(b, h) + aoff + m * 2048 + k * 1024); } while (0)
; #define PG8_MMA(ai, bj, At, Bt) do { __builtin_amdgcn_s_setprio(1); _Pragma("unroll") for (int m = 0; m < 4; ++m) _Pragma("unroll") for (int n = 0; n < 2; ++n) _Pragma("unroll") for (int k = 0; k < 2; ++k) \
;         acc[ai][bj][m][n] = __builtin_amdgcn_mfma_f32_16x16x32_bf16(Bt[n][k], At[m][k], acc[ai][bj][m][n], 0, 0, 0); __builtin_amdgcn_s_setprio(0); } while (0)
; #define PG8_WAIT_V(n) asm volatile("s_waitcnt vmcnt(" #n ")" ::: "memory")
; #define PG8_WAIT_L(n) asm volatile("s_waitcnt lgkmcnt(" #n ")" ::: "memory")
; #define PG8_BAR __builtin_amdgcn_s_barrier()
; #define PG8_SCHED __builtin_amdgcn_sched_barrier(0)
;     __device__ __forceinline__ void operator()(f32x4 (&acc)[2][2][4][2], const Unit& u, int wr, int wc, int fr, int fq) const {
;         const int col0 = u.pn * BM + wc * 32 + 8 * fq;
;         bf16_t* rp0 = x + (size_t)(u.pm * BM + wr * 64 + fr) * DM + col0;
;         u32x4 bx[2][4][2];
; #pragma unroll
;         for (int ai = 0; ai < 2; ++ai)
; #pragma unroll
;             for (int m = 0; m < 4; ++m)
; #pragma unroll
;                 for (int bj = 0; bj < 2; ++bj) bx[ai][m][bj] = *(const u32x4*)(rp0 + (size_t)(ai * HALF + m * 16) * DM + bj * HALF);
; template <class Epi, bool SEG>
; __device__ __forceinline__ void gemm_phase(LAS unsigned char* lds, const Gemm g, const int G, const int cidx, const Epi& E) {
;     ...
;             PG8_LDA(At, 1, 1); PG8_STAGE(PG8_SB(1, 0), b3, voffB); PG8_STAGE(PG8_SB(1, 1), b3 + hstepB, voffB); PG8_STAGE(PG8_SA(1, 0), a3, voffA);
;             PG8_WAIT_V(8); PG8_WAIT_L(0); PG8_BAR; PG8_MMA(1, 0, At, B0); PG8_MMA(1, 1, At, B1); PG8_BAR; PG8_SCHED;
;         }
	s_setprio 0
	s_add_i32 s18, s55, s9
	v_lshl_add_u64 v[208:209], v[208:209], 0, s[28:29]
	s_mov_b32 m0, s18
	ds_read_b128 v[166:169], v244 offset:49152
	ds_read_b128 v[170:173], v244 offset:50176
	ds_read_b128 v[174:177], v244 offset:51200
	ds_read_b128 v[178:181], v244 offset:52224
	ds_read_b128 v[182:185], v244 offset:53248
	ds_read_b128 v[186:189], v244 offset:54272
	ds_read_b128 v[190:193], v244 offset:55296
	ds_read_b128 v[212:215], v244 offset:56320
	global_load_lds_dwordx4 v[208:209], off
	s_add_i32 m0, s18, 0x2000
	s_add_u32 s18, s22, 0xb0080
	v_lshl_add_u64 v[208:209], v[216:217], 0, s[28:29]
	s_addc_u32 s19, s23, 0
	s_add_i32 s22, s56, s9
	global_load_lds_dwordx4 v[208:209], off
	v_lshl_add_u64 v[208:209], s[18:19], 0, v[0:1]
	s_mov_b32 m0, s22
	s_nop 0
	global_load_lds_dwordx4 v[208:209], off
	v_lshl_add_u64 v[208:209], s[18:19], 0, v[14:15]
	s_add_i32 m0, s22, 0x2000
	s_nop 0
	global_load_lds_dwordx4 v[208:209], off
	v_lshl_add_u64 v[208:209], v[218:219], 0, s[28:29]
	s_mov_b32 m0, s39
	s_nop 0
	global_load_lds_dwordx4 v[208:209], off
	v_lshl_add_u64 v[208:209], v[220:221], 0, s[28:29]
	s_mov_b32 m0, s48
	s_nop 0
	global_load_lds_dwordx4 v[208:209], off
	s_waitcnt vmcnt(8)
	s_waitcnt lgkmcnt(0)
	s_setprio 1
	s_barrier
	v_mfma_f32_16x16x32_bf16 v[66:69], v[130:133], v[166:169], v[66:69]
	v_mfma_f32_16x16x32_bf16 v[62:65], v[142:145], v[166:169], v[62:65]
	v_mfma_f32_16x16x32_bf16 v[50:53], v[130:133], v[174:177], v[50:53]
	v_mfma_f32_16x16x32_bf16 v[46:49], v[142:145], v[174:177], v[46:49]
	v_mfma_f32_16x16x32_bf16 v[34:37], v[130:133], v[182:185], v[34:37]
	v_mfma_f32_16x16x32_bf16 v[30:33], v[142:145], v[182:185], v[30:33]
	v_mfma_f32_16x16x32_bf16 v[18:21], v[130:133], v[190:193], v[18:21]
	v_mfma_f32_16x16x32_bf16 v[10:13], v[142:145], v[190:193], v[10:13]
	v_mfma_f32_16x16x32_bf16 v[66:69], v[138:141], v[170:173], v[66:69]
	v_mfma_f32_16x16x32_bf16 v[62:65], v[146:149], v[170:173], v[62:65]
	v_mfma_f32_16x16x32_bf16 v[50:53], v[138:141], v[178:181], v[50:53]
	v_mfma_f32_16x16x32_bf16 v[46:49], v[146:149], v[178:181], v[46:49]
	v_mfma_f32_16x16x32_bf16 v[34:37], v[138:141], v[186:189], v[34:37]
	v_mfma_f32_16x16x32_bf16 v[30:33], v[146:149], v[186:189], v[30:33]
	v_mfma_f32_16x16x32_bf16 v[18:21], v[138:141], v[212:215], v[18:21]
	v_mfma_f32_16x16x32_bf16 v[10:13], v[146:149], v[212:215], v[10:13]
	v_mfma_f32_16x16x32_bf16 v[58:61], v[150:153], v[166:169], v[58:61]
	v_mfma_f32_16x16x32_bf16 v[54:57], v[158:161], v[166:169], v[54:57]
	v_mfma_f32_16x16x32_bf16 v[42:45], v[150:153], v[174:177], v[42:45]
	v_mfma_f32_16x16x32_bf16 v[38:41], v[158:161], v[174:177], v[38:41]
	v_mfma_f32_16x16x32_bf16 v[26:29], v[150:153], v[182:185], v[26:29]
	v_mfma_f32_16x16x32_bf16 v[22:25], v[158:161], v[182:185], v[22:25]
	v_mfma_f32_16x16x32_bf16 v[6:9], v[150:153], v[190:193], v[6:9]
	v_mfma_f32_16x16x32_bf16 v[2:5], v[158:161], v[190:193], v[2:5]
	v_mfma_f32_16x16x32_bf16 v[58:61], v[154:157], v[170:173], v[58:61]
	v_mfma_f32_16x16x32_bf16 v[54:57], v[162:165], v[170:173], v[54:57]
	v_mfma_f32_16x16x32_bf16 v[42:45], v[154:157], v[178:181], v[42:45]
	v_mfma_f32_16x16x32_bf16 v[38:41], v[162:165], v[178:181], v[38:41]
	v_mfma_f32_16x16x32_bf16 v[26:29], v[154:157], v[186:189], v[26:29]
	v_mfma_f32_16x16x32_bf16 v[22:25], v[162:165], v[186:189], v[22:25]
	v_mfma_f32_16x16x32_bf16 v[6:9], v[154:157], v[212:215], v[6:9]
	v_mfma_f32_16x16x32_bf16 v[2:5], v[162:165], v[212:215], v[2:5]
	s_barrier
	s_setprio 0
	s_add_i32 s54, s54, 2
	s_add_u32 s52, s52, 0x100
	s_addc_u32 s53, s53, 0
	s_cmp_gt_u32 s54, 41
	s_mov_b64 s[18:19], s[20:21]
	s_cbranch_scc0 .LBB0_958
	s_lshl_b32 s15, s15, 8
	v_add_u32_e32 v132, s15, v17
	v_ashrrev_i32_e32 v133, 31, v132
	v_lshl_or_b32 v130, s14, 8, v229
	v_lshlrev_b64 v[132:133], 11, v[132:133]
	v_lshl_add_u64 v[132:133], s[82:83], 0, v[132:133]
	v_ashrrev_i32_e32 v131, 31, v130
	v_lshl_add_u64 v[226:227], v[130:131], 1, v[132:133]
	global_load_dwordx4 v[248:251], v[226:227], off
	global_load_dwordx4 v[190:193], v[226:227], off offset:256
	v_add_co_u32_e32 v224, vcc, 0x8000, v226
	s_mov_b32 s18, 0x18000
	s_nop 0
	v_addc_co_u32_e32 v225, vcc, 0, v227, vcc
	global_load_dwordx4 v[186:189], v[224:225], off
	global_load_dwordx4 v[182:185], v[224:225], off offset:256
	s_nop 4
	s_and_b64 vcc, exec, s[12:13]
	s_cbranch_vccz .LBB0_961
	s_barrier

; #define PG8_STAGE(bufoff, gbase, voff) do { _Pragma("unroll") for (int _i = 0; _i < 2; ++_i) \
;         __builtin_amdgcn_global_load_lds((const unsigned*)((const char*)(gbase) + (voff)[_i]), (LAS unsigned*)(lds + (bufoff) + ldsw + _i * 8192), 16, 0, 0); } while (0)
; #define PG8_LDA(dst, b, h) do { _Pragma("unroll") for (int m = 0; m < 4; ++m) _Pragma("unroll") for (int k = 0; k < 2; ++k) dst[m][k] = *(const LAS bf16x8*)(lds + PG8_SA(b, h) + aoff + m * 2048 + k * 1024); } while (0)
; #define PG8_LDB(dst, b, h) do { _Pragma("unroll") for (int n = 0; n < 2; ++n) _Pragma("unroll") for (int k = 0; k < 2; ++k) dst[n][k] = *(const LAS bf16x8*)(lds + PG8_SB(b, h) + boff + n * 2048 + k * 1024); } while (0)
; #define PG8_MMA(ai, bj, At, Bt) do { __builtin_amdgcn_s_setprio(1); _Pragma("unroll") for (int m = 0; m < 4; ++m) _Pragma("unroll") for (int n = 0; n < 2; ++n) _Pragma("unroll") for (int k = 0; k < 2; ++k) \
;         acc[ai][bj][m][n] = __builtin_amdgcn_mfma_f32_16x16x32_bf16(Bt[n][k], At[m][k], acc[ai][bj][m][n], 0, 0, 0); __builtin_amdgcn_s_setprio(0); } while (0)
; #define PG8_WAIT_V(n) asm volatile("s_waitcnt vmcnt(" #n ")" ::: "memory")
; #define PG8_WAIT_L(n) asm volatile("s_waitcnt lgkmcnt(" #n ")" ::: "memory")
; #define PG8_BAR __builtin_amdgcn_s_barrier()
; #define PG8_SCHED __builtin_amdgcn_sched_barrier(0)
; template <class Epi, bool SEG>
; __device__ __forceinline__ void gemm_phase(LAS unsigned char* lds, const Gemm g, const int G, const int cidx, const Epi& E) {
;     ...
;         for (int t = 0; t < nt; t += 2) {
;             const bool last = (t == nt - 2);
;             const char* a1 = cA + (size_t)(t + 1) * kstep;
;             const char* a2 = last ? nA : cA + (size_t)(t + 2) * kstep; const char* b2 = last ? nB : cB + (size_t)(t + 2) * kstep;
;             const char* a3 = a2 + kstep; const char* b3 = b2 + kstep;
;             PG8_LDB(B0, 0, 0); PG8_LDB(B1, 0, 1); PG8_SCHED; PG8_LDA(At, 0, 0); PG8_STAGE(PG8_SA(1, 1), a1 + hstepA, voffA);
;             PG8_WAIT_V(8); PG8_WAIT_L(0); PG8_BAR; PG8_MMA(0, 0, At, B0); PG8_MMA(0, 1, At, B1); PG8_BAR; PG8_SCHED;
;             PG8_LDA(At, 0, 1); PG8_STAGE(PG8_SB(0, 0), b2, voffB); PG8_STAGE(PG8_SB(0, 1), b2 + hstepB, voffB); PG8_STAGE(PG8_SA(0, 0), a2, voffA);
;             PG8_WAIT_V(8); PG8_WAIT_L(0); PG8_BAR; PG8_MMA(1, 0, At, B0); PG8_MMA(1, 1, At, B1); PG8_BAR; PG8_SCHED;
.LBB0_1060:
	s_add_i32 s63, s42, 2
	s_add_u32 s40, s22, 0x100
	s_addc_u32 s41, s23, 0
	s_add_i32 s66, 0, 0x10000
	s_cmp_eq_u32 s57, s42
	s_cselect_b32 s43, s19, s41
	s_cselect_b32 s42, s18, s40
	v_add_u32_e32 v145, s66, v142
	s_cselect_b32 s65, s21, s62
	s_cselect_b32 s64, s20, s61
	s_add_i32 s67, 0, 0x14000
	ds_read_b128 v[146:149], v145
	ds_read_b128 v[150:153], v145 offset:1024
	ds_read_b128 v[154:157], v145 offset:2048
	ds_read_b128 v[158:161], v145 offset:3072
	v_add_u32_e32 v145, s67, v142
	ds_read_b128 v[162:165], v145
	ds_read_b128 v[166:169], v145 offset:1024
	ds_read_b128 v[170:173], v145 offset:2048
	ds_read_b128 v[174:177], v145 offset:3072
	v_lshl_add_u64 v[220:221], s[22:23], 0, v[138:139]
	s_add_i32 m0, s47, 0xc000
	ds_read_b128 v[178:181], v144
	ds_read_b128 v[182:185], v144 offset:1024
	ds_read_b128 v[186:189], v144 offset:2048
	ds_read_b128 v[190:193], v144 offset:3072
	ds_read_b128 v[194:197], v144 offset:4096
	ds_read_b128 v[198:201], v144 offset:5120
	ds_read_b128 v[212:215], v144 offset:6144
	ds_read_b128 v[216:219], v144 offset:7168
	global_load_lds_dwordx4 v[220:221], off
	v_lshl_add_u64 v[220:221], s[22:23], 0, v[140:141]
	s_add_i32 m0, s47, 0xe000
	s_nop 0
	global_load_lds_dwordx4 v[220:221], off
	s_waitcnt vmcnt(8)
	s_waitcnt lgkmcnt(0)
	s_setprio 1
	s_barrier
	v_mfma_f32_16x16x32_bf16 v[130:133], v[146:149], v[178:181], v[130:133]
	v_mfma_f32_16x16x32_bf16 v[126:129], v[154:157], v[178:181], v[126:129]
	v_mfma_f32_16x16x32_bf16 v[122:125], v[146:149], v[186:189], v[122:125]
	v_mfma_f32_16x16x32_bf16 v[118:121], v[154:157], v[186:189], v[118:121]
	v_mfma_f32_16x16x32_bf16 v[106:109], v[146:149], v[194:197], v[106:109]
	v_mfma_f32_16x16x32_bf16 v[102:105], v[154:157], v[194:197], v[102:105]
	v_mfma_f32_16x16x32_bf16 v[90:93], v[146:149], v[212:215], v[90:93]
	v_mfma_f32_16x16x32_bf16 v[86:89], v[154:157], v[212:215], v[86:89]
	v_mfma_f32_16x16x32_bf16 v[130:133], v[150:153], v[182:185], v[130:133]
	v_mfma_f32_16x16x32_bf16 v[126:129], v[158:161], v[182:185], v[126:129]
	v_mfma_f32_16x16x32_bf16 v[122:125], v[150:153], v[190:193], v[122:125]
	v_mfma_f32_16x16x32_bf16 v[118:121], v[158:161], v[190:193], v[118:121]
	v_mfma_f32_16x16x32_bf16 v[106:109], v[150:153], v[198:201], v[106:109]
	v_mfma_f32_16x16x32_bf16 v[102:105], v[158:161], v[198:201], v[102:105]
	v_mfma_f32_16x16x32_bf16 v[90:93], v[150:153], v[216:219], v[90:93]
	v_mfma_f32_16x16x32_bf16 v[86:89], v[158:161], v[216:219], v[86:89]
	v_mfma_f32_16x16x32_bf16 v[114:117], v[162:165], v[178:181], v[114:117]
	v_mfma_f32_16x16x32_bf16 v[110:113], v[170:173], v[178:181], v[110:113]
	v_mfma_f32_16x16x32_bf16 v[98:101], v[162:165], v[186:189], v[98:101]
	v_mfma_f32_16x16x32_bf16 v[94:97], v[170:173], v[186:189], v[94:97]
	v_mfma_f32_16x16x32_bf16 v[82:85], v[162:165], v[194:197], v[82:85]
	v_mfma_f32_16x16x32_bf16 v[78:81], v[170:173], v[194:197], v[78:81]
	v_mfma_f32_16x16x32_bf16 v[74:77], v[162:165], v[212:215], v[74:77]
	v_mfma_f32_16x16x32_bf16 v[70:73], v[170:173], v[212:215], v[70:73]
	v_mfma_f32_16x16x32_bf16 v[114:117], v[166:169], v[182:185], v[114:117]
	v_mfma_f32_16x16x32_bf16 v[110:113], v[174:177], v[182:185], v[110:113]
	v_mfma_f32_16x16x32_bf16 v[98:101], v[166:169], v[190:193], v[98:101]
	v_mfma_f32_16x16x32_bf16 v[94:97], v[174:177], v[190:193], v[94:97]
	v_mfma_f32_16x16x32_bf16 v[82:85], v[166:169], v[198:201], v[82:85]
	v_mfma_f32_16x16x32_bf16 v[78:81], v[174:177], v[198:201], v[78:81]
	v_mfma_f32_16x16x32_bf16 v[74:77], v[166:169], v[216:219], v[74:77]
	v_mfma_f32_16x16x32_bf16 v[70:73], v[174:177], v[216:219], v[70:73]
	s_barrier
	s_setprio 0
	s_add_i32 s22, s66, s39
	v_lshl_add_u64 v[220:221], s[64:65], 0, v[0:1]
	s_mov_b32 m0, s22
	ds_read_b128 v[178:181], v144 offset:16384
	ds_read_b128 v[182:185], v144 offset:17408
	ds_read_b128 v[186:189], v144 offset:18432
	ds_read_b128 v[190:193], v144 offset:19456
	ds_read_b128 v[194:197], v144 offset:20480
	ds_read_b128 v[198:201], v144 offset:21504
	ds_read_b128 v[212:215], v144 offset:22528
	ds_read_b128 v[216:219], v144 offset:23552
	global_load_lds_dwordx4 v[220:221], off
	s_add_i32 m0, s22, 0x2000
	s_add_u32 s22, s64, s31
	v_lshl_add_u64 v[222:223], s[64:65], 0, v[14:15]
	s_addc_u32 s23, s65, 0
	s_add_i32 s64, s67, s39
	global_load_lds_dwordx4 v[222:223], off
	v_lshl_add_u64 v[224:225], s[22:23], 0, v[0:1]
	s_mov_b32 m0, s64
	v_lshl_add_u64 v[226:227], s[22:23], 0, v[14:15]
	global_load_lds_dwordx4 v[224:225], off
	s_add_i32 m0, s64, 0x2000
	v_lshl_add_u64 v[228:229], s[42:43], 0, v[136:137]
	global_load_lds_dwordx4 v[226:227], off
	s_mov_b32 m0, s47
	v_lshl_add_u64 v[244:245], s[42:43], 0, v[134:135]
	global_load_lds_dwordx4 v[228:229], off
	s_mov_b32 m0, s48
	s_nop 0
	global_load_lds_dwordx4 v[244:245], off
	s_waitcnt vmcnt(8)
	s_waitcnt lgkmcnt(0)
	s_setprio 1
	s_barrier
; #define PG8_STAGE(bufoff, gbase, voff) do { _Pragma("unroll") for (int _i = 0; _i < 2; ++_i) \
;         __builtin_amdgcn_global_load_lds((const unsigned*)((const char*)(gbase) + (voff)[_i]), (LAS unsigned*)(lds + (bufoff) + ldsw + _i * 8192), 16, 0, 0); } while (0)
; #define PG8_LDA(dst, b, h) do { _Pragma("unroll") for (int m = 0; m < 4; ++m) _Pragma("unroll") for (int k = 0; k < 2; ++k) dst[m][k] = *(const LAS bf16x8*)(lds + PG8_SA(b, h) + aoff + m * 2048 + k * 1024); } while (0)
; #define PG8_LDB(dst, b, h) do { _Pragma("unroll") for (int n = 0; n < 2; ++n) _Pragma("unroll") for (int k = 0; k < 2; ++k) dst[n][k] = *(const LAS bf16x8*)(lds + PG8_SB(b, h) + boff + n * 2048 + k * 1024); } while (0)
; #define PG8_MMA(ai, bj, At, Bt) do { __builtin_amdgcn_s_setprio(1); _Pragma("unroll") for (int m = 0; m < 4; ++m) _Pragma("unroll") for (int n = 0; n < 2; ++n) _Pragma("unroll") for (int k = 0; k < 2; ++k) \
;         acc[ai][bj][m][n] = __builtin_amdgcn_mfma_f32_16x16x32_bf16(Bt[n][k], At[m][k], acc[ai][bj][m][n], 0, 0, 0); __builtin_amdgcn_s_setprio(0); } while (0)
; #define PG8_WAIT_V(n) asm volatile("s_waitcnt vmcnt(" #n ")" ::: "memory")
; #define PG8_WAIT_L(n) asm volatile("s_waitcnt lgkmcnt(" #n ")" ::: "memory")
; #define PG8_BAR __builtin_amdgcn_s_barrier()
; #define PG8_SCHED __builtin_amdgcn_sched_barrier(0)
; template <class Epi, bool SEG>
; __device__ __forceinline__ void gemm_phase(LAS unsigned char* lds, const Gemm g, const int G, const int cidx, const Epi& E) {
;     ...
;             PG8_WAIT_V(8); PG8_WAIT_L(0); PG8_BAR; PG8_MMA(1, 0, At, B0); PG8_MMA(1, 1, At, B1); PG8_BAR; PG8_SCHED;
;             PG8_LDB(B0, 1, 0); PG8_LDB(B1, 1, 1); PG8_SCHED; PG8_LDA(At, 1, 0); PG8_STAGE(PG8_SA(0, 1), a2 + hstepA, voffA);
;             PG8_WAIT_V(8); PG8_WAIT_L(0); PG8_BAR; PG8_MMA(0, 0, At, B0); PG8_MMA(0, 1, At, B1); PG8_BAR; PG8_SCHED;
	v_mfma_f32_16x16x32_bf16 v[66:69], v[146:149], v[178:181], v[66:69]
	v_mfma_f32_16x16x32_bf16 v[62:65], v[154:157], v[178:181], v[62:65]
	v_mfma_f32_16x16x32_bf16 v[58:61], v[146:149], v[186:189], v[58:61]
	v_mfma_f32_16x16x32_bf16 v[54:57], v[154:157], v[186:189], v[54:57]
	v_mfma_f32_16x16x32_bf16 v[42:45], v[146:149], v[194:197], v[42:45]
	v_mfma_f32_16x16x32_bf16 v[38:41], v[154:157], v[194:197], v[38:41]
	v_mfma_f32_16x16x32_bf16 v[26:29], v[146:149], v[212:215], v[26:29]
	v_mfma_f32_16x16x32_bf16 v[22:25], v[154:157], v[212:215], v[22:25]
	v_mfma_f32_16x16x32_bf16 v[66:69], v[150:153], v[182:185], v[66:69]
	v_mfma_f32_16x16x32_bf16 v[62:65], v[158:161], v[182:185], v[62:65]
	v_mfma_f32_16x16x32_bf16 v[58:61], v[150:153], v[190:193], v[58:61]
	v_mfma_f32_16x16x32_bf16 v[54:57], v[158:161], v[190:193], v[54:57]
	v_mfma_f32_16x16x32_bf16 v[42:45], v[150:153], v[198:201], v[42:45]
	v_mfma_f32_16x16x32_bf16 v[38:41], v[158:161], v[198:201], v[38:41]
	v_mfma_f32_16x16x32_bf16 v[26:29], v[150:153], v[216:219], v[26:29]
	v_mfma_f32_16x16x32_bf16 v[22:25], v[158:161], v[216:219], v[22:25]
	v_mfma_f32_16x16x32_bf16 v[50:53], v[162:165], v[178:181], v[50:53]
	v_mfma_f32_16x16x32_bf16 v[46:49], v[170:173], v[178:181], v[46:49]
	v_mfma_f32_16x16x32_bf16 v[34:37], v[162:165], v[186:189], v[34:37]
	v_mfma_f32_16x16x32_bf16 v[30:33], v[170:173], v[186:189], v[30:33]
	v_mfma_f32_16x16x32_bf16 v[18:21], v[162:165], v[194:197], v[18:21]
	v_mfma_f32_16x16x32_bf16 v[10:13], v[170:173], v[194:197], v[10:13]
	v_mfma_f32_16x16x32_bf16 v[6:9], v[162:165], v[212:215], v[6:9]
	v_mfma_f32_16x16x32_bf16 v[2:5], v[170:173], v[212:215], v[2:5]
	v_mfma_f32_16x16x32_bf16 v[50:53], v[166:169], v[182:185], v[50:53]
	v_mfma_f32_16x16x32_bf16 v[46:49], v[174:177], v[182:185], v[46:49]
	v_mfma_f32_16x16x32_bf16 v[34:37], v[166:169], v[190:193], v[34:37]
	v_mfma_f32_16x16x32_bf16 v[30:33], v[174:177], v[190:193], v[30:33]
	v_mfma_f32_16x16x32_bf16 v[18:21], v[166:169], v[198:201], v[18:21]
	v_mfma_f32_16x16x32_bf16 v[10:13], v[174:177], v[198:201], v[10:13]
	v_mfma_f32_16x16x32_bf16 v[6:9], v[166:169], v[216:219], v[6:9]
	v_mfma_f32_16x16x32_bf16 v[2:5], v[174:177], v[216:219], v[2:5]
	s_barrier
	s_setprio 0
	s_add_i32 s64, 0, 0x18000
	v_add_u32_e32 v145, s64, v142
	s_add_i32 s65, 0, 0x1c000
	ds_read_b128 v[146:149], v145
	ds_read_b128 v[150:153], v145 offset:1024
	ds_read_b128 v[154:157], v145 offset:2048
	ds_read_b128 v[158:161], v145 offset:3072
	v_add_u32_e32 v145, s65, v142
	ds_read_b128 v[162:165], v145
	ds_read_b128 v[166:169], v145 offset:1024
	ds_read_b128 v[170:173], v145 offset:2048
	ds_read_b128 v[174:177], v145 offset:3072
	s_add_u32 s22, s42, 0x30000
	s_addc_u32 s23, s43, 0
	s_mov_b32 m0, s49
	v_lshl_add_u64 v[246:247], s[22:23], 0, v[136:137]
	ds_read_b128 v[178:181], v144 offset:32768
	ds_read_b128 v[182:185], v144 offset:33792
	ds_read_b128 v[186:189], v144 offset:34816
	ds_read_b128 v[190:193], v144 offset:35840
	ds_read_b128 v[194:197], v144 offset:36864
	ds_read_b128 v[198:201], v144 offset:37888
	ds_read_b128 v[212:215], v144 offset:38912
	ds_read_b128 v[216:219], v144 offset:39936
	global_load_lds_dwordx4 v[246:247], off
	v_lshl_add_u64 v[246:247], s[22:23], 0, v[134:135]
	s_mov_b32 m0, s50
	s_nop 0
	global_load_lds_dwordx4 v[246:247], off
	s_waitcnt vmcnt(8)
	s_waitcnt lgkmcnt(0)
	s_setprio 1
	s_barrier
	v_mfma_f32_16x16x32_bf16 v[130:133], v[146:149], v[178:181], v[130:133]
	v_mfma_f32_16x16x32_bf16 v[126:129], v[154:157], v[178:181], v[126:129]
	v_mfma_f32_16x16x32_bf16 v[122:125], v[146:149], v[186:189], v[122:125]
	v_mfma_f32_16x16x32_bf16 v[118:121], v[154:157], v[186:189], v[118:121]
	v_mfma_f32_16x16x32_bf16 v[106:109], v[146:149], v[194:197], v[106:109]
	v_mfma_f32_16x16x32_bf16 v[102:105], v[154:157], v[194:197], v[102:105]
	v_mfma_f32_16x16x32_bf16 v[90:93], v[146:149], v[212:215], v[90:93]
	v_mfma_f32_16x16x32_bf16 v[86:89], v[154:157], v[212:215], v[86:89]
	v_mfma_f32_16x16x32_bf16 v[130:133], v[150:153], v[182:185], v[130:133]
	v_mfma_f32_16x16x32_bf16 v[126:129], v[158:161], v[182:185], v[126:129]
	v_mfma_f32_16x16x32_bf16 v[122:125], v[150:153], v[190:193], v[122:125]
	v_mfma_f32_16x16x32_bf16 v[118:121], v[158:161], v[190:193], v[118:121]
	v_mfma_f32_16x16x32_bf16 v[106:109], v[150:153], v[198:201], v[106:109]
	v_mfma_f32_16x16x32_bf16 v[102:105], v[158:161], v[198:201], v[102:105]
	v_mfma_f32_16x16x32_bf16 v[90:93], v[150:153], v[216:219], v[90:93]
	v_mfma_f32_16x16x32_bf16 v[86:89], v[158:161], v[216:219], v[86:89]
	v_mfma_f32_16x16x32_bf16 v[114:117], v[162:165], v[178:181], v[114:117]
	v_mfma_f32_16x16x32_bf16 v[110:113], v[170:173], v[178:181], v[110:113]
	v_mfma_f32_16x16x32_bf16 v[98:101], v[162:165], v[186:189], v[98:101]
	v_mfma_f32_16x16x32_bf16 v[94:97], v[170:173], v[186:189], v[94:97]
	v_mfma_f32_16x16x32_bf16 v[82:85], v[162:165], v[194:197], v[82:85]
	v_mfma_f32_16x16x32_bf16 v[78:81], v[170:173], v[194:197], v[78:81]
	v_mfma_f32_16x16x32_bf16 v[74:77], v[162:165], v[212:215], v[74:77]
	v_mfma_f32_16x16x32_bf16 v[70:73], v[170:173], v[212:215], v[70:73]
	v_mfma_f32_16x16x32_bf16 v[114:117], v[166:169], v[182:185], v[114:117]
	v_mfma_f32_16x16x32_bf16 v[110:113], v[174:177], v[182:185], v[110:113]
	v_mfma_f32_16x16x32_bf16 v[98:101], v[166:169], v[190:193], v[98:101]
	v_mfma_f32_16x16x32_bf16 v[94:97], v[174:177], v[190:193], v[94:97]
	v_mfma_f32_16x16x32_bf16 v[82:85], v[166:169], v[198:201], v[82:85]
	v_mfma_f32_16x16x32_bf16 v[78:81], v[174:177], v[198:201], v[78:81]
	v_mfma_f32_16x16x32_bf16 v[74:77], v[166:169], v[216:219], v[74:77]
	v_mfma_f32_16x16x32_bf16 v[70:73], v[174:177], v[216:219], v[70:73]
	s_barrier
; #define PG8_STAGE(bufoff, gbase, voff) do { _Pragma("unroll") for (int _i = 0; _i < 2; ++_i) \
;         __builtin_amdgcn_global_load_lds((const unsigned*)((const char*)(gbase) + (voff)[_i]), (LAS unsigned*)(lds + (bufoff) + ldsw + _i * 8192), 16, 0, 0); } while (0)
; #define PG8_LDA(dst, b, h) do { _Pragma("unroll") for (int m = 0; m < 4; ++m) _Pragma("unroll") for (int k = 0; k < 2; ++k) dst[m][k] = *(const LAS bf16x8*)(lds + PG8_SA(b, h) + aoff + m * 2048 + k * 1024); } while (0)
; #define PG8_MMA(ai, bj, At, Bt) do { __builtin_amdgcn_s_setprio(1); _Pragma("unroll") for (int m = 0; m < 4; ++m) _Pragma("unroll") for (int n = 0; n < 2; ++n) _Pragma("unroll") for (int k = 0; k < 2; ++k) \
;         acc[ai][bj][m][n] = __builtin_amdgcn_mfma_f32_16x16x32_bf16(Bt[n][k], At[m][k], acc[ai][bj][m][n], 0, 0, 0); __builtin_amdgcn_s_setprio(0); } while (0)
; #define PG8_WAIT_V(n) asm volatile("s_waitcnt vmcnt(" #n ")" ::: "memory")
; #define PG8_WAIT_L(n) asm volatile("s_waitcnt lgkmcnt(" #n ")" ::: "memory")
; #define PG8_BAR __builtin_amdgcn_s_barrier()
; #define PG8_SCHED __builtin_amdgcn_sched_barrier(0)
; template <class Epi, bool SEG>
; __device__ __forceinline__ void gemm_phase(LAS unsigned char* lds, const Gemm g, const int G, const int cidx, const Epi& E) {
;     ...
;             PG8_LDA(At, 1, 1); PG8_STAGE(PG8_SB(1, 0), b3, voffB); PG8_STAGE(PG8_SB(1, 1), b3 + hstepB, voffB); PG8_STAGE(PG8_SA(1, 0), a3, voffA);
;             PG8_WAIT_V(8); PG8_WAIT_L(0); PG8_BAR; PG8_MMA(1, 0, At, B0); PG8_MMA(1, 1, At, B1); PG8_BAR; PG8_SCHED;
;         }
;         if (wr == 0) PG8_BAR;
	s_setprio 0
	s_add_i32 s22, s64, s39
	v_lshl_add_u64 v[220:221], v[220:221], 0, s[28:29]
	s_mov_b32 m0, s22
	ds_read_b128 v[178:181], v144 offset:49152
	ds_read_b128 v[182:185], v144 offset:50176
	ds_read_b128 v[186:189], v144 offset:51200
	ds_read_b128 v[190:193], v144 offset:52224
	ds_read_b128 v[194:197], v144 offset:53248
	ds_read_b128 v[198:201], v144 offset:54272
	ds_read_b128 v[212:215], v144 offset:55296
	ds_read_b128 v[216:219], v144 offset:56320
	global_load_lds_dwordx4 v[220:221], off
	v_lshl_add_u64 v[220:221], v[222:223], 0, s[28:29]
	s_add_i32 m0, s22, 0x2000
	s_add_i32 s22, s65, s39
	global_load_lds_dwordx4 v[220:221], off
	v_lshl_add_u64 v[220:221], v[224:225], 0, s[28:29]
	s_mov_b32 m0, s22
	s_nop 0
	global_load_lds_dwordx4 v[220:221], off
	v_lshl_add_u64 v[220:221], v[226:227], 0, s[28:29]
	s_add_i32 m0, s22, 0x2000
	s_nop 0
	global_load_lds_dwordx4 v[220:221], off
	v_lshl_add_u64 v[220:221], v[228:229], 0, s[28:29]
	s_mov_b32 m0, s55
	s_nop 0
	global_load_lds_dwordx4 v[220:221], off
	v_lshl_add_u64 v[220:221], v[244:245], 0, s[28:29]
	s_mov_b32 m0, s56
	s_nop 0
	global_load_lds_dwordx4 v[220:221], off
	s_waitcnt vmcnt(8)
	s_waitcnt lgkmcnt(0)
	s_setprio 1
	s_barrier
	v_mfma_f32_16x16x32_bf16 v[66:69], v[146:149], v[178:181], v[66:69]
	v_mfma_f32_16x16x32_bf16 v[62:65], v[154:157], v[178:181], v[62:65]
	v_mfma_f32_16x16x32_bf16 v[58:61], v[146:149], v[186:189], v[58:61]
	v_mfma_f32_16x16x32_bf16 v[54:57], v[154:157], v[186:189], v[54:57]
	v_mfma_f32_16x16x32_bf16 v[42:45], v[146:149], v[194:197], v[42:45]
	v_mfma_f32_16x16x32_bf16 v[38:41], v[154:157], v[194:197], v[38:41]
	v_mfma_f32_16x16x32_bf16 v[26:29], v[146:149], v[212:215], v[26:29]
	v_mfma_f32_16x16x32_bf16 v[22:25], v[154:157], v[212:215], v[22:25]
	v_mfma_f32_16x16x32_bf16 v[66:69], v[150:153], v[182:185], v[66:69]
	v_mfma_f32_16x16x32_bf16 v[62:65], v[158:161], v[182:185], v[62:65]
	v_mfma_f32_16x16x32_bf16 v[58:61], v[150:153], v[190:193], v[58:61]
	v_mfma_f32_16x16x32_bf16 v[54:57], v[158:161], v[190:193], v[54:57]
	v_mfma_f32_16x16x32_bf16 v[42:45], v[150:153], v[198:201], v[42:45]
	v_mfma_f32_16x16x32_bf16 v[38:41], v[158:161], v[198:201], v[38:41]
	v_mfma_f32_16x16x32_bf16 v[26:29], v[150:153], v[216:219], v[26:29]
	v_mfma_f32_16x16x32_bf16 v[22:25], v[158:161], v[216:219], v[22:25]
	v_mfma_f32_16x16x32_bf16 v[50:53], v[162:165], v[178:181], v[50:53]
	v_mfma_f32_16x16x32_bf16 v[46:49], v[170:173], v[178:181], v[46:49]
	v_mfma_f32_16x16x32_bf16 v[34:37], v[162:165], v[186:189], v[34:37]
	v_mfma_f32_16x16x32_bf16 v[30:33], v[170:173], v[186:189], v[30:33]
	v_mfma_f32_16x16x32_bf16 v[18:21], v[162:165], v[194:197], v[18:21]
	v_mfma_f32_16x16x32_bf16 v[10:13], v[170:173], v[194:197], v[10:13]
	v_mfma_f32_16x16x32_bf16 v[6:9], v[162:165], v[212:215], v[6:9]
	v_mfma_f32_16x16x32_bf16 v[2:5], v[170:173], v[212:215], v[2:5]
	v_mfma_f32_16x16x32_bf16 v[50:53], v[166:169], v[182:185], v[50:53]
	v_mfma_f32_16x16x32_bf16 v[46:49], v[174:177], v[182:185], v[46:49]
	v_mfma_f32_16x16x32_bf16 v[34:37], v[166:169], v[190:193], v[34:37]
	v_mfma_f32_16x16x32_bf16 v[30:33], v[174:177], v[190:193], v[30:33]
	v_mfma_f32_16x16x32_bf16 v[18:21], v[166:169], v[198:201], v[18:21]
	v_mfma_f32_16x16x32_bf16 v[10:13], v[174:177], v[198:201], v[10:13]
	v_mfma_f32_16x16x32_bf16 v[6:9], v[166:169], v[216:219], v[6:9]
	v_mfma_f32_16x16x32_bf16 v[2:5], v[174:177], v[216:219], v[2:5]
	s_barrier
	s_setprio 0
	s_add_u32 s61, s61, 0x100
	s_addc_u32 s62, s62, 0
	s_cmp_ge_u32 s63, s53
	s_mov_b64 s[22:23], s[40:41]
	s_mov_b32 s42, s63
	s_cbranch_scc0 .LBB0_1060
	s_and_b64 vcc, exec, s[16:17]
	s_cbranch_vccz .LBB0_1063
	s_barrier
